# gate tiles store s=1+exp(-logit) (clamped, bf16, fragment-major): input projection keeps the exp but drops the reciprocal; up-projection epilogue needs only rcp+mul per gate ratio
# baseline (speedup 1.0000x reference)
; DI bf16_t f2bf(float x) { return (bf16_t)(pk2(x, 0.f) & 0xffffu); }
; DI u32x4 pack8(f32x4 a, f32x4 b) { u32x4 w; w.x = pk2(a[0], a[1]); w.y = pk2(a[2], a[3]); w.z = pk2(b[0], b[1]); w.w = pk2(b[2], b[3]); return w; }
;     DI void operator()(Acc& acc, const Unit& u, int wr, int wc, int fr, int fq) const {
;     ...
;             for (int m = 0; m < 4; ++m) { const int row = u.pm * 256 + ai * 128 + wr * 64 + m * 16 + fr;
;                 bf16_t* prow = proj + (size_t)row * NPJ + pn * 256 + wc * 32 + fq * 8;
; #pragma unroll
;                 for (int bj = 0; bj < 2; ++bj) { f32x4 v0 = acc[ai][bj][m][0], v1 = acc[ai][bj][m][1];
;                     if (pn == 2) {
;                         const int kvh = wc >> 1, d = (wc & 1) * 32 + fq * 8;
;                         float* o = nullptr;
;                         if (row >= MP) { const int bs = (row - MP) >> 3, t = (row - MP) & 7; o = out + (bj ? O_VWS : O_KWS) + ((size_t)(bs * 128 + 120 + t) * 2 + kvh) * 64 + d; }
;                         else { const int t = row & 4095; if (t >= 3968) o = out + (bj ? O_VWP : O_KWP) + ((size_t)((row >> 12) * 128 + t - 3968) * 2 + kvh) * 64 + d; }
;                         if (o) { *(f32x4*)o = v0; *(f32x4*)(o + 4) = v1; }
;                         if (row < MP) { const int tt = row & 4095, bk = ((row >> 12) * 2 + kvh);
;                             if (bj == 0) *(u32x4*)(ksw + ((((((size_t)bk * 128 + (tt >> 5)) * 4 + (d >> 4)) * 2 + ((d >> 3) & 1)) * 32 + (tt & 31)) * 8)) = pack8(v0, v1);
;                             else { const int w16 = tt & 15; bf16_t* t = vtsw + (((((size_t)bk * 256 + (tt >> 4)) * 2 + ((w16 >> 2) & 1)) * 64 + d) * 8) + (w16 & 3) + 4 * (w16 >> 3);
; #pragma unroll
;                                 for (int j = 0; j < 4; ++j) { t[j * 8] = f2bf(v0[j]); t[(4 + j) * 8] = f2bf(v1[j]); } } }
;                         continue;
;                     }
;                     if (pn < 2) { v0 *= 0.125f * LOG2E; v1 *= 0.125f * LOG2E; }
;                     else if (pn < 5 || (pn >= 9 && pn < 11)) {
.LBB0_122:
	s_mov_b64 s[4:5], -1
	s_cmpk_gt_i32 s96, 0x83
	v_lshlrev_b32_e32 v193, 5, v154
	v_and_b32_e32 v194, 31, v192
	s_cbranch_scc1 .LBB0_639
	s_lshl_b32 s4, s96, 8
	s_lshl_b32 s54, s94, 8
	s_add_i32 s4, s4, s23
	s_ashr_i32 s55, s54, 31
	s_cmp_lg_u32 s94, 2
	v_add_u32_e32 v200, s4, v192
	s_cselect_b64 s[4:5], -1, 0
	s_cmp_gt_i32 s94, 1
	s_cselect_b64 s[40:41], -1, 0
	s_cmp_gt_u32 s94, 6
	s_cselect_b64 s[52:53], -1, 0
	s_cmp_gt_u32 s94, 8
	v_mov_b64_e32 v[162:163], s[48:49]
	s_cselect_b64 s[18:19], -1, 0
	s_cmp_gt_u32 s94, 12
	v_mad_i64_i32 v[162:163], s[6:7], v200, s50, v[162:163]
	s_cselect_b64 s[16:17], -1, 0
	v_lshrrev_b32_e32 v246, 8, v183
	v_lshlrev_b32_e32 v246, 6, v246
	v_bfe_u32 v247, v183, 5, 3
	s_lshl_b32 s100, s96, 8
	v_add3_u32 v246, v246, v247, s100
	v_mul_u32_u24_e32 v246, 0x3200, v246
	v_and_b32_e32 v247, 31, v183
	v_lshlrev_b32_e32 v247, 4, v247
	s_lshl_b32 s100, s94, 9
	v_add3_u32 v246, v246, v247, s100
	v_mov_b32_e32 v247, 0
	v_lshl_add_u64 v[244:245], s[48:49], 0, v[246:247]
	v_lshl_add_u64 v[162:163], s[54:55], 1, v[162:163]
	s_lshl_b32 s28, s33, 1
	v_ashrrev_i32_e32 v161, 31, v160
	v_lshl_add_u64 v[162:163], v[162:163], 0, s[28:29]
	v_and_b32_e32 v154, 0xfff, v200
	v_lshl_add_u64 v[164:165], v[160:161], 1, v[162:163]
	v_cmp_gt_i32_e64 s[8:9], s14, v200
	v_cmp_lt_u32_e64 s[10:11], s51, v154
	s_mov_b64 s[6:7], -1
	s_and_b64 vcc, exec, s[4:5]
	s_cbranch_vccz .LBB0_136
	s_and_b64 vcc, exec, s[40:41]
	s_cbranch_vccz .LBB0_133
	s_cmp_lt_i32 s94, 9
	s_cbranch_scc1 .LBB0_127
	s_cmp_gt_i32 s94, 10
	s_cselect_b64 s[78:79], -1, 0
	s_cbranch_execz .LBB0_128
	s_branch .LBB0_129

; DI float fsigmoid(float x) { return frcp(1.0f + fexp(-x)); }
; DI u32x4 pack8(f32x4 a, f32x4 b) { u32x4 w; w.x = pk2(a[0], a[1]); w.y = pk2(a[2], a[3]); w.z = pk2(b[0], b[1]); w.w = pk2(b[2], b[3]); return w; }
;     DI void operator()(Acc& acc, const Unit& u, int wr, int wc, int fr, int fq) const {
;     ...
;                     else if (pn < 9) {}
;                     else if (pn < 13) { v0 *= 0.08838834764831845f * LOG2E; v1 *= 0.08838834764831845f * LOG2E; }
;                     else {
; #pragma unroll
;                         for (int j = 0; j < 4; ++j) { v0[j] = fsigmoid(v0[j]); v1[j] = fsigmoid(v1[j]); } }
;                     const u32x4 w8 = pack8(v0, v1);
.LBB0_150:
	s_mov_b64 s[6:7], -1
	s_and_b64 vcc, exec, s[52:53]
	s_cbranch_vccz .LBB0_157
	s_andn2_b64 vcc, exec, s[18:19]
	v_mov_b32_e32 v167, v129
	v_mov_b32_e32 v166, v128
	v_mov_b32_e32 v163, v127
	v_mov_b32_e32 v162, v126
	v_mov_b32_e32 v171, v125
	v_mov_b32_e32 v170, v124
	v_mov_b32_e32 v169, v123
	v_mov_b32_e32 v168, v122
	s_cbranch_vccnz .LBB0_156
	s_andn2_b64 vcc, exec, s[16:17]
	s_cbranch_vccnz .LBB0_154
	v_mul_f32_e32 v163, 0xbfb8aa3b, v122
	v_exp_f32_e32 v163, v163
	v_mul_f32_e32 v166, 0xbfb8aa3b, v127
	v_mul_f32_e32 v167, 0xbfb8aa3b, v123
	v_exp_f32_e32 v166, v166
	v_exp_f32_e32 v167, v167
	v_add_f32_e32 v163, 1.0, v163
	v_min_f32_e32 v168, 0x71800000, v163
	v_add_f32_e32 v163, 1.0, v166
	v_add_f32_e32 v166, 1.0, v167
	v_mul_f32_e32 v167, 0xbfb8aa3b, v128
	v_mul_f32_e32 v169, 0xbfb8aa3b, v124
	v_exp_f32_e32 v167, v167
	v_exp_f32_e32 v170, v169
	v_min_f32_e32 v169, 0x71800000, v166
	v_mul_f32_e32 v162, 0xbfb8aa3b, v126
	v_add_f32_e32 v166, 1.0, v167
	v_add_f32_e32 v167, 1.0, v170
	v_mul_f32_e32 v170, 0xbfb8aa3b, v129
	v_exp_f32_e32 v171, v170
	v_mul_f32_e32 v170, 0xbfb8aa3b, v125
	v_exp_f32_e32 v162, v162
	v_exp_f32_e32 v172, v170
	v_min_f32_e32 v170, 0x71800000, v167
	v_add_f32_e32 v167, 1.0, v171
	v_add_f32_e32 v162, 1.0, v162
	v_add_f32_e32 v171, 1.0, v172
	v_min_f32_e32 v162, 0x71800000, v162
	v_min_f32_e32 v163, 0x71800000, v163
	v_min_f32_e32 v166, 0x71800000, v166
	v_min_f32_e32 v167, 0x71800000, v167
	v_min_f32_e32 v171, 0x71800000, v171
	s_mov_b64 s[6:7], 0

; DI float fsigmoid(float x) { return frcp(1.0f + fexp(-x)); }
; DI u32x4 pack8(f32x4 a, f32x4 b) { u32x4 w; w.x = pk2(a[0], a[1]); w.y = pk2(a[2], a[3]); w.z = pk2(b[0], b[1]); w.w = pk2(b[2], b[3]); return w; }
;     DI void operator()(Acc& acc, const Unit& u, int wr, int wc, int fr, int fq) const {
;     ...
;                     else if (pn < 9) {}
;                     else if (pn < 13) { v0 *= 0.08838834764831845f * LOG2E; v1 *= 0.08838834764831845f * LOG2E; }
;                     else {
; #pragma unroll
;                         for (int j = 0; j < 4; ++j) { v0[j] = fsigmoid(v0[j]); v1[j] = fsigmoid(v1[j]); } }
;                     const u32x4 w8 = pack8(v0, v1);
.LBB0_183:
	s_andn2_b64 vcc, exec, s[52:53]
	s_mov_b64 s[40:41], -1
	s_cbranch_vccnz .LBB0_190
	s_andn2_b64 vcc, exec, s[18:19]
	v_mov_b32_e32 v177, v121
	v_mov_b32_e32 v176, v120
	v_mov_b32_e32 v175, v119
	v_mov_b32_e32 v174, v118
	v_mov_b32_e32 v181, v117
	v_mov_b32_e32 v180, v116
	v_mov_b32_e32 v179, v115
	v_mov_b32_e32 v178, v114
	s_cbranch_vccnz .LBB0_189
	s_andn2_b64 vcc, exec, s[16:17]
	s_cbranch_vccnz .LBB0_187
	v_mul_f32_e32 v154, 0xbfb8aa3b, v118
	v_exp_f32_e32 v154, v154
	v_mul_f32_e32 v174, 0xbfb8aa3b, v114
	v_exp_f32_e32 v174, v174
	v_mul_f32_e32 v176, 0xbfb8aa3b, v115
	v_add_f32_e32 v154, 1.0, v154
	v_exp_f32_e32 v176, v176
	v_add_f32_e32 v175, 1.0, v174
	v_min_f32_e32 v174, 0x71800000, v154
	v_mul_f32_e32 v154, 0xbfb8aa3b, v119
	v_exp_f32_e32 v154, v154
	v_min_f32_e32 v178, 0x71800000, v175
	v_mul_f32_e32 v177, 0xbfb8aa3b, v116
	v_exp_f32_e32 v177, v177
	v_add_f32_e32 v154, 1.0, v154
	v_min_f32_e32 v175, 0x71800000, v154
	v_add_f32_e32 v154, 1.0, v176
	v_mul_f32_e32 v176, 0xbfb8aa3b, v120
	v_exp_f32_e32 v176, v176
	v_min_f32_e32 v179, 0x71800000, v154
	v_mul_f32_e32 v180, 0xbfb8aa3b, v117
	v_exp_f32_e32 v181, v180
	v_add_f32_e32 v154, 1.0, v176
	v_min_f32_e32 v176, 0x71800000, v154
	v_add_f32_e32 v154, 1.0, v177
	v_mul_f32_e32 v177, 0xbfb8aa3b, v121
	v_exp_f32_e32 v177, v177
	v_min_f32_e32 v180, 0x71800000, v154
	s_mov_b64 s[40:41], 0
	v_add_f32_e32 v154, 1.0, v177
	v_min_f32_e32 v177, 0x71800000, v154
	v_add_f32_e32 v154, 1.0, v181
	v_min_f32_e32 v181, 0x71800000, v154

; DI float fsigmoid(float x) { return frcp(1.0f + fexp(-x)); }
; DI u32x4 pack8(f32x4 a, f32x4 b) { u32x4 w; w.x = pk2(a[0], a[1]); w.y = pk2(a[2], a[3]); w.z = pk2(b[0], b[1]); w.w = pk2(b[2], b[3]); return w; }
;     DI void operator()(Acc& acc, const Unit& u, int wr, int wc, int fr, int fq) const {
;     ...
;                     else if (pn < 9) {}
;                     else if (pn < 13) { v0 *= 0.08838834764831845f * LOG2E; v1 *= 0.08838834764831845f * LOG2E; }
;                     else {
; #pragma unroll
;                         for (int j = 0; j < 4; ++j) { v0[j] = fsigmoid(v0[j]); v1[j] = fsigmoid(v1[j]); } }
;                     const u32x4 w8 = pack8(v0, v1);
.LBB0_217:
	s_andn2_b64 vcc, exec, s[52:53]
	s_mov_b64 s[40:41], -1
	s_cbranch_vccnz .LBB0_224
	s_andn2_b64 vcc, exec, s[18:19]
	v_mov_b32_e32 v173, v113
	v_mov_b32_e32 v172, v112
	v_mov_b32_e32 v171, v111
	v_mov_b32_e32 v170, v110
	v_mov_b32_e32 v177, v109
	v_mov_b32_e32 v176, v108
	v_mov_b32_e32 v175, v107
	v_mov_b32_e32 v174, v106
	s_cbranch_vccnz .LBB0_223
	s_andn2_b64 vcc, exec, s[16:17]
	s_cbranch_vccnz .LBB0_221
	v_mul_f32_e32 v171, 0xbfb8aa3b, v106
	v_exp_f32_e32 v171, v171
	v_mul_f32_e32 v172, 0xbfb8aa3b, v111
	v_mul_f32_e32 v173, 0xbfb8aa3b, v107
	v_exp_f32_e32 v172, v172
	v_exp_f32_e32 v173, v173
	v_add_f32_e32 v171, 1.0, v171
	v_min_f32_e32 v174, 0x71800000, v171
	v_add_f32_e32 v171, 1.0, v172
	v_add_f32_e32 v172, 1.0, v173
	v_mul_f32_e32 v173, 0xbfb8aa3b, v112
	v_mul_f32_e32 v175, 0xbfb8aa3b, v108
	v_exp_f32_e32 v173, v173
	v_exp_f32_e32 v176, v175
	v_min_f32_e32 v175, 0x71800000, v172
	v_mul_f32_e32 v170, 0xbfb8aa3b, v110
	v_add_f32_e32 v172, 1.0, v173
	v_add_f32_e32 v173, 1.0, v176
	v_mul_f32_e32 v176, 0xbfb8aa3b, v113
	v_exp_f32_e32 v177, v176
	v_mul_f32_e32 v176, 0xbfb8aa3b, v109
	v_exp_f32_e32 v170, v170
	v_exp_f32_e32 v179, v176
	v_min_f32_e32 v176, 0x71800000, v173
	v_add_f32_e32 v173, 1.0, v177
	v_add_f32_e32 v170, 1.0, v170
	v_add_f32_e32 v177, 1.0, v179
	v_min_f32_e32 v170, 0x71800000, v170
	v_min_f32_e32 v171, 0x71800000, v171
	v_min_f32_e32 v172, 0x71800000, v172
	v_min_f32_e32 v173, 0x71800000, v173
	v_min_f32_e32 v177, 0x71800000, v177
	s_mov_b64 s[40:41], 0

; DI float fsigmoid(float x) { return frcp(1.0f + fexp(-x)); }
; DI u32x4 pack8(f32x4 a, f32x4 b) { u32x4 w; w.x = pk2(a[0], a[1]); w.y = pk2(a[2], a[3]); w.z = pk2(b[0], b[1]); w.w = pk2(b[2], b[3]); return w; }
;     DI void operator()(Acc& acc, const Unit& u, int wr, int wc, int fr, int fq) const {
;     ...
;                     else if (pn < 9) {}
;                     else if (pn < 13) { v0 *= 0.08838834764831845f * LOG2E; v1 *= 0.08838834764831845f * LOG2E; }
;                     else {
; #pragma unroll
;                         for (int j = 0; j < 4; ++j) { v0[j] = fsigmoid(v0[j]); v1[j] = fsigmoid(v1[j]); } }
;                     const u32x4 w8 = pack8(v0, v1);
.LBB0_249:
	s_andn2_b64 vcc, exec, s[52:53]
	s_mov_b64 s[40:41], -1
	s_cbranch_vccnz .LBB0_256
	s_andn2_b64 vcc, exec, s[18:19]
	v_mov_b32_e32 v179, v105
	v_mov_b32_e32 v178, v104
	v_mov_b32_e32 v177, v103
	v_mov_b32_e32 v176, v102
	v_mov_b32_e32 v185, v101
	v_mov_b32_e32 v184, v100
	v_mov_b32_e32 v181, v99
	v_mov_b32_e32 v180, v98
	s_cbranch_vccnz .LBB0_255
	s_andn2_b64 vcc, exec, s[16:17]
	s_cbranch_vccnz .LBB0_253
	v_mul_f32_e32 v154, 0xbfb8aa3b, v102
	v_exp_f32_e32 v154, v154
	v_mul_f32_e32 v176, 0xbfb8aa3b, v98
	v_exp_f32_e32 v176, v176
	v_mul_f32_e32 v178, 0xbfb8aa3b, v99
	v_add_f32_e32 v154, 1.0, v154
	v_exp_f32_e32 v178, v178
	v_add_f32_e32 v177, 1.0, v176
	v_min_f32_e32 v176, 0x71800000, v154
	v_mul_f32_e32 v154, 0xbfb8aa3b, v103
	v_exp_f32_e32 v154, v154
	v_min_f32_e32 v180, 0x71800000, v177
	v_mul_f32_e32 v179, 0xbfb8aa3b, v100
	v_exp_f32_e32 v179, v179
	v_add_f32_e32 v154, 1.0, v154
	v_min_f32_e32 v177, 0x71800000, v154
	v_add_f32_e32 v154, 1.0, v178
	v_mul_f32_e32 v178, 0xbfb8aa3b, v104
	v_exp_f32_e32 v178, v178
	v_min_f32_e32 v181, 0x71800000, v154
	v_mul_f32_e32 v184, 0xbfb8aa3b, v101
	v_exp_f32_e32 v185, v184
	v_add_f32_e32 v154, 1.0, v178
	v_min_f32_e32 v178, 0x71800000, v154
	v_add_f32_e32 v154, 1.0, v179
	v_mul_f32_e32 v179, 0xbfb8aa3b, v105
	v_exp_f32_e32 v179, v179
	v_min_f32_e32 v184, 0x71800000, v154
	s_mov_b64 s[40:41], 0
	v_add_f32_e32 v154, 1.0, v179
	v_min_f32_e32 v179, 0x71800000, v154
	v_add_f32_e32 v154, 1.0, v185
	v_min_f32_e32 v185, 0x71800000, v154

; DI float fsigmoid(float x) { return frcp(1.0f + fexp(-x)); }
; DI u32x4 pack8(f32x4 a, f32x4 b) { u32x4 w; w.x = pk2(a[0], a[1]); w.y = pk2(a[2], a[3]); w.z = pk2(b[0], b[1]); w.w = pk2(b[2], b[3]); return w; }
;     DI void operator()(Acc& acc, const Unit& u, int wr, int wc, int fr, int fq) const {
;     ...
;                     else if (pn < 9) {}
;                     else if (pn < 13) { v0 *= 0.08838834764831845f * LOG2E; v1 *= 0.08838834764831845f * LOG2E; }
;                     else {
; #pragma unroll
;                         for (int j = 0; j < 4; ++j) { v0[j] = fsigmoid(v0[j]); v1[j] = fsigmoid(v1[j]); } }
;                     const u32x4 w8 = pack8(v0, v1);
.LBB0_283:
	s_andn2_b64 vcc, exec, s[52:53]
	s_mov_b64 s[40:41], -1
	s_cbranch_vccnz .LBB0_290
	s_andn2_b64 vcc, exec, s[18:19]
	v_mov_b32_e32 v173, v97
	v_mov_b32_e32 v172, v96
	v_mov_b32_e32 v171, v95
	v_mov_b32_e32 v170, v94
	v_mov_b32_e32 v177, v93
	v_mov_b32_e32 v176, v92
	v_mov_b32_e32 v175, v91
	v_mov_b32_e32 v174, v90
	s_cbranch_vccnz .LBB0_289
	s_andn2_b64 vcc, exec, s[16:17]
	s_cbranch_vccnz .LBB0_287
	v_mul_f32_e32 v171, 0xbfb8aa3b, v90
	v_exp_f32_e32 v171, v171
	v_mul_f32_e32 v172, 0xbfb8aa3b, v95
	v_mul_f32_e32 v173, 0xbfb8aa3b, v91
	v_exp_f32_e32 v172, v172
	v_exp_f32_e32 v173, v173
	v_add_f32_e32 v171, 1.0, v171
	v_min_f32_e32 v174, 0x71800000, v171
	v_add_f32_e32 v171, 1.0, v172
	v_add_f32_e32 v172, 1.0, v173
	v_mul_f32_e32 v173, 0xbfb8aa3b, v96
	v_mul_f32_e32 v175, 0xbfb8aa3b, v92
	v_exp_f32_e32 v173, v173
	v_exp_f32_e32 v176, v175
	v_min_f32_e32 v175, 0x71800000, v172
	v_mul_f32_e32 v170, 0xbfb8aa3b, v94
	v_add_f32_e32 v172, 1.0, v173
	v_add_f32_e32 v173, 1.0, v176
	v_mul_f32_e32 v176, 0xbfb8aa3b, v97
	v_exp_f32_e32 v177, v176
	v_mul_f32_e32 v176, 0xbfb8aa3b, v93
	v_exp_f32_e32 v170, v170
	v_exp_f32_e32 v179, v176
	v_min_f32_e32 v176, 0x71800000, v173
	v_add_f32_e32 v173, 1.0, v177
	v_add_f32_e32 v170, 1.0, v170
	v_add_f32_e32 v177, 1.0, v179
	v_min_f32_e32 v170, 0x71800000, v170
	v_min_f32_e32 v171, 0x71800000, v171
	v_min_f32_e32 v172, 0x71800000, v172
	v_min_f32_e32 v173, 0x71800000, v173
	v_min_f32_e32 v177, 0x71800000, v177
	s_mov_b64 s[40:41], 0

; DI float fsigmoid(float x) { return frcp(1.0f + fexp(-x)); }
; DI u32x4 pack8(f32x4 a, f32x4 b) { u32x4 w; w.x = pk2(a[0], a[1]); w.y = pk2(a[2], a[3]); w.z = pk2(b[0], b[1]); w.w = pk2(b[2], b[3]); return w; }
;     DI void operator()(Acc& acc, const Unit& u, int wr, int wc, int fr, int fq) const {
;     ...
;                     else if (pn < 9) {}
;                     else if (pn < 13) { v0 *= 0.08838834764831845f * LOG2E; v1 *= 0.08838834764831845f * LOG2E; }
;                     else {
; #pragma unroll
;                         for (int j = 0; j < 4; ++j) { v0[j] = fsigmoid(v0[j]); v1[j] = fsigmoid(v1[j]); } }
;                     const u32x4 w8 = pack8(v0, v1);
.LBB0_315:
	s_andn2_b64 vcc, exec, s[52:53]
	s_mov_b64 s[40:41], -1
	s_cbranch_vccnz .LBB0_322
	s_andn2_b64 vcc, exec, s[18:19]
	v_mov_b32_e32 v179, v89
	v_mov_b32_e32 v178, v88
	v_mov_b32_e32 v177, v87
	v_mov_b32_e32 v176, v86
	v_mov_b32_e32 v185, v85
	v_mov_b32_e32 v184, v84
	v_mov_b32_e32 v181, v83
	v_mov_b32_e32 v180, v82
	s_cbranch_vccnz .LBB0_321
	s_andn2_b64 vcc, exec, s[16:17]
	s_cbranch_vccnz .LBB0_319
	v_mul_f32_e32 v154, 0xbfb8aa3b, v86
	v_exp_f32_e32 v154, v154
	v_mul_f32_e32 v176, 0xbfb8aa3b, v82
	v_exp_f32_e32 v176, v176
	v_mul_f32_e32 v178, 0xbfb8aa3b, v83
	v_add_f32_e32 v154, 1.0, v154
	v_exp_f32_e32 v178, v178
	v_add_f32_e32 v177, 1.0, v176
	v_min_f32_e32 v176, 0x71800000, v154
	v_mul_f32_e32 v154, 0xbfb8aa3b, v87
	v_exp_f32_e32 v154, v154
	v_min_f32_e32 v180, 0x71800000, v177
	v_mul_f32_e32 v179, 0xbfb8aa3b, v84
	v_exp_f32_e32 v179, v179
	v_add_f32_e32 v154, 1.0, v154
	v_min_f32_e32 v177, 0x71800000, v154
	v_add_f32_e32 v154, 1.0, v178
	v_mul_f32_e32 v178, 0xbfb8aa3b, v88
	v_exp_f32_e32 v178, v178
	v_min_f32_e32 v181, 0x71800000, v154
	v_mul_f32_e32 v184, 0xbfb8aa3b, v85
	v_exp_f32_e32 v185, v184
	v_add_f32_e32 v154, 1.0, v178
	v_min_f32_e32 v178, 0x71800000, v154
	v_add_f32_e32 v154, 1.0, v179
	v_mul_f32_e32 v179, 0xbfb8aa3b, v89
	v_exp_f32_e32 v179, v179
	v_min_f32_e32 v184, 0x71800000, v154
	s_mov_b64 s[40:41], 0
	v_add_f32_e32 v154, 1.0, v179
	v_min_f32_e32 v179, 0x71800000, v154
	v_add_f32_e32 v154, 1.0, v185
	v_min_f32_e32 v185, 0x71800000, v154

; DI float fsigmoid(float x) { return frcp(1.0f + fexp(-x)); }
; DI u32x4 pack8(f32x4 a, f32x4 b) { u32x4 w; w.x = pk2(a[0], a[1]); w.y = pk2(a[2], a[3]); w.z = pk2(b[0], b[1]); w.w = pk2(b[2], b[3]); return w; }
;     DI void operator()(Acc& acc, const Unit& u, int wr, int wc, int fr, int fq) const {
;     ...
;                     else if (pn < 9) {}
;                     else if (pn < 13) { v0 *= 0.08838834764831845f * LOG2E; v1 *= 0.08838834764831845f * LOG2E; }
;                     else {
; #pragma unroll
;                         for (int j = 0; j < 4; ++j) { v0[j] = fsigmoid(v0[j]); v1[j] = fsigmoid(v1[j]); } }
;                     const u32x4 w8 = pack8(v0, v1);
.LBB0_349:
	s_andn2_b64 vcc, exec, s[52:53]
	s_mov_b64 s[40:41], -1
	s_cbranch_vccnz .LBB0_356
	s_andn2_b64 vcc, exec, s[18:19]
	v_mov_b32_e32 v173, v81
	v_mov_b32_e32 v172, v80
	v_mov_b32_e32 v171, v79
	v_mov_b32_e32 v170, v78
	v_mov_b32_e32 v177, v77
	v_mov_b32_e32 v176, v76
	v_mov_b32_e32 v175, v75
	v_mov_b32_e32 v174, v74
	s_cbranch_vccnz .LBB0_355
	s_andn2_b64 vcc, exec, s[16:17]
	s_cbranch_vccnz .LBB0_353
	v_mul_f32_e32 v171, 0xbfb8aa3b, v74
	v_exp_f32_e32 v171, v171
	v_mul_f32_e32 v172, 0xbfb8aa3b, v79
	v_mul_f32_e32 v173, 0xbfb8aa3b, v75
	v_exp_f32_e32 v172, v172
	v_exp_f32_e32 v173, v173
	v_add_f32_e32 v171, 1.0, v171
	v_min_f32_e32 v174, 0x71800000, v171
	v_add_f32_e32 v171, 1.0, v172
	v_add_f32_e32 v172, 1.0, v173
	v_mul_f32_e32 v173, 0xbfb8aa3b, v80
	v_mul_f32_e32 v175, 0xbfb8aa3b, v76
	v_exp_f32_e32 v173, v173
	v_exp_f32_e32 v176, v175
	v_min_f32_e32 v175, 0x71800000, v172
	v_mul_f32_e32 v170, 0xbfb8aa3b, v78
	v_add_f32_e32 v172, 1.0, v173
	v_add_f32_e32 v173, 1.0, v176
	v_mul_f32_e32 v176, 0xbfb8aa3b, v81
	v_exp_f32_e32 v177, v176
	v_mul_f32_e32 v176, 0xbfb8aa3b, v77
	v_exp_f32_e32 v170, v170
	v_exp_f32_e32 v179, v176
	v_min_f32_e32 v176, 0x71800000, v173
	v_add_f32_e32 v173, 1.0, v177
	v_add_f32_e32 v170, 1.0, v170
	v_add_f32_e32 v177, 1.0, v179
	v_min_f32_e32 v170, 0x71800000, v170
	v_min_f32_e32 v171, 0x71800000, v171
	v_min_f32_e32 v172, 0x71800000, v172
	v_min_f32_e32 v173, 0x71800000, v173
	v_min_f32_e32 v177, 0x71800000, v177
	s_mov_b64 s[40:41], 0

; DI float fsigmoid(float x) { return frcp(1.0f + fexp(-x)); }
; DI u32x4 pack8(f32x4 a, f32x4 b) { u32x4 w; w.x = pk2(a[0], a[1]); w.y = pk2(a[2], a[3]); w.z = pk2(b[0], b[1]); w.w = pk2(b[2], b[3]); return w; }
;     DI void operator()(Acc& acc, const Unit& u, int wr, int wc, int fr, int fq) const {
;     ...
;                     else if (pn < 9) {}
;                     else if (pn < 13) { v0 *= 0.08838834764831845f * LOG2E; v1 *= 0.08838834764831845f * LOG2E; }
;                     else {
; #pragma unroll
;                         for (int j = 0; j < 4; ++j) { v0[j] = fsigmoid(v0[j]); v1[j] = fsigmoid(v1[j]); } }
;                     const u32x4 w8 = pack8(v0, v1);
.LBB0_381:
	s_andn2_b64 vcc, exec, s[52:53]
	s_mov_b64 s[40:41], -1
	s_cbranch_vccnz .LBB0_388
	s_andn2_b64 vcc, exec, s[18:19]
	v_mov_b32_e32 v179, v73
	v_mov_b32_e32 v178, v72
	v_mov_b32_e32 v177, v71
	v_mov_b32_e32 v176, v70
	v_mov_b32_e32 v185, v69
	v_mov_b32_e32 v184, v68
	v_mov_b32_e32 v181, v67
	v_mov_b32_e32 v180, v66
	s_cbranch_vccnz .LBB0_387
	s_andn2_b64 vcc, exec, s[16:17]
	s_cbranch_vccnz .LBB0_385
	v_mul_f32_e32 v154, 0xbfb8aa3b, v70
	v_exp_f32_e32 v154, v154
	v_mul_f32_e32 v176, 0xbfb8aa3b, v66
	v_exp_f32_e32 v176, v176
	v_mul_f32_e32 v178, 0xbfb8aa3b, v67
	v_add_f32_e32 v154, 1.0, v154
	v_exp_f32_e32 v178, v178
	v_add_f32_e32 v177, 1.0, v176
	v_min_f32_e32 v176, 0x71800000, v154
	v_mul_f32_e32 v154, 0xbfb8aa3b, v71
	v_exp_f32_e32 v154, v154
	v_min_f32_e32 v180, 0x71800000, v177
	v_mul_f32_e32 v179, 0xbfb8aa3b, v68
	v_exp_f32_e32 v179, v179
	v_add_f32_e32 v154, 1.0, v154
	v_min_f32_e32 v177, 0x71800000, v154
	v_add_f32_e32 v154, 1.0, v178
	v_mul_f32_e32 v178, 0xbfb8aa3b, v72
	v_exp_f32_e32 v178, v178
	v_min_f32_e32 v181, 0x71800000, v154
	v_mul_f32_e32 v184, 0xbfb8aa3b, v69
	v_exp_f32_e32 v185, v184
	v_add_f32_e32 v154, 1.0, v178
	v_min_f32_e32 v178, 0x71800000, v154
	v_add_f32_e32 v154, 1.0, v179
	v_mul_f32_e32 v179, 0xbfb8aa3b, v73
	v_exp_f32_e32 v179, v179
	v_min_f32_e32 v184, 0x71800000, v154
	s_mov_b64 s[40:41], 0
	v_add_f32_e32 v154, 1.0, v179
	v_min_f32_e32 v179, 0x71800000, v154
	v_add_f32_e32 v154, 1.0, v185
	v_min_f32_e32 v185, 0x71800000, v154

; DI float fsigmoid(float x) { return frcp(1.0f + fexp(-x)); }
; DI u32x4 pack8(f32x4 a, f32x4 b) { u32x4 w; w.x = pk2(a[0], a[1]); w.y = pk2(a[2], a[3]); w.z = pk2(b[0], b[1]); w.w = pk2(b[2], b[3]); return w; }
;     DI void operator()(Acc& acc, const Unit& u, int wr, int wc, int fr, int fq) const {
;     ...
;                     else if (pn < 9) {}
;                     else if (pn < 13) { v0 *= 0.08838834764831845f * LOG2E; v1 *= 0.08838834764831845f * LOG2E; }
;                     else {
; #pragma unroll
;                         for (int j = 0; j < 4; ++j) { v0[j] = fsigmoid(v0[j]); v1[j] = fsigmoid(v1[j]); } }
;                     const u32x4 w8 = pack8(v0, v1);
.LBB0_415:
	s_andn2_b64 vcc, exec, s[52:53]
	s_mov_b64 s[40:41], -1
	s_cbranch_vccnz .LBB0_422
	s_andn2_b64 vcc, exec, s[18:19]
	v_mov_b32_e32 v173, v65
	v_mov_b32_e32 v172, v64
	v_mov_b32_e32 v171, v63
	v_mov_b32_e32 v170, v62
	v_mov_b32_e32 v177, v61
	v_mov_b32_e32 v176, v60
	v_mov_b32_e32 v175, v59
	v_mov_b32_e32 v174, v58
	s_cbranch_vccnz .LBB0_421
	s_andn2_b64 vcc, exec, s[16:17]
	s_cbranch_vccnz .LBB0_419
	v_mul_f32_e32 v171, 0xbfb8aa3b, v58
	v_exp_f32_e32 v171, v171
	v_mul_f32_e32 v172, 0xbfb8aa3b, v63
	v_mul_f32_e32 v173, 0xbfb8aa3b, v59
	v_exp_f32_e32 v172, v172
	v_exp_f32_e32 v173, v173
	v_add_f32_e32 v171, 1.0, v171
	v_min_f32_e32 v174, 0x71800000, v171
	v_add_f32_e32 v171, 1.0, v172
	v_add_f32_e32 v172, 1.0, v173
	v_mul_f32_e32 v173, 0xbfb8aa3b, v64
	v_mul_f32_e32 v175, 0xbfb8aa3b, v60
	v_exp_f32_e32 v173, v173
	v_exp_f32_e32 v176, v175
	v_min_f32_e32 v175, 0x71800000, v172
	v_mul_f32_e32 v170, 0xbfb8aa3b, v62
	v_add_f32_e32 v172, 1.0, v173
	v_add_f32_e32 v173, 1.0, v176
	v_mul_f32_e32 v176, 0xbfb8aa3b, v65
	v_exp_f32_e32 v177, v176
	v_mul_f32_e32 v176, 0xbfb8aa3b, v61
	v_exp_f32_e32 v170, v170
	v_exp_f32_e32 v179, v176
	v_min_f32_e32 v176, 0x71800000, v173
	v_add_f32_e32 v173, 1.0, v177
	v_add_f32_e32 v170, 1.0, v170
	v_add_f32_e32 v177, 1.0, v179
	v_min_f32_e32 v170, 0x71800000, v170
	v_min_f32_e32 v171, 0x71800000, v171
	v_min_f32_e32 v172, 0x71800000, v172
	v_min_f32_e32 v173, 0x71800000, v173
	v_min_f32_e32 v177, 0x71800000, v177
	s_mov_b64 s[40:41], 0

; DI float fsigmoid(float x) { return frcp(1.0f + fexp(-x)); }
; DI u32x4 pack8(f32x4 a, f32x4 b) { u32x4 w; w.x = pk2(a[0], a[1]); w.y = pk2(a[2], a[3]); w.z = pk2(b[0], b[1]); w.w = pk2(b[2], b[3]); return w; }
;     DI void operator()(Acc& acc, const Unit& u, int wr, int wc, int fr, int fq) const {
;     ...
;                     else if (pn < 9) {}
;                     else if (pn < 13) { v0 *= 0.08838834764831845f * LOG2E; v1 *= 0.08838834764831845f * LOG2E; }
;                     else {
; #pragma unroll
;                         for (int j = 0; j < 4; ++j) { v0[j] = fsigmoid(v0[j]); v1[j] = fsigmoid(v1[j]); } }
;                     const u32x4 w8 = pack8(v0, v1);
.LBB0_447:
	s_andn2_b64 vcc, exec, s[52:53]
	s_mov_b64 s[40:41], -1
	s_cbranch_vccnz .LBB0_454
	s_andn2_b64 vcc, exec, s[18:19]
	v_mov_b32_e32 v179, v57
	v_mov_b32_e32 v178, v56
	v_mov_b32_e32 v177, v55
	v_mov_b32_e32 v176, v54
	v_mov_b32_e32 v185, v53
	v_mov_b32_e32 v184, v52
	v_mov_b32_e32 v181, v51
	v_mov_b32_e32 v180, v50
	s_cbranch_vccnz .LBB0_453
	s_andn2_b64 vcc, exec, s[16:17]
	s_cbranch_vccnz .LBB0_451
	v_mul_f32_e32 v154, 0xbfb8aa3b, v54
	v_exp_f32_e32 v154, v154
	v_mul_f32_e32 v176, 0xbfb8aa3b, v50
	v_exp_f32_e32 v176, v176
	v_mul_f32_e32 v178, 0xbfb8aa3b, v51
	v_add_f32_e32 v154, 1.0, v154
	v_exp_f32_e32 v178, v178
	v_add_f32_e32 v177, 1.0, v176
	v_min_f32_e32 v176, 0x71800000, v154
	v_mul_f32_e32 v154, 0xbfb8aa3b, v55
	v_exp_f32_e32 v154, v154
	v_min_f32_e32 v180, 0x71800000, v177
	v_mul_f32_e32 v179, 0xbfb8aa3b, v52
	v_exp_f32_e32 v179, v179
	v_add_f32_e32 v154, 1.0, v154
	v_min_f32_e32 v177, 0x71800000, v154
	v_add_f32_e32 v154, 1.0, v178
	v_mul_f32_e32 v178, 0xbfb8aa3b, v56
	v_exp_f32_e32 v178, v178
	v_min_f32_e32 v181, 0x71800000, v154
	v_mul_f32_e32 v184, 0xbfb8aa3b, v53
	v_exp_f32_e32 v185, v184
	v_add_f32_e32 v154, 1.0, v178
	v_min_f32_e32 v178, 0x71800000, v154
	v_add_f32_e32 v154, 1.0, v179
	v_mul_f32_e32 v179, 0xbfb8aa3b, v57
	v_exp_f32_e32 v179, v179
	v_min_f32_e32 v184, 0x71800000, v154
	s_mov_b64 s[40:41], 0
	v_add_f32_e32 v154, 1.0, v179
	v_min_f32_e32 v179, 0x71800000, v154
	v_add_f32_e32 v154, 1.0, v185
	v_min_f32_e32 v185, 0x71800000, v154

; DI float fsigmoid(float x) { return frcp(1.0f + fexp(-x)); }
; DI u32x4 pack8(f32x4 a, f32x4 b) { u32x4 w; w.x = pk2(a[0], a[1]); w.y = pk2(a[2], a[3]); w.z = pk2(b[0], b[1]); w.w = pk2(b[2], b[3]); return w; }
;     DI void operator()(Acc& acc, const Unit& u, int wr, int wc, int fr, int fq) const {
;     ...
;                     else if (pn < 9) {}
;                     else if (pn < 13) { v0 *= 0.08838834764831845f * LOG2E; v1 *= 0.08838834764831845f * LOG2E; }
;                     else {
; #pragma unroll
;                         for (int j = 0; j < 4; ++j) { v0[j] = fsigmoid(v0[j]); v1[j] = fsigmoid(v1[j]); } }
;                     const u32x4 w8 = pack8(v0, v1);
.LBB0_481:
	s_andn2_b64 vcc, exec, s[52:53]
	s_mov_b64 s[40:41], -1
	s_cbranch_vccnz .LBB0_488
	s_andn2_b64 vcc, exec, s[18:19]
	v_mov_b32_e32 v173, v49
	v_mov_b32_e32 v172, v48
	v_mov_b32_e32 v171, v47
	v_mov_b32_e32 v170, v46
	v_mov_b32_e32 v177, v45
	v_mov_b32_e32 v176, v44
	v_mov_b32_e32 v175, v43
	v_mov_b32_e32 v174, v42
	s_cbranch_vccnz .LBB0_487
	s_andn2_b64 vcc, exec, s[16:17]
	s_cbranch_vccnz .LBB0_485
	v_mul_f32_e32 v171, 0xbfb8aa3b, v42
	v_exp_f32_e32 v171, v171
	v_mul_f32_e32 v172, 0xbfb8aa3b, v47
	v_mul_f32_e32 v173, 0xbfb8aa3b, v43
	v_exp_f32_e32 v172, v172
	v_exp_f32_e32 v173, v173
	v_add_f32_e32 v171, 1.0, v171
	v_min_f32_e32 v174, 0x71800000, v171
	v_add_f32_e32 v171, 1.0, v172
	v_add_f32_e32 v172, 1.0, v173
	v_mul_f32_e32 v173, 0xbfb8aa3b, v48
	v_mul_f32_e32 v175, 0xbfb8aa3b, v44
	v_exp_f32_e32 v173, v173
	v_exp_f32_e32 v176, v175
	v_min_f32_e32 v175, 0x71800000, v172
	v_mul_f32_e32 v170, 0xbfb8aa3b, v46
	v_add_f32_e32 v172, 1.0, v173
	v_add_f32_e32 v173, 1.0, v176
	v_mul_f32_e32 v176, 0xbfb8aa3b, v49
	v_exp_f32_e32 v177, v176
	v_mul_f32_e32 v176, 0xbfb8aa3b, v45
	v_exp_f32_e32 v170, v170
	v_exp_f32_e32 v179, v176
	v_min_f32_e32 v176, 0x71800000, v173
	v_add_f32_e32 v173, 1.0, v177
	v_add_f32_e32 v170, 1.0, v170
	v_add_f32_e32 v177, 1.0, v179
	v_min_f32_e32 v170, 0x71800000, v170
	v_min_f32_e32 v171, 0x71800000, v171
	v_min_f32_e32 v172, 0x71800000, v172
	v_min_f32_e32 v173, 0x71800000, v173
	v_min_f32_e32 v177, 0x71800000, v177
	s_mov_b64 s[40:41], 0

; DI float fsigmoid(float x) { return frcp(1.0f + fexp(-x)); }
; DI u32x4 pack8(f32x4 a, f32x4 b) { u32x4 w; w.x = pk2(a[0], a[1]); w.y = pk2(a[2], a[3]); w.z = pk2(b[0], b[1]); w.w = pk2(b[2], b[3]); return w; }
;     DI void operator()(Acc& acc, const Unit& u, int wr, int wc, int fr, int fq) const {
;     ...
;                     else if (pn < 9) {}
;                     else if (pn < 13) { v0 *= 0.08838834764831845f * LOG2E; v1 *= 0.08838834764831845f * LOG2E; }
;                     else {
; #pragma unroll
;                         for (int j = 0; j < 4; ++j) { v0[j] = fsigmoid(v0[j]); v1[j] = fsigmoid(v1[j]); } }
;                     const u32x4 w8 = pack8(v0, v1);
.LBB0_513:
	s_andn2_b64 vcc, exec, s[52:53]
	s_mov_b64 s[40:41], -1
	s_cbranch_vccnz .LBB0_520
	s_andn2_b64 vcc, exec, s[18:19]
	v_mov_b32_e32 v179, v41
	v_mov_b32_e32 v178, v40
	v_mov_b32_e32 v177, v39
	v_mov_b32_e32 v176, v38
	v_mov_b32_e32 v185, v37
	v_mov_b32_e32 v184, v36
	v_mov_b32_e32 v181, v35
	v_mov_b32_e32 v180, v34
	s_cbranch_vccnz .LBB0_519
	s_andn2_b64 vcc, exec, s[16:17]
	s_cbranch_vccnz .LBB0_517
	v_mul_f32_e32 v154, 0xbfb8aa3b, v38
	v_exp_f32_e32 v154, v154
	v_mul_f32_e32 v176, 0xbfb8aa3b, v34
	v_exp_f32_e32 v176, v176
	v_mul_f32_e32 v178, 0xbfb8aa3b, v35
	v_add_f32_e32 v154, 1.0, v154
	v_exp_f32_e32 v178, v178
	v_add_f32_e32 v177, 1.0, v176
	v_min_f32_e32 v176, 0x71800000, v154
	v_mul_f32_e32 v154, 0xbfb8aa3b, v39
	v_exp_f32_e32 v154, v154
	v_min_f32_e32 v180, 0x71800000, v177
	v_mul_f32_e32 v179, 0xbfb8aa3b, v36
	v_exp_f32_e32 v179, v179
	v_add_f32_e32 v154, 1.0, v154
	v_min_f32_e32 v177, 0x71800000, v154
	v_add_f32_e32 v154, 1.0, v178
	v_mul_f32_e32 v178, 0xbfb8aa3b, v40
	v_exp_f32_e32 v178, v178
	v_min_f32_e32 v181, 0x71800000, v154
	v_mul_f32_e32 v184, 0xbfb8aa3b, v37
	v_exp_f32_e32 v185, v184
	v_add_f32_e32 v154, 1.0, v178
	v_min_f32_e32 v178, 0x71800000, v154
	v_add_f32_e32 v154, 1.0, v179
	v_mul_f32_e32 v179, 0xbfb8aa3b, v41
	v_exp_f32_e32 v179, v179
	v_min_f32_e32 v184, 0x71800000, v154
	s_mov_b64 s[40:41], 0
	v_add_f32_e32 v154, 1.0, v179
	v_min_f32_e32 v179, 0x71800000, v154
	v_add_f32_e32 v154, 1.0, v185
	v_min_f32_e32 v185, 0x71800000, v154

; DI float fsigmoid(float x) { return frcp(1.0f + fexp(-x)); }
; DI u32x4 pack8(f32x4 a, f32x4 b) { u32x4 w; w.x = pk2(a[0], a[1]); w.y = pk2(a[2], a[3]); w.z = pk2(b[0], b[1]); w.w = pk2(b[2], b[3]); return w; }
;     DI void operator()(Acc& acc, const Unit& u, int wr, int wc, int fr, int fq) const {
;     ...
;                     else if (pn < 9) {}
;                     else if (pn < 13) { v0 *= 0.08838834764831845f * LOG2E; v1 *= 0.08838834764831845f * LOG2E; }
;                     else {
; #pragma unroll
;                         for (int j = 0; j < 4; ++j) { v0[j] = fsigmoid(v0[j]); v1[j] = fsigmoid(v1[j]); } }
;                     const u32x4 w8 = pack8(v0, v1);
.LBB0_547:
	s_andn2_b64 vcc, exec, s[52:53]
	s_mov_b64 s[40:41], -1
	s_cbranch_vccnz .LBB0_554
	s_andn2_b64 vcc, exec, s[18:19]
	v_mov_b32_e32 v173, v33
	v_mov_b32_e32 v172, v32
	v_mov_b32_e32 v171, v31
	v_mov_b32_e32 v170, v30
	v_mov_b32_e32 v177, v29
	v_mov_b32_e32 v176, v28
	v_mov_b32_e32 v175, v27
	v_mov_b32_e32 v174, v26
	s_cbranch_vccnz .LBB0_553
	s_andn2_b64 vcc, exec, s[16:17]
	s_cbranch_vccnz .LBB0_551
	v_mul_f32_e32 v171, 0xbfb8aa3b, v26
	v_exp_f32_e32 v171, v171
	v_mul_f32_e32 v172, 0xbfb8aa3b, v31
	v_mul_f32_e32 v173, 0xbfb8aa3b, v27
	v_exp_f32_e32 v172, v172
	v_exp_f32_e32 v173, v173
	v_add_f32_e32 v171, 1.0, v171
	v_min_f32_e32 v174, 0x71800000, v171
	v_add_f32_e32 v171, 1.0, v172
	v_add_f32_e32 v172, 1.0, v173
	v_mul_f32_e32 v173, 0xbfb8aa3b, v32
	v_mul_f32_e32 v175, 0xbfb8aa3b, v28
	v_exp_f32_e32 v173, v173
	v_exp_f32_e32 v176, v175
	v_min_f32_e32 v175, 0x71800000, v172
	v_mul_f32_e32 v170, 0xbfb8aa3b, v30
	v_add_f32_e32 v172, 1.0, v173
	v_add_f32_e32 v173, 1.0, v176
	v_mul_f32_e32 v176, 0xbfb8aa3b, v33
	v_exp_f32_e32 v177, v176
	v_mul_f32_e32 v176, 0xbfb8aa3b, v29
	v_exp_f32_e32 v170, v170
	v_exp_f32_e32 v179, v176
	v_min_f32_e32 v176, 0x71800000, v173
	v_add_f32_e32 v173, 1.0, v177
	v_add_f32_e32 v170, 1.0, v170
	v_add_f32_e32 v177, 1.0, v179
	v_min_f32_e32 v170, 0x71800000, v170
	v_min_f32_e32 v171, 0x71800000, v171
	v_min_f32_e32 v172, 0x71800000, v172
	v_min_f32_e32 v173, 0x71800000, v173
	v_min_f32_e32 v177, 0x71800000, v177
	s_mov_b64 s[40:41], 0

; DI float fsigmoid(float x) { return frcp(1.0f + fexp(-x)); }
; DI u32x4 pack8(f32x4 a, f32x4 b) { u32x4 w; w.x = pk2(a[0], a[1]); w.y = pk2(a[2], a[3]); w.z = pk2(b[0], b[1]); w.w = pk2(b[2], b[3]); return w; }
;     DI void operator()(Acc& acc, const Unit& u, int wr, int wc, int fr, int fq) const {
;     ...
;                     else if (pn < 9) {}
;                     else if (pn < 13) { v0 *= 0.08838834764831845f * LOG2E; v1 *= 0.08838834764831845f * LOG2E; }
;                     else {
; #pragma unroll
;                         for (int j = 0; j < 4; ++j) { v0[j] = fsigmoid(v0[j]); v1[j] = fsigmoid(v1[j]); } }
;                     const u32x4 w8 = pack8(v0, v1);
.LBB0_579:
	s_andn2_b64 vcc, exec, s[52:53]
	s_mov_b64 s[40:41], -1
	s_cbranch_vccnz .LBB0_586
	s_andn2_b64 vcc, exec, s[18:19]
	v_mov_b32_e32 v179, v25
	v_mov_b32_e32 v178, v24
	v_mov_b32_e32 v177, v23
	v_mov_b32_e32 v176, v22
	v_mov_b32_e32 v185, v21
	v_mov_b32_e32 v184, v20
	v_mov_b32_e32 v181, v19
	v_mov_b32_e32 v180, v18
	s_cbranch_vccnz .LBB0_585
	s_andn2_b64 vcc, exec, s[16:17]
	s_cbranch_vccnz .LBB0_583
	v_mul_f32_e32 v154, 0xbfb8aa3b, v22
	v_exp_f32_e32 v154, v154
	v_mul_f32_e32 v176, 0xbfb8aa3b, v18
	v_exp_f32_e32 v176, v176
	v_mul_f32_e32 v178, 0xbfb8aa3b, v19
	v_add_f32_e32 v154, 1.0, v154
	v_exp_f32_e32 v178, v178
	v_add_f32_e32 v177, 1.0, v176
	v_min_f32_e32 v176, 0x71800000, v154
	v_mul_f32_e32 v154, 0xbfb8aa3b, v23
	v_exp_f32_e32 v154, v154
	v_min_f32_e32 v180, 0x71800000, v177
	v_mul_f32_e32 v179, 0xbfb8aa3b, v20
	v_exp_f32_e32 v179, v179
	v_add_f32_e32 v154, 1.0, v154
	v_min_f32_e32 v177, 0x71800000, v154
	v_add_f32_e32 v154, 1.0, v178
	v_mul_f32_e32 v178, 0xbfb8aa3b, v24
	v_exp_f32_e32 v178, v178
	v_min_f32_e32 v181, 0x71800000, v154
	v_mul_f32_e32 v184, 0xbfb8aa3b, v21
	v_exp_f32_e32 v185, v184
	v_add_f32_e32 v154, 1.0, v178
	v_min_f32_e32 v178, 0x71800000, v154
	v_add_f32_e32 v154, 1.0, v179
	v_mul_f32_e32 v179, 0xbfb8aa3b, v25
	v_exp_f32_e32 v179, v179
	v_min_f32_e32 v184, 0x71800000, v154
	s_mov_b64 s[40:41], 0
	v_add_f32_e32 v154, 1.0, v179
	v_min_f32_e32 v179, 0x71800000, v154
	v_add_f32_e32 v154, 1.0, v185
	v_min_f32_e32 v185, 0x71800000, v154

; DI float fsigmoid(float x) { return frcp(1.0f + fexp(-x)); }
; DI u32x4 pack8(f32x4 a, f32x4 b) { u32x4 w; w.x = pk2(a[0], a[1]); w.y = pk2(a[2], a[3]); w.z = pk2(b[0], b[1]); w.w = pk2(b[2], b[3]); return w; }
;     DI void operator()(Acc& acc, const Unit& u, int wr, int wc, int fr, int fq) const {
;     ...
;                     else if (pn < 9) {}
;                     else if (pn < 13) { v0 *= 0.08838834764831845f * LOG2E; v1 *= 0.08838834764831845f * LOG2E; }
;                     else {
; #pragma unroll
;                         for (int j = 0; j < 4; ++j) { v0[j] = fsigmoid(v0[j]); v1[j] = fsigmoid(v1[j]); } }
;                     const u32x4 w8 = pack8(v0, v1);
.LBB0_613:
	s_andn2_b64 vcc, exec, s[52:53]
	s_mov_b64 s[40:41], -1
	s_cbranch_vccnz .LBB0_620
	s_andn2_b64 vcc, exec, s[18:19]
	v_mov_b32_e32 v173, v17
	v_mov_b32_e32 v172, v16
	v_mov_b32_e32 v171, v15
	v_mov_b32_e32 v170, v14
	v_mov_b32_e32 v177, v13
	v_mov_b32_e32 v176, v12
	v_mov_b32_e32 v175, v11
	v_mov_b32_e32 v174, v10
	s_cbranch_vccnz .LBB0_619
	s_andn2_b64 vcc, exec, s[16:17]
	s_cbranch_vccnz .LBB0_617
	v_mul_f32_e32 v161, 0xbfb8aa3b, v14
	v_exp_f32_e32 v161, v161
	v_mul_f32_e32 v170, 0xbfb8aa3b, v10
	v_exp_f32_e32 v170, v170
	v_mul_f32_e32 v172, 0xbfb8aa3b, v11
	v_add_f32_e32 v161, 1.0, v161
	v_exp_f32_e32 v172, v172
	v_add_f32_e32 v171, 1.0, v170
	v_min_f32_e32 v170, 0x71800000, v161
	v_mul_f32_e32 v161, 0xbfb8aa3b, v15
	v_exp_f32_e32 v161, v161
	v_min_f32_e32 v174, 0x71800000, v171
	v_mul_f32_e32 v173, 0xbfb8aa3b, v12
	v_exp_f32_e32 v173, v173
	v_add_f32_e32 v161, 1.0, v161
	v_min_f32_e32 v171, 0x71800000, v161
	v_add_f32_e32 v161, 1.0, v172
	v_mul_f32_e32 v172, 0xbfb8aa3b, v16
	v_exp_f32_e32 v172, v172
	v_min_f32_e32 v175, 0x71800000, v161
	v_mul_f32_e32 v176, 0xbfb8aa3b, v13
	v_exp_f32_e32 v177, v176
	v_add_f32_e32 v161, 1.0, v172
	v_min_f32_e32 v172, 0x71800000, v161
	v_add_f32_e32 v161, 1.0, v173
	v_mul_f32_e32 v173, 0xbfb8aa3b, v17
	v_exp_f32_e32 v173, v173
	v_min_f32_e32 v176, 0x71800000, v161
	s_mov_b64 s[40:41], 0
	v_add_f32_e32 v161, 1.0, v173
	v_min_f32_e32 v173, 0x71800000, v161
	v_add_f32_e32 v161, 1.0, v177
	v_min_f32_e32 v177, 0x71800000, v161

; DI float fsigmoid(float x) { return frcp(1.0f + fexp(-x)); }
; DI u32x4 pack8(f32x4 a, f32x4 b) { u32x4 w; w.x = pk2(a[0], a[1]); w.y = pk2(a[2], a[3]); w.z = pk2(b[0], b[1]); w.w = pk2(b[2], b[3]); return w; }
;     DI void operator()(Acc& acc, const Unit& u, int wr, int wc, int fr, int fq) const {
;     ...
;                     else if (pn < 9) {}
;                     else if (pn < 13) { v0 *= 0.08838834764831845f * LOG2E; v1 *= 0.08838834764831845f * LOG2E; }
;                     else {
; #pragma unroll
;                         for (int j = 0; j < 4; ++j) { v0[j] = fsigmoid(v0[j]); v1[j] = fsigmoid(v1[j]); } }
;                     const u32x4 w8 = pack8(v0, v1);
.LBB0_710:
	s_andn2_b64 vcc, exec, s[52:53]
	s_mov_b64 s[4:5], -1
	s_cbranch_vccnz .LBB0_717
	s_andn2_b64 vcc, exec, s[18:19]
	v_mov_b32_e32 v167, v9
	v_mov_b32_e32 v166, v8
	v_mov_b32_e32 v145, v7
	v_mov_b32_e32 v144, v6
	v_mov_b32_e32 v173, v5
	v_mov_b32_e32 v172, v4
	v_mov_b32_e32 v171, v3
	v_mov_b32_e32 v170, v2
	s_cbranch_vccnz .LBB0_716
	s_andn2_b64 vcc, exec, s[16:17]
	s_cbranch_vccnz .LBB0_714
	v_mul_f32_e32 v145, 0xbfb8aa3b, v2
	v_exp_f32_e32 v145, v145
	v_mul_f32_e32 v154, 0xbfb8aa3b, v7
	v_mul_f32_e32 v166, 0xbfb8aa3b, v3
	v_exp_f32_e32 v154, v154
	v_exp_f32_e32 v166, v166
	v_add_f32_e32 v145, 1.0, v145
	v_min_f32_e32 v170, 0x71800000, v145
	v_add_f32_e32 v145, 1.0, v154
	v_add_f32_e32 v154, 1.0, v166
	v_mul_f32_e32 v166, 0xbfb8aa3b, v8
	v_exp_f32_e32 v166, v166
	v_mul_f32_e32 v167, 0xbfb8aa3b, v4
	v_exp_f32_e32 v167, v167
	v_min_f32_e32 v171, 0x71800000, v154
	v_add_f32_e32 v154, 1.0, v166
	v_min_f32_e32 v166, 0x71800000, v154
	v_add_f32_e32 v154, 1.0, v167
	v_mul_f32_e32 v167, 0xbfb8aa3b, v9
	v_mul_f32_e32 v144, 0xbfb8aa3b, v6
	v_exp_f32_e32 v167, v167
	v_mul_f32_e32 v172, 0xbfb8aa3b, v5
	v_exp_f32_e32 v144, v144
	v_exp_f32_e32 v173, v172
	v_min_f32_e32 v172, 0x71800000, v154
	v_add_f32_e32 v154, 1.0, v167
	v_add_f32_e32 v144, 1.0, v144
	v_min_f32_e32 v167, 0x71800000, v154
	v_add_f32_e32 v154, 1.0, v173
	v_min_f32_e32 v144, 0x71800000, v144
	v_min_f32_e32 v145, 0x71800000, v145
	v_min_f32_e32 v173, 0x71800000, v154
	s_mov_b64 s[4:5], 0

; DI float bflo(unsigned w) { return __uint_as_float(w << 16); }
; DI float bfhi(unsigned w) { return __uint_as_float(w & 0xffff0000u); }
;     DI void operator()(Acc& acc, const Unit& u, int wr, int wc, int fr, int fq) const {
;     ...
;         bf16_t* base = proj + (size_t)(u.pm * 256 + wr * 64 + fr) * NPJ + C_GL + u.pn * 256 + wc * 32 + fq * 8;
;         {
;             u32x4 g[2][4][2];
; #pragma unroll
;             for (int ai = 0; ai < 2; ++ai)
; #pragma unroll
;                 for (int m = 0; m < 4; ++m)
; #pragma unroll
;                     for (int bj = 0; bj < 2; ++bj) g[ai][m][bj] = *(const u32x4*)(base + (size_t)(ai * 128 + m * 16) * NPJ + u.k * 1024 + bj * 128);
; #pragma unroll
;             for (int ai = 0; ai < 2; ++ai)
; #pragma unroll
;                 for (int m = 0; m < 4; ++m)
; #pragma unroll
;                     for (int bj = 0; bj < 2; ++bj) { const u32x4 q = g[ai][m][bj]; f32x4& v0 = acc[ai][bj][m][0]; f32x4& v1 = acc[ai][bj][m][1];
;                         v0[0] *= bflo(q.x); v0[1] *= bfhi(q.x); v0[2] *= bflo(q.y); v0[3] *= bfhi(q.y); v1[0] *= bflo(q.z); v1[1] *= bfhi(q.z); v1[2] *= bflo(q.w); v1[3] *= bfhi(q.w); }
.LBB0_948:
	v_mov_b32_e32 v130, v1
	v_mov_b32_e32 v132, v172
	s_lshl_b32 s8, s30, 1
	v_add_u32_e32 v133, s39, v130
	v_mov_b64_e32 v[130:131], s[48:49]
	v_mad_i64_i32 v[130:131], s[24:25], v133, s41, v[130:131]
	v_lshl_add_u64 v[130:131], v[130:131], 0, s[8:9]
	s_mov_b32 s17, s9
	v_lshlrev_b32_e32 v132, 3, v132
	v_lshl_add_u64 v[130:131], v[130:131], 0, s[16:17]
	v_ashrrev_i32_e32 v133, 31, v132
	v_lshl_add_u64 v[130:131], v[132:133], 1, v[130:131]
	v_lshl_add_u64 v[166:167], v[130:131], 0, s[18:19]
	s_lshl_b32 s8, s84, 10
	v_lshl_add_u64 v[130:131], s[8:9], 1, v[166:167]
	s_nop 0
	v_readfirstlane_b32 s98, v130
	v_readfirstlane_b32 s99, v131
	v_bfe_u32 v146, v183, 5, 3
	v_mul_u32_u24_e32 v146, 0x3200, v146
	v_and_b32_e32 v147, 31, v183
	v_lshl_add_u32 v146, v147, 4, v146
	v_bfe_u32 v147, v183, 6, 2
	v_lshlrev_b32_e32 v147, 6, v147
	v_sub_u32_e32 v243, v146, v147
	s_cmp_eq_u32 s84, 2
	s_cbranch_scc1 .Lup3_final
	s_add_u32 s100, s98, 0x0
	s_addc_u32 s101, s99, 0
	global_load_dwordx4 v[184:187], v243, s[100:101]
	s_add_u32 s100, s98, 0x19000
	s_addc_u32 s101, s99, 0
	global_load_dwordx4 v[188:191], v243, s[100:101]
	s_add_u32 s100, s98, 0x0
	s_addc_u32 s101, s99, 0
	global_load_dwordx4 v[192:195], v243, s[100:101] offset:2048
	s_add_u32 s100, s98, 0x19000
	s_addc_u32 s101, s99, 0
	global_load_dwordx4 v[196:199], v243, s[100:101] offset:2048
	s_add_u32 s100, s98, 0x32000
	s_addc_u32 s101, s99, 0
	global_load_dwordx4 v[200:203], v243, s[100:101]
	s_add_u32 s100, s98, 0x4b000
	s_addc_u32 s101, s99, 0
	global_load_dwordx4 v[204:207], v243, s[100:101]
	s_add_u32 s100, s98, 0x32000
	s_addc_u32 s101, s99, 0
	global_load_dwordx4 v[208:211], v243, s[100:101] offset:2048
	s_add_u32 s100, s98, 0x4b000
	s_addc_u32 s101, s99, 0
	global_load_dwordx4 v[212:215], v243, s[100:101] offset:2048
	s_add_u32 s100, s98, 0x64000
	s_addc_u32 s101, s99, 0
	global_load_dwordx4 v[216:219], v243, s[100:101]
	s_add_u32 s100, s98, 0x7d000
	s_addc_u32 s101, s99, 0
	global_load_dwordx4 v[220:223], v243, s[100:101]
	s_add_u32 s100, s98, 0x64000
	s_addc_u32 s101, s99, 0
	global_load_dwordx4 v[224:227], v243, s[100:101] offset:2048
	s_add_u32 s100, s98, 0x7d000
	s_addc_u32 s101, s99, 0
	global_load_dwordx4 v[228:231], v243, s[100:101] offset:2048
	s_waitcnt vmcnt(8)
	v_lshlrev_b32_e32 v146, 16, v184
	v_and_b32_e32 v147, 0xffff0000, v184
	v_lshlrev_b32_e32 v148, 16, v192
	v_and_b32_e32 v149, 0xffff0000, v192
	v_lshlrev_b32_e32 v150, 16, v185
	v_and_b32_e32 v151, 0xffff0000, v185
	v_lshlrev_b32_e32 v152, 16, v193
	v_and_b32_e32 v153, 0xffff0000, v193
	v_rcp_f32_e32 v146, v146
	v_rcp_f32_e32 v147, v147
	v_rcp_f32_e32 v150, v150
	v_rcp_f32_e32 v151, v151
	s_nop 0
	v_pk_mul_f32 v[146:147], v[146:147], v[148:149]
	v_pk_mul_f32 v[150:151], v[150:151], v[152:153]
	v_pk_mul_f32 v[126:127], v[126:127], v[146:147]
	v_pk_mul_f32 v[128:129], v[128:129], v[150:151]
	v_lshlrev_b32_e32 v168, 16, v186
	v_and_b32_e32 v169, 0xffff0000, v186
	v_lshlrev_b32_e32 v178, 16, v194
	v_and_b32_e32 v179, 0xffff0000, v194
	v_lshlrev_b32_e32 v180, 16, v187
	v_and_b32_e32 v181, 0xffff0000, v187
	v_lshlrev_b32_e32 v244, 16, v195
	v_and_b32_e32 v245, 0xffff0000, v195
	v_rcp_f32_e32 v168, v168
	v_rcp_f32_e32 v169, v169
	v_rcp_f32_e32 v180, v180
	v_rcp_f32_e32 v181, v181
	s_nop 0
	v_pk_mul_f32 v[168:169], v[168:169], v[178:179]
	v_pk_mul_f32 v[180:181], v[180:181], v[244:245]
	v_pk_mul_f32 v[122:123], v[122:123], v[168:169]
	v_pk_mul_f32 v[124:125], v[124:125], v[180:181]
	v_lshlrev_b32_e32 v168, 16, v188
	v_and_b32_e32 v169, 0xffff0000, v188
	v_lshlrev_b32_e32 v178, 16, v196
	v_and_b32_e32 v179, 0xffff0000, v196
	v_lshlrev_b32_e32 v180, 16, v189
	v_and_b32_e32 v181, 0xffff0000, v189
	v_lshlrev_b32_e32 v244, 16, v197
	v_and_b32_e32 v245, 0xffff0000, v197
	v_rcp_f32_e32 v168, v168
	v_rcp_f32_e32 v169, v169
	v_rcp_f32_e32 v180, v180
	v_rcp_f32_e32 v181, v181
	s_nop 0
	v_pk_mul_f32 v[168:169], v[168:169], v[178:179]
	v_pk_mul_f32 v[180:181], v[180:181], v[244:245]
	v_pk_mul_f32 v[114:115], v[114:115], v[168:169]
	v_pk_mul_f32 v[116:117], v[116:117], v[180:181]
	v_lshlrev_b32_e32 v146, 16, v190
	v_and_b32_e32 v147, 0xffff0000, v190
	v_lshlrev_b32_e32 v148, 16, v198
	v_and_b32_e32 v149, 0xffff0000, v198
	v_lshlrev_b32_e32 v150, 16, v191
	v_and_b32_e32 v151, 0xffff0000, v191
	v_lshlrev_b32_e32 v152, 16, v199
	v_and_b32_e32 v153, 0xffff0000, v199
	v_rcp_f32_e32 v146, v146
	v_rcp_f32_e32 v147, v147
	v_rcp_f32_e32 v150, v150
	v_rcp_f32_e32 v151, v151
	s_nop 0
	v_pk_mul_f32 v[146:147], v[146:147], v[148:149]
	v_pk_mul_f32 v[150:151], v[150:151], v[152:153]
	v_pk_mul_f32 v[110:111], v[110:111], v[146:147]
	v_pk_mul_f32 v[112:113], v[112:113], v[150:151]
	s_add_u32 s100, s98, 0x96000
	s_addc_u32 s101, s99, 0
	global_load_dwordx4 v[184:187], v243, s[100:101]
	s_add_u32 s100, s98, 0xaf000
	s_addc_u32 s101, s99, 0
	global_load_dwordx4 v[188:191], v243, s[100:101]
	s_add_u32 s100, s98, 0x96000
	s_addc_u32 s101, s99, 0
	global_load_dwordx4 v[192:195], v243, s[100:101] offset:2048
	s_add_u32 s100, s98, 0xaf000
	s_addc_u32 s101, s99, 0
	global_load_dwordx4 v[196:199], v243, s[100:101] offset:2048
	s_waitcnt vmcnt(8)
; DI float bflo(unsigned w) { return __uint_as_float(w << 16); }
; DI float bfhi(unsigned w) { return __uint_as_float(w & 0xffff0000u); }
;     DI void operator()(Acc& acc, const Unit& u, int wr, int wc, int fr, int fq) const {
;     ...
;             for (int ai = 0; ai < 2; ++ai)
; #pragma unroll
;                 for (int m = 0; m < 4; ++m)
; #pragma unroll
;                     for (int bj = 0; bj < 2; ++bj) g[ai][m][bj] = *(const u32x4*)(base + (size_t)(ai * 128 + m * 16) * NPJ + u.k * 1024 + bj * 128);
; #pragma unroll
;             for (int ai = 0; ai < 2; ++ai)
; #pragma unroll
;                 for (int m = 0; m < 4; ++m)
; #pragma unroll
;                     for (int bj = 0; bj < 2; ++bj) { const u32x4 q = g[ai][m][bj]; f32x4& v0 = acc[ai][bj][m][0]; f32x4& v1 = acc[ai][bj][m][1];
;                         v0[0] *= bflo(q.x); v0[1] *= bfhi(q.x); v0[2] *= bflo(q.y); v0[3] *= bfhi(q.y); v1[0] *= bflo(q.z); v1[1] *= bfhi(q.z); v1[2] *= bflo(q.w); v1[3] *= bfhi(q.w); }
	v_lshlrev_b32_e32 v146, 16, v200
	v_and_b32_e32 v147, 0xffff0000, v200
	v_lshlrev_b32_e32 v148, 16, v208
	v_and_b32_e32 v149, 0xffff0000, v208
	v_lshlrev_b32_e32 v150, 16, v201
	v_and_b32_e32 v151, 0xffff0000, v201
	v_lshlrev_b32_e32 v152, 16, v209
	v_and_b32_e32 v153, 0xffff0000, v209
	v_rcp_f32_e32 v146, v146
	v_rcp_f32_e32 v147, v147
	v_rcp_f32_e32 v150, v150
	v_rcp_f32_e32 v151, v151
	s_nop 0
	v_pk_mul_f32 v[146:147], v[146:147], v[148:149]
	v_pk_mul_f32 v[150:151], v[150:151], v[152:153]
	v_pk_mul_f32 v[118:119], v[118:119], v[146:147]
	v_pk_mul_f32 v[120:121], v[120:121], v[150:151]
	v_lshlrev_b32_e32 v168, 16, v202
	v_and_b32_e32 v169, 0xffff0000, v202
	v_lshlrev_b32_e32 v178, 16, v210
	v_and_b32_e32 v179, 0xffff0000, v210
	v_lshlrev_b32_e32 v180, 16, v203
	v_and_b32_e32 v181, 0xffff0000, v203
	v_lshlrev_b32_e32 v244, 16, v211
	v_and_b32_e32 v245, 0xffff0000, v211
	v_rcp_f32_e32 v168, v168
	v_rcp_f32_e32 v169, v169
	v_rcp_f32_e32 v180, v180
	v_rcp_f32_e32 v181, v181
	s_nop 0
	v_pk_mul_f32 v[168:169], v[168:169], v[178:179]
	v_pk_mul_f32 v[180:181], v[180:181], v[244:245]
	v_pk_mul_f32 v[106:107], v[106:107], v[168:169]
	v_pk_mul_f32 v[108:109], v[108:109], v[180:181]
	v_lshlrev_b32_e32 v168, 16, v204
	v_and_b32_e32 v169, 0xffff0000, v204
	v_lshlrev_b32_e32 v178, 16, v212
	v_and_b32_e32 v179, 0xffff0000, v212
	v_lshlrev_b32_e32 v180, 16, v205
	v_and_b32_e32 v181, 0xffff0000, v205
	v_lshlrev_b32_e32 v244, 16, v213
	v_and_b32_e32 v245, 0xffff0000, v213
	v_rcp_f32_e32 v168, v168
	v_rcp_f32_e32 v169, v169
	v_rcp_f32_e32 v180, v180
	v_rcp_f32_e32 v181, v181
	s_nop 0
	v_pk_mul_f32 v[168:169], v[168:169], v[178:179]
	v_pk_mul_f32 v[180:181], v[180:181], v[244:245]
	v_pk_mul_f32 v[98:99], v[98:99], v[168:169]
	v_pk_mul_f32 v[100:101], v[100:101], v[180:181]
	v_lshlrev_b32_e32 v146, 16, v206
	v_and_b32_e32 v147, 0xffff0000, v206
	v_lshlrev_b32_e32 v148, 16, v214
	v_and_b32_e32 v149, 0xffff0000, v214
	v_lshlrev_b32_e32 v150, 16, v207
	v_and_b32_e32 v151, 0xffff0000, v207
	v_lshlrev_b32_e32 v152, 16, v215
	v_and_b32_e32 v153, 0xffff0000, v215
	v_rcp_f32_e32 v146, v146
	v_rcp_f32_e32 v147, v147
	v_rcp_f32_e32 v150, v150
	v_rcp_f32_e32 v151, v151
	s_nop 0
	v_pk_mul_f32 v[146:147], v[146:147], v[148:149]
	v_pk_mul_f32 v[150:151], v[150:151], v[152:153]
	v_pk_mul_f32 v[90:91], v[90:91], v[146:147]
	v_pk_mul_f32 v[92:93], v[92:93], v[150:151]
	s_add_u32 s100, s98, 0x190000
	s_addc_u32 s101, s99, 0
	global_load_dwordx4 v[200:203], v243, s[100:101]
	s_add_u32 s100, s98, 0x1a9000
	s_addc_u32 s101, s99, 0
	global_load_dwordx4 v[204:207], v243, s[100:101]
	s_add_u32 s100, s98, 0x190000
	s_addc_u32 s101, s99, 0
	global_load_dwordx4 v[208:211], v243, s[100:101] offset:2048
	s_add_u32 s100, s98, 0x1a9000
	s_addc_u32 s101, s99, 0
	global_load_dwordx4 v[212:215], v243, s[100:101] offset:2048
	s_waitcnt vmcnt(8)
	v_lshlrev_b32_e32 v146, 16, v216
	v_and_b32_e32 v147, 0xffff0000, v216
	v_lshlrev_b32_e32 v148, 16, v224
	v_and_b32_e32 v149, 0xffff0000, v224
	v_lshlrev_b32_e32 v150, 16, v217
	v_and_b32_e32 v151, 0xffff0000, v217
	v_lshlrev_b32_e32 v152, 16, v225
	v_and_b32_e32 v153, 0xffff0000, v225
	v_rcp_f32_e32 v146, v146
	v_rcp_f32_e32 v147, v147
	v_rcp_f32_e32 v150, v150
	v_rcp_f32_e32 v151, v151
	s_nop 0
	v_pk_mul_f32 v[146:147], v[146:147], v[148:149]
	v_pk_mul_f32 v[150:151], v[150:151], v[152:153]
	v_pk_mul_f32 v[102:103], v[102:103], v[146:147]
	v_pk_mul_f32 v[104:105], v[104:105], v[150:151]
	v_lshlrev_b32_e32 v168, 16, v218
	v_and_b32_e32 v169, 0xffff0000, v218
	v_lshlrev_b32_e32 v178, 16, v226
	v_and_b32_e32 v179, 0xffff0000, v226
	v_lshlrev_b32_e32 v180, 16, v219
	v_and_b32_e32 v181, 0xffff0000, v219
	v_lshlrev_b32_e32 v244, 16, v227
	v_and_b32_e32 v245, 0xffff0000, v227
	v_rcp_f32_e32 v168, v168
	v_rcp_f32_e32 v169, v169
	v_rcp_f32_e32 v180, v180
	v_rcp_f32_e32 v181, v181
	s_nop 0
	v_pk_mul_f32 v[168:169], v[168:169], v[178:179]
	v_pk_mul_f32 v[180:181], v[180:181], v[244:245]
	v_pk_mul_f32 v[94:95], v[94:95], v[168:169]
	v_pk_mul_f32 v[96:97], v[96:97], v[180:181]
	v_lshlrev_b32_e32 v168, 16, v220
	v_and_b32_e32 v169, 0xffff0000, v220
	v_lshlrev_b32_e32 v178, 16, v228
	v_and_b32_e32 v179, 0xffff0000, v228
	v_lshlrev_b32_e32 v180, 16, v221
	v_and_b32_e32 v181, 0xffff0000, v221
	v_lshlrev_b32_e32 v244, 16, v229
	v_and_b32_e32 v245, 0xffff0000, v229
	v_rcp_f32_e32 v168, v168
	v_rcp_f32_e32 v169, v169
	v_rcp_f32_e32 v180, v180
	v_rcp_f32_e32 v181, v181
	s_nop 0
	v_pk_mul_f32 v[168:169], v[168:169], v[178:179]
	v_pk_mul_f32 v[180:181], v[180:181], v[244:245]
	v_pk_mul_f32 v[82:83], v[82:83], v[168:169]
	v_pk_mul_f32 v[84:85], v[84:85], v[180:181]
	v_lshlrev_b32_e32 v146, 16, v222
	v_and_b32_e32 v147, 0xffff0000, v222
	v_lshlrev_b32_e32 v148, 16, v230
	v_and_b32_e32 v149, 0xffff0000, v230
	v_lshlrev_b32_e32 v150, 16, v223
	v_and_b32_e32 v151, 0xffff0000, v223
	v_lshlrev_b32_e32 v152, 16, v231
	v_and_b32_e32 v153, 0xffff0000, v231
	v_rcp_f32_e32 v146, v146
	v_rcp_f32_e32 v147, v147
	v_rcp_f32_e32 v150, v150
	v_rcp_f32_e32 v151, v151
	s_nop 0
	v_pk_mul_f32 v[146:147], v[146:147], v[148:149]
	v_pk_mul_f32 v[150:151], v[150:151], v[152:153]
	v_pk_mul_f32 v[74:75], v[74:75], v[146:147]
	v_pk_mul_f32 v[76:77], v[76:77], v[150:151]
	s_add_u32 s100, s98, 0x1c2000
	s_addc_u32 s101, s99, 0
	global_load_dwordx4 v[216:219], v243, s[100:101]
	s_add_u32 s100, s98, 0x1db000
	s_addc_u32 s101, s99, 0
	global_load_dwordx4 v[220:223], v243, s[100:101]
	s_add_u32 s100, s98, 0x1c2000
	s_addc_u32 s101, s99, 0
	global_load_dwordx4 v[224:227], v243, s[100:101] offset:2048
	s_add_u32 s100, s98, 0x1db000
	s_addc_u32 s101, s99, 0
	global_load_dwordx4 v[228:231], v243, s[100:101] offset:2048
	s_waitcnt vmcnt(8)
; DI float bflo(unsigned w) { return __uint_as_float(w << 16); }
; DI float bfhi(unsigned w) { return __uint_as_float(w & 0xffff0000u); }
;     DI void operator()(Acc& acc, const Unit& u, int wr, int wc, int fr, int fq) const {
;     ...
;             for (int ai = 0; ai < 2; ++ai)
; #pragma unroll
;                 for (int m = 0; m < 4; ++m)
; #pragma unroll
;                     for (int bj = 0; bj < 2; ++bj) g[ai][m][bj] = *(const u32x4*)(base + (size_t)(ai * 128 + m * 16) * NPJ + u.k * 1024 + bj * 128);
; #pragma unroll
;             for (int ai = 0; ai < 2; ++ai)
; #pragma unroll
;                 for (int m = 0; m < 4; ++m)
; #pragma unroll
;                     for (int bj = 0; bj < 2; ++bj) { const u32x4 q = g[ai][m][bj]; f32x4& v0 = acc[ai][bj][m][0]; f32x4& v1 = acc[ai][bj][m][1];
;                         v0[0] *= bflo(q.x); v0[1] *= bfhi(q.x); v0[2] *= bflo(q.y); v0[3] *= bfhi(q.y); v1[0] *= bflo(q.z); v1[1] *= bfhi(q.z); v1[2] *= bflo(q.w); v1[3] *= bfhi(q.w); }
	v_lshlrev_b32_e32 v146, 16, v184
	v_and_b32_e32 v147, 0xffff0000, v184
	v_lshlrev_b32_e32 v148, 16, v192
	v_and_b32_e32 v149, 0xffff0000, v192
	v_lshlrev_b32_e32 v150, 16, v185
	v_and_b32_e32 v151, 0xffff0000, v185
	v_lshlrev_b32_e32 v152, 16, v193
	v_and_b32_e32 v153, 0xffff0000, v193
	v_rcp_f32_e32 v146, v146
	v_rcp_f32_e32 v147, v147
	v_rcp_f32_e32 v150, v150
	v_rcp_f32_e32 v151, v151
	s_nop 0
	v_pk_mul_f32 v[146:147], v[146:147], v[148:149]
	v_pk_mul_f32 v[150:151], v[150:151], v[152:153]
	v_pk_mul_f32 v[86:87], v[86:87], v[146:147]
	v_pk_mul_f32 v[88:89], v[88:89], v[150:151]
	v_lshlrev_b32_e32 v168, 16, v186
	v_and_b32_e32 v169, 0xffff0000, v186
	v_lshlrev_b32_e32 v178, 16, v194
	v_and_b32_e32 v179, 0xffff0000, v194
	v_lshlrev_b32_e32 v180, 16, v187
	v_and_b32_e32 v181, 0xffff0000, v187
	v_lshlrev_b32_e32 v244, 16, v195
	v_and_b32_e32 v245, 0xffff0000, v195
	v_rcp_f32_e32 v168, v168
	v_rcp_f32_e32 v169, v169
	v_rcp_f32_e32 v180, v180
	v_rcp_f32_e32 v181, v181
	s_nop 0
	v_pk_mul_f32 v[168:169], v[168:169], v[178:179]
	v_pk_mul_f32 v[180:181], v[180:181], v[244:245]
	v_pk_mul_f32 v[78:79], v[78:79], v[168:169]
	v_pk_mul_f32 v[80:81], v[80:81], v[180:181]
	v_lshlrev_b32_e32 v168, 16, v188
	v_and_b32_e32 v169, 0xffff0000, v188
	v_lshlrev_b32_e32 v178, 16, v196
	v_and_b32_e32 v179, 0xffff0000, v196
	v_lshlrev_b32_e32 v180, 16, v189
	v_and_b32_e32 v181, 0xffff0000, v189
	v_lshlrev_b32_e32 v244, 16, v197
	v_and_b32_e32 v245, 0xffff0000, v197
	v_rcp_f32_e32 v168, v168
	v_rcp_f32_e32 v169, v169
	v_rcp_f32_e32 v180, v180
	v_rcp_f32_e32 v181, v181
	s_nop 0
	v_pk_mul_f32 v[168:169], v[168:169], v[178:179]
	v_pk_mul_f32 v[180:181], v[180:181], v[244:245]
	v_pk_mul_f32 v[70:71], v[70:71], v[168:169]
	v_pk_mul_f32 v[72:73], v[72:73], v[180:181]
	v_lshlrev_b32_e32 v146, 16, v190
	v_and_b32_e32 v147, 0xffff0000, v190
	v_lshlrev_b32_e32 v148, 16, v198
	v_and_b32_e32 v149, 0xffff0000, v198
	v_lshlrev_b32_e32 v150, 16, v191
	v_and_b32_e32 v151, 0xffff0000, v191
	v_lshlrev_b32_e32 v152, 16, v199
	v_and_b32_e32 v153, 0xffff0000, v199
	v_rcp_f32_e32 v146, v146
	v_rcp_f32_e32 v147, v147
	v_rcp_f32_e32 v150, v150
	v_rcp_f32_e32 v151, v151
	s_nop 0
	v_pk_mul_f32 v[146:147], v[146:147], v[148:149]
	v_pk_mul_f32 v[150:151], v[150:151], v[152:153]
	v_pk_mul_f32 v[66:67], v[66:67], v[146:147]
	v_pk_mul_f32 v[68:69], v[68:69], v[150:151]
	s_add_u32 s100, s98, 0x1f4000
	s_addc_u32 s101, s99, 0
	global_load_dwordx4 v[184:187], v243, s[100:101]
	s_add_u32 s100, s98, 0x20d000
	s_addc_u32 s101, s99, 0
	global_load_dwordx4 v[188:191], v243, s[100:101]
	s_add_u32 s100, s98, 0x1f4000
	s_addc_u32 s101, s99, 0
	global_load_dwordx4 v[192:195], v243, s[100:101] offset:2048
	s_add_u32 s100, s98, 0x20d000
	s_addc_u32 s101, s99, 0
	global_load_dwordx4 v[196:199], v243, s[100:101] offset:2048
	s_waitcnt vmcnt(8)
	v_lshlrev_b32_e32 v146, 16, v200
	v_and_b32_e32 v147, 0xffff0000, v200
	v_lshlrev_b32_e32 v148, 16, v208
	v_and_b32_e32 v149, 0xffff0000, v208
	v_lshlrev_b32_e32 v150, 16, v201
	v_and_b32_e32 v151, 0xffff0000, v201
	v_lshlrev_b32_e32 v152, 16, v209
	v_and_b32_e32 v153, 0xffff0000, v209
	v_rcp_f32_e32 v146, v146
	v_rcp_f32_e32 v147, v147
	v_rcp_f32_e32 v150, v150
	v_rcp_f32_e32 v151, v151
	s_nop 0
	v_pk_mul_f32 v[146:147], v[146:147], v[148:149]
	v_pk_mul_f32 v[150:151], v[150:151], v[152:153]
	v_pk_mul_f32 v[62:63], v[62:63], v[146:147]
	v_pk_mul_f32 v[64:65], v[64:65], v[150:151]
	v_lshlrev_b32_e32 v168, 16, v202
	v_and_b32_e32 v169, 0xffff0000, v202
	v_lshlrev_b32_e32 v178, 16, v210
	v_and_b32_e32 v179, 0xffff0000, v210
	v_lshlrev_b32_e32 v180, 16, v203
	v_and_b32_e32 v181, 0xffff0000, v203
	v_lshlrev_b32_e32 v244, 16, v211
	v_and_b32_e32 v245, 0xffff0000, v211
	v_rcp_f32_e32 v168, v168
	v_rcp_f32_e32 v169, v169
	v_rcp_f32_e32 v180, v180
	v_rcp_f32_e32 v181, v181
	s_nop 0
	v_pk_mul_f32 v[168:169], v[168:169], v[178:179]
	v_pk_mul_f32 v[180:181], v[180:181], v[244:245]
	v_pk_mul_f32 v[58:59], v[58:59], v[168:169]
	v_pk_mul_f32 v[60:61], v[60:61], v[180:181]
	v_lshlrev_b32_e32 v168, 16, v204
	v_and_b32_e32 v169, 0xffff0000, v204
	v_lshlrev_b32_e32 v178, 16, v212
	v_and_b32_e32 v179, 0xffff0000, v212
	v_lshlrev_b32_e32 v180, 16, v205
	v_and_b32_e32 v181, 0xffff0000, v205
	v_lshlrev_b32_e32 v244, 16, v213
	v_and_b32_e32 v245, 0xffff0000, v213
	v_rcp_f32_e32 v168, v168
	v_rcp_f32_e32 v169, v169
	v_rcp_f32_e32 v180, v180
	v_rcp_f32_e32 v181, v181
	s_nop 0
	v_pk_mul_f32 v[168:169], v[168:169], v[178:179]
	v_pk_mul_f32 v[180:181], v[180:181], v[244:245]
	v_pk_mul_f32 v[50:51], v[50:51], v[168:169]
	v_pk_mul_f32 v[52:53], v[52:53], v[180:181]
	v_lshlrev_b32_e32 v146, 16, v206
	v_and_b32_e32 v147, 0xffff0000, v206
	v_lshlrev_b32_e32 v148, 16, v214
	v_and_b32_e32 v149, 0xffff0000, v214
	v_lshlrev_b32_e32 v150, 16, v207
	v_and_b32_e32 v151, 0xffff0000, v207
	v_lshlrev_b32_e32 v152, 16, v215
	v_and_b32_e32 v153, 0xffff0000, v215
	v_rcp_f32_e32 v146, v146
	v_rcp_f32_e32 v147, v147
	v_rcp_f32_e32 v150, v150
	v_rcp_f32_e32 v151, v151
	s_nop 0
	v_pk_mul_f32 v[146:147], v[146:147], v[148:149]
	v_pk_mul_f32 v[150:151], v[150:151], v[152:153]
	v_pk_mul_f32 v[42:43], v[42:43], v[146:147]
	v_pk_mul_f32 v[44:45], v[44:45], v[150:151]
	s_add_u32 s100, s98, 0x226000
	s_addc_u32 s101, s99, 0
	global_load_dwordx4 v[200:203], v243, s[100:101]
	s_add_u32 s100, s98, 0x23f000
	s_addc_u32 s101, s99, 0
	global_load_dwordx4 v[204:207], v243, s[100:101]
	s_add_u32 s100, s98, 0x226000
	s_addc_u32 s101, s99, 0
	global_load_dwordx4 v[208:211], v243, s[100:101] offset:2048
	s_add_u32 s100, s98, 0x23f000
	s_addc_u32 s101, s99, 0
	global_load_dwordx4 v[212:215], v243, s[100:101] offset:2048
	s_waitcnt vmcnt(8)
; DI float bflo(unsigned w) { return __uint_as_float(w << 16); }
; DI float bfhi(unsigned w) { return __uint_as_float(w & 0xffff0000u); }
;     DI void operator()(Acc& acc, const Unit& u, int wr, int wc, int fr, int fq) const {
;     ...
;             for (int ai = 0; ai < 2; ++ai)
; #pragma unroll
;                 for (int m = 0; m < 4; ++m)
; #pragma unroll
;                     for (int bj = 0; bj < 2; ++bj) g[ai][m][bj] = *(const u32x4*)(base + (size_t)(ai * 128 + m * 16) * NPJ + u.k * 1024 + bj * 128);
; #pragma unroll
;             for (int ai = 0; ai < 2; ++ai)
; #pragma unroll
;                 for (int m = 0; m < 4; ++m)
; #pragma unroll
;                     for (int bj = 0; bj < 2; ++bj) { const u32x4 q = g[ai][m][bj]; f32x4& v0 = acc[ai][bj][m][0]; f32x4& v1 = acc[ai][bj][m][1];
;                         v0[0] *= bflo(q.x); v0[1] *= bfhi(q.x); v0[2] *= bflo(q.y); v0[3] *= bfhi(q.y); v1[0] *= bflo(q.z); v1[1] *= bfhi(q.z); v1[2] *= bflo(q.w); v1[3] *= bfhi(q.w); }
	v_lshlrev_b32_e32 v146, 16, v216
	v_and_b32_e32 v147, 0xffff0000, v216
	v_lshlrev_b32_e32 v148, 16, v224
	v_and_b32_e32 v149, 0xffff0000, v224
	v_lshlrev_b32_e32 v150, 16, v217
	v_and_b32_e32 v151, 0xffff0000, v217
	v_lshlrev_b32_e32 v152, 16, v225
	v_and_b32_e32 v153, 0xffff0000, v225
	v_rcp_f32_e32 v146, v146
	v_rcp_f32_e32 v147, v147
	v_rcp_f32_e32 v150, v150
	v_rcp_f32_e32 v151, v151
	s_nop 0
	v_pk_mul_f32 v[146:147], v[146:147], v[148:149]
	v_pk_mul_f32 v[150:151], v[150:151], v[152:153]
	v_pk_mul_f32 v[54:55], v[54:55], v[146:147]
	v_pk_mul_f32 v[56:57], v[56:57], v[150:151]
	v_lshlrev_b32_e32 v168, 16, v218
	v_and_b32_e32 v169, 0xffff0000, v218
	v_lshlrev_b32_e32 v178, 16, v226
	v_and_b32_e32 v179, 0xffff0000, v226
	v_lshlrev_b32_e32 v180, 16, v219
	v_and_b32_e32 v181, 0xffff0000, v219
	v_lshlrev_b32_e32 v244, 16, v227
	v_and_b32_e32 v245, 0xffff0000, v227
	v_rcp_f32_e32 v168, v168
	v_rcp_f32_e32 v169, v169
	v_rcp_f32_e32 v180, v180
	v_rcp_f32_e32 v181, v181
	s_nop 0
	v_pk_mul_f32 v[168:169], v[168:169], v[178:179]
	v_pk_mul_f32 v[180:181], v[180:181], v[244:245]
	v_pk_mul_f32 v[46:47], v[46:47], v[168:169]
	v_pk_mul_f32 v[48:49], v[48:49], v[180:181]
	v_lshlrev_b32_e32 v168, 16, v220
	v_and_b32_e32 v169, 0xffff0000, v220
	v_lshlrev_b32_e32 v178, 16, v228
	v_and_b32_e32 v179, 0xffff0000, v228
	v_lshlrev_b32_e32 v180, 16, v221
	v_and_b32_e32 v181, 0xffff0000, v221
	v_lshlrev_b32_e32 v244, 16, v229
	v_and_b32_e32 v245, 0xffff0000, v229
	v_rcp_f32_e32 v168, v168
	v_rcp_f32_e32 v169, v169
	v_rcp_f32_e32 v180, v180
	v_rcp_f32_e32 v181, v181
	s_nop 0
	v_pk_mul_f32 v[168:169], v[168:169], v[178:179]
	v_pk_mul_f32 v[180:181], v[180:181], v[244:245]
	v_pk_mul_f32 v[34:35], v[34:35], v[168:169]
	v_pk_mul_f32 v[36:37], v[36:37], v[180:181]
	v_lshlrev_b32_e32 v146, 16, v222
	v_and_b32_e32 v147, 0xffff0000, v222
	v_lshlrev_b32_e32 v148, 16, v230
	v_and_b32_e32 v149, 0xffff0000, v230
	v_lshlrev_b32_e32 v150, 16, v223
	v_and_b32_e32 v151, 0xffff0000, v223
	v_lshlrev_b32_e32 v152, 16, v231
	v_and_b32_e32 v153, 0xffff0000, v231
	v_rcp_f32_e32 v146, v146
	v_rcp_f32_e32 v147, v147
	v_rcp_f32_e32 v150, v150
	v_rcp_f32_e32 v151, v151
	s_nop 0
	v_pk_mul_f32 v[146:147], v[146:147], v[148:149]
	v_pk_mul_f32 v[150:151], v[150:151], v[152:153]
	v_pk_mul_f32 v[26:27], v[26:27], v[146:147]
	v_pk_mul_f32 v[28:29], v[28:29], v[150:151]
	s_waitcnt vmcnt(4)
	v_lshlrev_b32_e32 v146, 16, v184
	v_and_b32_e32 v147, 0xffff0000, v184
	v_lshlrev_b32_e32 v148, 16, v192
	v_and_b32_e32 v149, 0xffff0000, v192
	v_lshlrev_b32_e32 v150, 16, v185
	v_and_b32_e32 v151, 0xffff0000, v185
	v_lshlrev_b32_e32 v152, 16, v193
	v_and_b32_e32 v153, 0xffff0000, v193
	v_rcp_f32_e32 v146, v146
	v_rcp_f32_e32 v147, v147
	v_rcp_f32_e32 v150, v150
	v_rcp_f32_e32 v151, v151
	s_nop 0
	v_pk_mul_f32 v[146:147], v[146:147], v[148:149]
	v_pk_mul_f32 v[150:151], v[150:151], v[152:153]
	v_pk_mul_f32 v[38:39], v[38:39], v[146:147]
	v_pk_mul_f32 v[40:41], v[40:41], v[150:151]
	v_lshlrev_b32_e32 v168, 16, v186
	v_and_b32_e32 v169, 0xffff0000, v186
	v_lshlrev_b32_e32 v178, 16, v194
	v_and_b32_e32 v179, 0xffff0000, v194
	v_lshlrev_b32_e32 v180, 16, v187
	v_and_b32_e32 v181, 0xffff0000, v187
	v_lshlrev_b32_e32 v244, 16, v195
	v_and_b32_e32 v245, 0xffff0000, v195
	v_rcp_f32_e32 v168, v168
	v_rcp_f32_e32 v169, v169
	v_rcp_f32_e32 v180, v180
	v_rcp_f32_e32 v181, v181
	s_nop 0
	v_pk_mul_f32 v[168:169], v[168:169], v[178:179]
	v_pk_mul_f32 v[180:181], v[180:181], v[244:245]
	v_pk_mul_f32 v[30:31], v[30:31], v[168:169]
	v_pk_mul_f32 v[32:33], v[32:33], v[180:181]
	v_lshlrev_b32_e32 v168, 16, v188
	v_and_b32_e32 v169, 0xffff0000, v188
	v_lshlrev_b32_e32 v178, 16, v196
	v_and_b32_e32 v179, 0xffff0000, v196
	v_lshlrev_b32_e32 v180, 16, v189
	v_and_b32_e32 v181, 0xffff0000, v189
	v_lshlrev_b32_e32 v244, 16, v197
	v_and_b32_e32 v245, 0xffff0000, v197
	v_rcp_f32_e32 v168, v168
	v_rcp_f32_e32 v169, v169
	v_rcp_f32_e32 v180, v180
	v_rcp_f32_e32 v181, v181
	s_nop 0
	v_pk_mul_f32 v[168:169], v[168:169], v[178:179]
	v_pk_mul_f32 v[180:181], v[180:181], v[244:245]
	v_pk_mul_f32 v[18:19], v[18:19], v[168:169]
	v_pk_mul_f32 v[20:21], v[20:21], v[180:181]
	v_lshlrev_b32_e32 v146, 16, v190
	v_and_b32_e32 v147, 0xffff0000, v190
	v_lshlrev_b32_e32 v148, 16, v198
	v_and_b32_e32 v149, 0xffff0000, v198
	v_lshlrev_b32_e32 v150, 16, v191
	v_and_b32_e32 v151, 0xffff0000, v191
	v_lshlrev_b32_e32 v152, 16, v199
	v_and_b32_e32 v153, 0xffff0000, v199
	v_rcp_f32_e32 v146, v146
	v_rcp_f32_e32 v147, v147
	v_rcp_f32_e32 v150, v150
	v_rcp_f32_e32 v151, v151
	s_nop 0
	v_pk_mul_f32 v[146:147], v[146:147], v[148:149]
	v_pk_mul_f32 v[150:151], v[150:151], v[152:153]
	v_pk_mul_f32 v[10:11], v[10:11], v[146:147]
	v_pk_mul_f32 v[12:13], v[12:13], v[150:151]
	s_waitcnt vmcnt(0)
; DI float bflo(unsigned w) { return __uint_as_float(w << 16); }
; DI float bfhi(unsigned w) { return __uint_as_float(w & 0xffff0000u); }
; DI u32x4 pack8(f32x4 a, f32x4 b) { u32x4 w; w.x = pk2(a[0], a[1]); w.y = pk2(a[2], a[3]); w.z = pk2(b[0], b[1]); w.w = pk2(b[2], b[3]); return w; }
;     DI void operator()(Acc& acc, const Unit& u, int wr, int wc, int fr, int fq) const {
;     ...
;             for (int ai = 0; ai < 2; ++ai)
; #pragma unroll
;                 for (int m = 0; m < 4; ++m)
; #pragma unroll
;                     for (int bj = 0; bj < 2; ++bj) g[ai][m][bj] = *(const u32x4*)(base + (size_t)(ai * 128 + m * 16) * NPJ + u.k * 1024 + bj * 128);
; #pragma unroll
;             for (int ai = 0; ai < 2; ++ai)
; #pragma unroll
;                 for (int m = 0; m < 4; ++m)
; #pragma unroll
;                     for (int bj = 0; bj < 2; ++bj) { const u32x4 q = g[ai][m][bj]; f32x4& v0 = acc[ai][bj][m][0]; f32x4& v1 = acc[ai][bj][m][1];
;                         v0[0] *= bflo(q.x); v0[1] *= bfhi(q.x); v0[2] *= bflo(q.y); v0[3] *= bfhi(q.y); v1[0] *= bflo(q.z); v1[1] *= bfhi(q.z); v1[2] *= bflo(q.w); v1[3] *= bfhi(q.w); }
;         }
;         if (u.k > 0) {
;             u32x4 g[2][4][2];
; #pragma unroll
;             for (int ai = 0; ai < 2; ++ai)
; #pragma unroll
;                 for (int m = 0; m < 4; ++m)
; #pragma unroll
;                     for (int bj = 0; bj < 2; ++bj) g[ai][m][bj] = *(const u32x4*)(base + (size_t)(ai * 128 + m * 16) * NPJ + bj * 128);
; #pragma unroll
;             for (int ai = 0; ai < 2; ++ai)
; #pragma unroll
;                 for (int m = 0; m < 4; ++m)
; #pragma unroll
;                     for (int bj = 0; bj < 2; ++bj) { const u32x4 q = g[ai][m][bj]; f32x4& v0 = acc[ai][bj][m][0]; f32x4& v1 = acc[ai][bj][m][1];
;                         v0[0] += bflo(q.x); v0[1] += bfhi(q.x); v0[2] += bflo(q.y); v0[3] += bfhi(q.y); v1[0] += bflo(q.z); v1[1] += bfhi(q.z); v1[2] += bflo(q.w); v1[3] += bfhi(q.w); }
;         }
;         if (!dry) {
; #pragma unroll
;             for (int ai = 0; ai < 2; ++ai)
; #pragma unroll
;                 for (int m = 0; m < 4; ++m)
; #pragma unroll
;                     for (int bj = 0; bj < 2; ++bj) *(u32x4*)(base + (size_t)(ai * 128 + m * 16) * NPJ + bj * 128) = pack8(acc[ai][bj][m][0], acc[ai][bj][m][1]);
	v_lshlrev_b32_e32 v146, 16, v200
	v_and_b32_e32 v147, 0xffff0000, v200
	v_lshlrev_b32_e32 v148, 16, v208
	v_and_b32_e32 v149, 0xffff0000, v208
	v_lshlrev_b32_e32 v150, 16, v201
	v_and_b32_e32 v151, 0xffff0000, v201
	v_lshlrev_b32_e32 v152, 16, v209
	v_and_b32_e32 v153, 0xffff0000, v209
	v_rcp_f32_e32 v146, v146
	v_rcp_f32_e32 v147, v147
	v_rcp_f32_e32 v150, v150
	v_rcp_f32_e32 v151, v151
	s_nop 0
	v_pk_mul_f32 v[146:147], v[146:147], v[148:149]
	v_pk_mul_f32 v[150:151], v[150:151], v[152:153]
	v_pk_mul_f32 v[22:23], v[22:23], v[146:147]
	v_pk_mul_f32 v[24:25], v[24:25], v[150:151]
	v_lshlrev_b32_e32 v168, 16, v202
	v_and_b32_e32 v169, 0xffff0000, v202
	v_lshlrev_b32_e32 v178, 16, v210
	v_and_b32_e32 v179, 0xffff0000, v210
	v_lshlrev_b32_e32 v180, 16, v203
	v_and_b32_e32 v181, 0xffff0000, v203
	v_lshlrev_b32_e32 v244, 16, v211
	v_and_b32_e32 v245, 0xffff0000, v211
	v_rcp_f32_e32 v168, v168
	v_rcp_f32_e32 v169, v169
	v_rcp_f32_e32 v180, v180
	v_rcp_f32_e32 v181, v181
	s_nop 0
	v_pk_mul_f32 v[168:169], v[168:169], v[178:179]
	v_pk_mul_f32 v[180:181], v[180:181], v[244:245]
	v_pk_mul_f32 v[14:15], v[14:15], v[168:169]
	v_pk_mul_f32 v[16:17], v[16:17], v[180:181]
	v_lshlrev_b32_e32 v168, 16, v204
	v_and_b32_e32 v169, 0xffff0000, v204
	v_lshlrev_b32_e32 v178, 16, v212
	v_and_b32_e32 v179, 0xffff0000, v212
	v_lshlrev_b32_e32 v180, 16, v205
	v_and_b32_e32 v181, 0xffff0000, v205
	v_lshlrev_b32_e32 v244, 16, v213
	v_and_b32_e32 v245, 0xffff0000, v213
	v_rcp_f32_e32 v168, v168
	v_rcp_f32_e32 v169, v169
	v_rcp_f32_e32 v180, v180
	v_rcp_f32_e32 v181, v181
	s_nop 0
	v_pk_mul_f32 v[168:169], v[168:169], v[178:179]
	v_pk_mul_f32 v[180:181], v[180:181], v[244:245]
	v_pk_mul_f32 v[6:7], v[6:7], v[168:169]
	v_pk_mul_f32 v[8:9], v[8:9], v[180:181]
	v_lshlrev_b32_e32 v146, 16, v206
	v_and_b32_e32 v147, 0xffff0000, v206
	v_lshlrev_b32_e32 v148, 16, v214
	v_and_b32_e32 v149, 0xffff0000, v214
	v_lshlrev_b32_e32 v150, 16, v207
	v_and_b32_e32 v151, 0xffff0000, v207
	v_lshlrev_b32_e32 v152, 16, v215
	v_and_b32_e32 v153, 0xffff0000, v215
	v_rcp_f32_e32 v146, v146
	v_rcp_f32_e32 v147, v147
	v_rcp_f32_e32 v150, v150
	v_rcp_f32_e32 v151, v151
	s_nop 0
	v_pk_mul_f32 v[146:147], v[146:147], v[148:149]
	v_pk_mul_f32 v[150:151], v[150:151], v[152:153]
	v_pk_mul_f32 v[2:3], v[2:3], v[146:147]
	v_pk_mul_f32 v[4:5], v[4:5], v[150:151]
	s_branch .Lup3_tail
.Lup3_final:
	s_mov_b32 s101, 0
	s_mov_b32 s100, 0x32000
	v_lshl_add_u64 v[132:133], v[166:167], 0, s[100:101]
	s_mov_b32 s100, 0x64000
	v_lshl_add_u64 v[134:135], v[166:167], 0, s[100:101]
	s_mov_b32 s100, 0x96000
	v_lshl_add_u64 v[136:137], v[166:167], 0, s[100:101]
	s_mov_b32 s100, 0x190000
	v_lshl_add_u64 v[138:139], v[166:167], 0, s[100:101]
	s_mov_b32 s100, 0x1c2000
	v_lshl_add_u64 v[140:141], v[166:167], 0, s[100:101]
	s_mov_b32 s100, 0x1f4000
	v_lshl_add_u64 v[142:143], v[166:167], 0, s[100:101]
	s_mov_b32 s100, 0x226000
	v_lshl_add_u64 v[144:145], v[166:167], 0, s[100:101]
	s_add_u32 s100, s98, 0x0
	s_addc_u32 s101, s99, 0
	global_load_dwordx4 v[184:187], v243, s[100:101]
	s_add_u32 s100, s98, 0x19000
	s_addc_u32 s101, s99, 0
	global_load_dwordx4 v[188:191], v243, s[100:101]
	s_add_u32 s100, s98, 0x32000
	s_addc_u32 s101, s99, 0
	global_load_dwordx4 v[192:195], v243, s[100:101]
	s_add_u32 s100, s98, 0x4b000
	s_addc_u32 s101, s99, 0
	global_load_dwordx4 v[196:199], v243, s[100:101]
	s_add_u32 s100, s98, 0x64000
	s_addc_u32 s101, s99, 0
	global_load_dwordx4 v[200:203], v243, s[100:101]
	s_add_u32 s100, s98, 0x7d000
	s_addc_u32 s101, s99, 0
	global_load_dwordx4 v[204:207], v243, s[100:101]
	s_add_u32 s100, s98, 0x96000
	s_addc_u32 s101, s99, 0
	global_load_dwordx4 v[208:211], v243, s[100:101]
	s_add_u32 s100, s98, 0xaf000
	s_addc_u32 s101, s99, 0
	global_load_dwordx4 v[212:215], v243, s[100:101]
	s_add_u32 s100, s98, 0x190000
	s_addc_u32 s101, s99, 0
	global_load_dwordx4 v[216:219], v243, s[100:101]
	s_add_u32 s100, s98, 0x1a9000
	s_addc_u32 s101, s99, 0
	global_load_dwordx4 v[220:223], v243, s[100:101]
	s_add_u32 s100, s98, 0x1c2000
	s_addc_u32 s101, s99, 0
	global_load_dwordx4 v[224:227], v243, s[100:101]
	s_add_u32 s100, s98, 0x1db000
	s_addc_u32 s101, s99, 0
	global_load_dwordx4 v[228:231], v243, s[100:101]
	s_waitcnt vmcnt(10)
	v_lshlrev_b32_e32 v146, 16, v184
	v_and_b32_e32 v147, 0xffff0000, v184
	v_lshlrev_b32_e32 v148, 16, v185
	v_and_b32_e32 v149, 0xffff0000, v185
	v_lshlrev_b32_e32 v150, 16, v186
	v_and_b32_e32 v151, 0xffff0000, v186
	v_lshlrev_b32_e32 v152, 16, v187
	v_and_b32_e32 v153, 0xffff0000, v187
	v_rcp_f32_e32 v146, v146
	v_rcp_f32_e32 v147, v147
	v_rcp_f32_e32 v148, v148
	v_rcp_f32_e32 v149, v149
	v_rcp_f32_e32 v150, v150
	v_rcp_f32_e32 v151, v151
	v_rcp_f32_e32 v152, v152
	v_rcp_f32_e32 v153, v153
	s_nop 0
	v_pk_mul_f32 v[126:127], v[126:127], v[146:147]
	v_pk_mul_f32 v[128:129], v[128:129], v[148:149]
	v_pk_mul_f32 v[122:123], v[122:123], v[150:151]
	v_pk_mul_f32 v[124:125], v[124:125], v[152:153]
	v_cvt_pk_bf16_f32 v184, v126, v127
	v_cvt_pk_bf16_f32 v185, v128, v129
	v_cvt_pk_bf16_f32 v186, v122, v123
	v_cvt_pk_bf16_f32 v187, v124, v125
	v_lshlrev_b32_e32 v168, 16, v188
	v_and_b32_e32 v169, 0xffff0000, v188
	v_lshlrev_b32_e32 v178, 16, v189
	v_and_b32_e32 v179, 0xffff0000, v189
	v_lshlrev_b32_e32 v180, 16, v190
	v_and_b32_e32 v181, 0xffff0000, v190
	v_lshlrev_b32_e32 v244, 16, v191
	v_and_b32_e32 v245, 0xffff0000, v191
	v_rcp_f32_e32 v168, v168
	v_rcp_f32_e32 v169, v169
	v_rcp_f32_e32 v178, v178
	v_rcp_f32_e32 v179, v179
	v_rcp_f32_e32 v180, v180
	v_rcp_f32_e32 v181, v181
	v_rcp_f32_e32 v244, v244
	v_rcp_f32_e32 v245, v245
	s_nop 0
	v_pk_mul_f32 v[114:115], v[114:115], v[168:169]
	v_pk_mul_f32 v[116:117], v[116:117], v[178:179]
	v_pk_mul_f32 v[110:111], v[110:111], v[180:181]
	v_pk_mul_f32 v[112:113], v[112:113], v[244:245]
	v_cvt_pk_bf16_f32 v188, v114, v115
	v_cvt_pk_bf16_f32 v189, v116, v117
	v_cvt_pk_bf16_f32 v190, v110, v111
	v_cvt_pk_bf16_f32 v191, v112, v113
	global_store_dwordx4 v[166:167], v[184:187], off
	global_store_dwordx4 v[166:167], v[188:191], off offset:256
	s_nop 1
	s_add_u32 s100, s98, 0x1f4000
	s_addc_u32 s101, s99, 0
	global_load_dwordx4 v[184:187], v243, s[100:101]
	s_add_u32 s100, s98, 0x20d000
	s_addc_u32 s101, s99, 0
	global_load_dwordx4 v[188:191], v243, s[100:101]
	s_waitcnt vmcnt(12)
; DI float bflo(unsigned w) { return __uint_as_float(w << 16); }
; DI float bfhi(unsigned w) { return __uint_as_float(w & 0xffff0000u); }
; DI u32x4 pack8(f32x4 a, f32x4 b) { u32x4 w; w.x = pk2(a[0], a[1]); w.y = pk2(a[2], a[3]); w.z = pk2(b[0], b[1]); w.w = pk2(b[2], b[3]); return w; }
;     DI void operator()(Acc& acc, const Unit& u, int wr, int wc, int fr, int fq) const {
;     ...
;             for (int ai = 0; ai < 2; ++ai)
; #pragma unroll
;                 for (int m = 0; m < 4; ++m)
; #pragma unroll
;                     for (int bj = 0; bj < 2; ++bj) g[ai][m][bj] = *(const u32x4*)(base + (size_t)(ai * 128 + m * 16) * NPJ + u.k * 1024 + bj * 128);
; #pragma unroll
;             for (int ai = 0; ai < 2; ++ai)
; #pragma unroll
;                 for (int m = 0; m < 4; ++m)
; #pragma unroll
;                     for (int bj = 0; bj < 2; ++bj) { const u32x4 q = g[ai][m][bj]; f32x4& v0 = acc[ai][bj][m][0]; f32x4& v1 = acc[ai][bj][m][1];
;                         v0[0] *= bflo(q.x); v0[1] *= bfhi(q.x); v0[2] *= bflo(q.y); v0[3] *= bfhi(q.y); v1[0] *= bflo(q.z); v1[1] *= bfhi(q.z); v1[2] *= bflo(q.w); v1[3] *= bfhi(q.w); }
;         }
;         if (u.k > 0) {
;             u32x4 g[2][4][2];
; #pragma unroll
;             for (int ai = 0; ai < 2; ++ai)
; #pragma unroll
;                 for (int m = 0; m < 4; ++m)
; #pragma unroll
;                     for (int bj = 0; bj < 2; ++bj) g[ai][m][bj] = *(const u32x4*)(base + (size_t)(ai * 128 + m * 16) * NPJ + bj * 128);
; #pragma unroll
;             for (int ai = 0; ai < 2; ++ai)
; #pragma unroll
;                 for (int m = 0; m < 4; ++m)
; #pragma unroll
;                     for (int bj = 0; bj < 2; ++bj) { const u32x4 q = g[ai][m][bj]; f32x4& v0 = acc[ai][bj][m][0]; f32x4& v1 = acc[ai][bj][m][1];
;                         v0[0] += bflo(q.x); v0[1] += bfhi(q.x); v0[2] += bflo(q.y); v0[3] += bfhi(q.y); v1[0] += bflo(q.z); v1[1] += bfhi(q.z); v1[2] += bflo(q.w); v1[3] += bfhi(q.w); }
;         }
;         if (!dry) {
; #pragma unroll
;             for (int ai = 0; ai < 2; ++ai)
; #pragma unroll
;                 for (int m = 0; m < 4; ++m)
; #pragma unroll
;                     for (int bj = 0; bj < 2; ++bj) *(u32x4*)(base + (size_t)(ai * 128 + m * 16) * NPJ + bj * 128) = pack8(acc[ai][bj][m][0], acc[ai][bj][m][1]);
	v_lshlrev_b32_e32 v146, 16, v192
	v_and_b32_e32 v147, 0xffff0000, v192
	v_lshlrev_b32_e32 v148, 16, v193
	v_and_b32_e32 v149, 0xffff0000, v193
	v_lshlrev_b32_e32 v150, 16, v194
	v_and_b32_e32 v151, 0xffff0000, v194
	v_lshlrev_b32_e32 v152, 16, v195
	v_and_b32_e32 v153, 0xffff0000, v195
	v_rcp_f32_e32 v146, v146
	v_rcp_f32_e32 v147, v147
	v_rcp_f32_e32 v148, v148
	v_rcp_f32_e32 v149, v149
	v_rcp_f32_e32 v150, v150
	v_rcp_f32_e32 v151, v151
	v_rcp_f32_e32 v152, v152
	v_rcp_f32_e32 v153, v153
	s_nop 0
	v_pk_mul_f32 v[118:119], v[118:119], v[146:147]
	v_pk_mul_f32 v[120:121], v[120:121], v[148:149]
	v_pk_mul_f32 v[106:107], v[106:107], v[150:151]
	v_pk_mul_f32 v[108:109], v[108:109], v[152:153]
	v_cvt_pk_bf16_f32 v192, v118, v119
	v_cvt_pk_bf16_f32 v193, v120, v121
	v_cvt_pk_bf16_f32 v194, v106, v107
	v_cvt_pk_bf16_f32 v195, v108, v109
	v_lshlrev_b32_e32 v168, 16, v196
	v_and_b32_e32 v169, 0xffff0000, v196
	v_lshlrev_b32_e32 v178, 16, v197
	v_and_b32_e32 v179, 0xffff0000, v197
	v_lshlrev_b32_e32 v180, 16, v198
	v_and_b32_e32 v181, 0xffff0000, v198
	v_lshlrev_b32_e32 v244, 16, v199
	v_and_b32_e32 v245, 0xffff0000, v199
	v_rcp_f32_e32 v168, v168
	v_rcp_f32_e32 v169, v169
	v_rcp_f32_e32 v178, v178
	v_rcp_f32_e32 v179, v179
	v_rcp_f32_e32 v180, v180
	v_rcp_f32_e32 v181, v181
	v_rcp_f32_e32 v244, v244
	v_rcp_f32_e32 v245, v245
	s_nop 0
	v_pk_mul_f32 v[98:99], v[98:99], v[168:169]
	v_pk_mul_f32 v[100:101], v[100:101], v[178:179]
	v_pk_mul_f32 v[90:91], v[90:91], v[180:181]
	v_pk_mul_f32 v[92:93], v[92:93], v[244:245]
	v_cvt_pk_bf16_f32 v196, v98, v99
	v_cvt_pk_bf16_f32 v197, v100, v101
	v_cvt_pk_bf16_f32 v198, v90, v91
	v_cvt_pk_bf16_f32 v199, v92, v93
	global_store_dwordx4 v[132:133], v[192:195], off
	global_store_dwordx4 v[132:133], v[196:199], off offset:256
	s_nop 1
	s_add_u32 s100, s98, 0x226000
	s_addc_u32 s101, s99, 0
	global_load_dwordx4 v[192:195], v243, s[100:101]
	s_add_u32 s100, s98, 0x23f000
	s_addc_u32 s101, s99, 0
	global_load_dwordx4 v[196:199], v243, s[100:101]
	s_waitcnt vmcnt(14)
	v_lshlrev_b32_e32 v146, 16, v200
	v_and_b32_e32 v147, 0xffff0000, v200
	v_lshlrev_b32_e32 v148, 16, v201
	v_and_b32_e32 v149, 0xffff0000, v201
	v_lshlrev_b32_e32 v150, 16, v202
	v_and_b32_e32 v151, 0xffff0000, v202
	v_lshlrev_b32_e32 v152, 16, v203
	v_and_b32_e32 v153, 0xffff0000, v203
	v_rcp_f32_e32 v146, v146
	v_rcp_f32_e32 v147, v147
	v_rcp_f32_e32 v148, v148
	v_rcp_f32_e32 v149, v149
	v_rcp_f32_e32 v150, v150
	v_rcp_f32_e32 v151, v151
	v_rcp_f32_e32 v152, v152
	v_rcp_f32_e32 v153, v153
	s_nop 0
	v_pk_mul_f32 v[102:103], v[102:103], v[146:147]
	v_pk_mul_f32 v[104:105], v[104:105], v[148:149]
	v_pk_mul_f32 v[94:95], v[94:95], v[150:151]
	v_pk_mul_f32 v[96:97], v[96:97], v[152:153]
	v_cvt_pk_bf16_f32 v200, v102, v103
	v_cvt_pk_bf16_f32 v201, v104, v105
	v_cvt_pk_bf16_f32 v202, v94, v95
	v_cvt_pk_bf16_f32 v203, v96, v97
	v_lshlrev_b32_e32 v168, 16, v204
	v_and_b32_e32 v169, 0xffff0000, v204
	v_lshlrev_b32_e32 v178, 16, v205
	v_and_b32_e32 v179, 0xffff0000, v205
	v_lshlrev_b32_e32 v180, 16, v206
	v_and_b32_e32 v181, 0xffff0000, v206
	v_lshlrev_b32_e32 v244, 16, v207
	v_and_b32_e32 v245, 0xffff0000, v207
	v_rcp_f32_e32 v168, v168
	v_rcp_f32_e32 v169, v169
	v_rcp_f32_e32 v178, v178
	v_rcp_f32_e32 v179, v179
	v_rcp_f32_e32 v180, v180
	v_rcp_f32_e32 v181, v181
	v_rcp_f32_e32 v244, v244
	v_rcp_f32_e32 v245, v245
	s_nop 0
	v_pk_mul_f32 v[82:83], v[82:83], v[168:169]
	v_pk_mul_f32 v[84:85], v[84:85], v[178:179]
	v_pk_mul_f32 v[74:75], v[74:75], v[180:181]
	v_pk_mul_f32 v[76:77], v[76:77], v[244:245]
	v_cvt_pk_bf16_f32 v204, v82, v83
	v_cvt_pk_bf16_f32 v205, v84, v85
	v_cvt_pk_bf16_f32 v206, v74, v75
	v_cvt_pk_bf16_f32 v207, v76, v77
	global_store_dwordx4 v[134:135], v[200:203], off
	global_store_dwordx4 v[134:135], v[204:207], off offset:256
	s_waitcnt vmcnt(14)
	v_lshlrev_b32_e32 v146, 16, v208
	v_and_b32_e32 v147, 0xffff0000, v208
	v_lshlrev_b32_e32 v148, 16, v209
	v_and_b32_e32 v149, 0xffff0000, v209
	v_lshlrev_b32_e32 v150, 16, v210
	v_and_b32_e32 v151, 0xffff0000, v210
	v_lshlrev_b32_e32 v152, 16, v211
	v_and_b32_e32 v153, 0xffff0000, v211
	v_rcp_f32_e32 v146, v146
	v_rcp_f32_e32 v147, v147
	v_rcp_f32_e32 v148, v148
	v_rcp_f32_e32 v149, v149
	v_rcp_f32_e32 v150, v150
	v_rcp_f32_e32 v151, v151
	v_rcp_f32_e32 v152, v152
	v_rcp_f32_e32 v153, v153
	s_nop 0
	v_pk_mul_f32 v[86:87], v[86:87], v[146:147]
	v_pk_mul_f32 v[88:89], v[88:89], v[148:149]
	v_pk_mul_f32 v[78:79], v[78:79], v[150:151]
	v_pk_mul_f32 v[80:81], v[80:81], v[152:153]
	v_cvt_pk_bf16_f32 v208, v86, v87
	v_cvt_pk_bf16_f32 v209, v88, v89
	v_cvt_pk_bf16_f32 v210, v78, v79
	v_cvt_pk_bf16_f32 v211, v80, v81
	v_lshlrev_b32_e32 v168, 16, v212
	v_and_b32_e32 v169, 0xffff0000, v212
	v_lshlrev_b32_e32 v178, 16, v213
	v_and_b32_e32 v179, 0xffff0000, v213
	v_lshlrev_b32_e32 v180, 16, v214
	v_and_b32_e32 v181, 0xffff0000, v214
	v_lshlrev_b32_e32 v244, 16, v215
	v_and_b32_e32 v245, 0xffff0000, v215
	v_rcp_f32_e32 v168, v168
	v_rcp_f32_e32 v169, v169
	v_rcp_f32_e32 v178, v178
	v_rcp_f32_e32 v179, v179
	v_rcp_f32_e32 v180, v180
	v_rcp_f32_e32 v181, v181
	v_rcp_f32_e32 v244, v244
	v_rcp_f32_e32 v245, v245
	s_nop 0
	v_pk_mul_f32 v[70:71], v[70:71], v[168:169]
	v_pk_mul_f32 v[72:73], v[72:73], v[178:179]
	v_pk_mul_f32 v[66:67], v[66:67], v[180:181]
	v_pk_mul_f32 v[68:69], v[68:69], v[244:245]
	v_cvt_pk_bf16_f32 v212, v70, v71
	v_cvt_pk_bf16_f32 v213, v72, v73
	v_cvt_pk_bf16_f32 v214, v66, v67
	v_cvt_pk_bf16_f32 v215, v68, v69
	global_store_dwordx4 v[136:137], v[208:211], off
	global_store_dwordx4 v[136:137], v[212:215], off offset:256
	s_waitcnt vmcnt(14)
; DI float bflo(unsigned w) { return __uint_as_float(w << 16); }
; DI float bfhi(unsigned w) { return __uint_as_float(w & 0xffff0000u); }
; DI u32x4 pack8(f32x4 a, f32x4 b) { u32x4 w; w.x = pk2(a[0], a[1]); w.y = pk2(a[2], a[3]); w.z = pk2(b[0], b[1]); w.w = pk2(b[2], b[3]); return w; }
;     DI void operator()(Acc& acc, const Unit& u, int wr, int wc, int fr, int fq) const {
;     ...
;             for (int ai = 0; ai < 2; ++ai)
; #pragma unroll
;                 for (int m = 0; m < 4; ++m)
; #pragma unroll
;                     for (int bj = 0; bj < 2; ++bj) g[ai][m][bj] = *(const u32x4*)(base + (size_t)(ai * 128 + m * 16) * NPJ + u.k * 1024 + bj * 128);
; #pragma unroll
;             for (int ai = 0; ai < 2; ++ai)
; #pragma unroll
;                 for (int m = 0; m < 4; ++m)
; #pragma unroll
;                     for (int bj = 0; bj < 2; ++bj) { const u32x4 q = g[ai][m][bj]; f32x4& v0 = acc[ai][bj][m][0]; f32x4& v1 = acc[ai][bj][m][1];
;                         v0[0] *= bflo(q.x); v0[1] *= bfhi(q.x); v0[2] *= bflo(q.y); v0[3] *= bfhi(q.y); v1[0] *= bflo(q.z); v1[1] *= bfhi(q.z); v1[2] *= bflo(q.w); v1[3] *= bfhi(q.w); }
;         }
;         if (u.k > 0) {
;             u32x4 g[2][4][2];
; #pragma unroll
;             for (int ai = 0; ai < 2; ++ai)
; #pragma unroll
;                 for (int m = 0; m < 4; ++m)
; #pragma unroll
;                     for (int bj = 0; bj < 2; ++bj) g[ai][m][bj] = *(const u32x4*)(base + (size_t)(ai * 128 + m * 16) * NPJ + bj * 128);
; #pragma unroll
;             for (int ai = 0; ai < 2; ++ai)
; #pragma unroll
;                 for (int m = 0; m < 4; ++m)
; #pragma unroll
;                     for (int bj = 0; bj < 2; ++bj) { const u32x4 q = g[ai][m][bj]; f32x4& v0 = acc[ai][bj][m][0]; f32x4& v1 = acc[ai][bj][m][1];
;                         v0[0] += bflo(q.x); v0[1] += bfhi(q.x); v0[2] += bflo(q.y); v0[3] += bfhi(q.y); v1[0] += bflo(q.z); v1[1] += bfhi(q.z); v1[2] += bflo(q.w); v1[3] += bfhi(q.w); }
;         }
;         if (!dry) {
; #pragma unroll
;             for (int ai = 0; ai < 2; ++ai)
; #pragma unroll
;                 for (int m = 0; m < 4; ++m)
; #pragma unroll
;                     for (int bj = 0; bj < 2; ++bj) *(u32x4*)(base + (size_t)(ai * 128 + m * 16) * NPJ + bj * 128) = pack8(acc[ai][bj][m][0], acc[ai][bj][m][1]);
	v_lshlrev_b32_e32 v146, 16, v216
	v_and_b32_e32 v147, 0xffff0000, v216
	v_lshlrev_b32_e32 v148, 16, v217
	v_and_b32_e32 v149, 0xffff0000, v217
	v_lshlrev_b32_e32 v150, 16, v218
	v_and_b32_e32 v151, 0xffff0000, v218
	v_lshlrev_b32_e32 v152, 16, v219
	v_and_b32_e32 v153, 0xffff0000, v219
	v_rcp_f32_e32 v146, v146
	v_rcp_f32_e32 v147, v147
	v_rcp_f32_e32 v148, v148
	v_rcp_f32_e32 v149, v149
	v_rcp_f32_e32 v150, v150
	v_rcp_f32_e32 v151, v151
	v_rcp_f32_e32 v152, v152
	v_rcp_f32_e32 v153, v153
	s_nop 0
	v_pk_mul_f32 v[62:63], v[62:63], v[146:147]
	v_pk_mul_f32 v[64:65], v[64:65], v[148:149]
	v_pk_mul_f32 v[58:59], v[58:59], v[150:151]
	v_pk_mul_f32 v[60:61], v[60:61], v[152:153]
	v_cvt_pk_bf16_f32 v216, v62, v63
	v_cvt_pk_bf16_f32 v217, v64, v65
	v_cvt_pk_bf16_f32 v218, v58, v59
	v_cvt_pk_bf16_f32 v219, v60, v61
	v_lshlrev_b32_e32 v168, 16, v220
	v_and_b32_e32 v169, 0xffff0000, v220
	v_lshlrev_b32_e32 v178, 16, v221
	v_and_b32_e32 v179, 0xffff0000, v221
	v_lshlrev_b32_e32 v180, 16, v222
	v_and_b32_e32 v181, 0xffff0000, v222
	v_lshlrev_b32_e32 v244, 16, v223
	v_and_b32_e32 v245, 0xffff0000, v223
	v_rcp_f32_e32 v168, v168
	v_rcp_f32_e32 v169, v169
	v_rcp_f32_e32 v178, v178
	v_rcp_f32_e32 v179, v179
	v_rcp_f32_e32 v180, v180
	v_rcp_f32_e32 v181, v181
	v_rcp_f32_e32 v244, v244
	v_rcp_f32_e32 v245, v245
	s_nop 0
	v_pk_mul_f32 v[50:51], v[50:51], v[168:169]
	v_pk_mul_f32 v[52:53], v[52:53], v[178:179]
	v_pk_mul_f32 v[42:43], v[42:43], v[180:181]
	v_pk_mul_f32 v[44:45], v[44:45], v[244:245]
	v_cvt_pk_bf16_f32 v220, v50, v51
	v_cvt_pk_bf16_f32 v221, v52, v53
	v_cvt_pk_bf16_f32 v222, v42, v43
	v_cvt_pk_bf16_f32 v223, v44, v45
	global_store_dwordx4 v[138:139], v[216:219], off
	global_store_dwordx4 v[138:139], v[220:223], off offset:256
	s_waitcnt vmcnt(14)
	v_lshlrev_b32_e32 v146, 16, v224
	v_and_b32_e32 v147, 0xffff0000, v224
	v_lshlrev_b32_e32 v148, 16, v225
	v_and_b32_e32 v149, 0xffff0000, v225
	v_lshlrev_b32_e32 v150, 16, v226
	v_and_b32_e32 v151, 0xffff0000, v226
	v_lshlrev_b32_e32 v152, 16, v227
	v_and_b32_e32 v153, 0xffff0000, v227
	v_rcp_f32_e32 v146, v146
	v_rcp_f32_e32 v147, v147
	v_rcp_f32_e32 v148, v148
	v_rcp_f32_e32 v149, v149
	v_rcp_f32_e32 v150, v150
	v_rcp_f32_e32 v151, v151
	v_rcp_f32_e32 v152, v152
	v_rcp_f32_e32 v153, v153
	s_nop 0
	v_pk_mul_f32 v[54:55], v[54:55], v[146:147]
	v_pk_mul_f32 v[56:57], v[56:57], v[148:149]
	v_pk_mul_f32 v[46:47], v[46:47], v[150:151]
	v_pk_mul_f32 v[48:49], v[48:49], v[152:153]
	v_cvt_pk_bf16_f32 v224, v54, v55
	v_cvt_pk_bf16_f32 v225, v56, v57
	v_cvt_pk_bf16_f32 v226, v46, v47
	v_cvt_pk_bf16_f32 v227, v48, v49
	v_lshlrev_b32_e32 v168, 16, v228
	v_and_b32_e32 v169, 0xffff0000, v228
	v_lshlrev_b32_e32 v178, 16, v229
	v_and_b32_e32 v179, 0xffff0000, v229
	v_lshlrev_b32_e32 v180, 16, v230
	v_and_b32_e32 v181, 0xffff0000, v230
	v_lshlrev_b32_e32 v244, 16, v231
	v_and_b32_e32 v245, 0xffff0000, v231
	v_rcp_f32_e32 v168, v168
	v_rcp_f32_e32 v169, v169
	v_rcp_f32_e32 v178, v178
	v_rcp_f32_e32 v179, v179
	v_rcp_f32_e32 v180, v180
	v_rcp_f32_e32 v181, v181
	v_rcp_f32_e32 v244, v244
	v_rcp_f32_e32 v245, v245
	s_nop 0
	v_pk_mul_f32 v[34:35], v[34:35], v[168:169]
	v_pk_mul_f32 v[36:37], v[36:37], v[178:179]
	v_pk_mul_f32 v[26:27], v[26:27], v[180:181]
	v_pk_mul_f32 v[28:29], v[28:29], v[244:245]
	v_cvt_pk_bf16_f32 v228, v34, v35
	v_cvt_pk_bf16_f32 v229, v36, v37
	v_cvt_pk_bf16_f32 v230, v26, v27
	v_cvt_pk_bf16_f32 v231, v28, v29
	global_store_dwordx4 v[140:141], v[224:227], off
	global_store_dwordx4 v[140:141], v[228:231], off offset:256
	s_waitcnt vmcnt(12)
; DI float bflo(unsigned w) { return __uint_as_float(w << 16); }
; DI float bfhi(unsigned w) { return __uint_as_float(w & 0xffff0000u); }
; DI u32x4 pack8(f32x4 a, f32x4 b) { u32x4 w; w.x = pk2(a[0], a[1]); w.y = pk2(a[2], a[3]); w.z = pk2(b[0], b[1]); w.w = pk2(b[2], b[3]); return w; }
;     DI void operator()(Acc& acc, const Unit& u, int wr, int wc, int fr, int fq) const {
;     ...
;             for (int ai = 0; ai < 2; ++ai)
; #pragma unroll
;                 for (int m = 0; m < 4; ++m)
; #pragma unroll
;                     for (int bj = 0; bj < 2; ++bj) g[ai][m][bj] = *(const u32x4*)(base + (size_t)(ai * 128 + m * 16) * NPJ + u.k * 1024 + bj * 128);
; #pragma unroll
;             for (int ai = 0; ai < 2; ++ai)
; #pragma unroll
;                 for (int m = 0; m < 4; ++m)
; #pragma unroll
;                     for (int bj = 0; bj < 2; ++bj) { const u32x4 q = g[ai][m][bj]; f32x4& v0 = acc[ai][bj][m][0]; f32x4& v1 = acc[ai][bj][m][1];
;                         v0[0] *= bflo(q.x); v0[1] *= bfhi(q.x); v0[2] *= bflo(q.y); v0[3] *= bfhi(q.y); v1[0] *= bflo(q.z); v1[1] *= bfhi(q.z); v1[2] *= bflo(q.w); v1[3] *= bfhi(q.w); }
;         }
;         if (u.k > 0) {
;             u32x4 g[2][4][2];
; #pragma unroll
;             for (int ai = 0; ai < 2; ++ai)
; #pragma unroll
;                 for (int m = 0; m < 4; ++m)
; #pragma unroll
;                     for (int bj = 0; bj < 2; ++bj) g[ai][m][bj] = *(const u32x4*)(base + (size_t)(ai * 128 + m * 16) * NPJ + bj * 128);
; #pragma unroll
;             for (int ai = 0; ai < 2; ++ai)
; #pragma unroll
;                 for (int m = 0; m < 4; ++m)
; #pragma unroll
;                     for (int bj = 0; bj < 2; ++bj) { const u32x4 q = g[ai][m][bj]; f32x4& v0 = acc[ai][bj][m][0]; f32x4& v1 = acc[ai][bj][m][1];
;                         v0[0] += bflo(q.x); v0[1] += bfhi(q.x); v0[2] += bflo(q.y); v0[3] += bfhi(q.y); v1[0] += bflo(q.z); v1[1] += bfhi(q.z); v1[2] += bflo(q.w); v1[3] += bfhi(q.w); }
;         }
;         if (!dry) {
; #pragma unroll
;             for (int ai = 0; ai < 2; ++ai)
; #pragma unroll
;                 for (int m = 0; m < 4; ++m)
; #pragma unroll
;                     for (int bj = 0; bj < 2; ++bj) *(u32x4*)(base + (size_t)(ai * 128 + m * 16) * NPJ + bj * 128) = pack8(acc[ai][bj][m][0], acc[ai][bj][m][1]);
	v_lshlrev_b32_e32 v146, 16, v184
	v_and_b32_e32 v147, 0xffff0000, v184
	v_lshlrev_b32_e32 v148, 16, v185
	v_and_b32_e32 v149, 0xffff0000, v185
	v_lshlrev_b32_e32 v150, 16, v186
	v_and_b32_e32 v151, 0xffff0000, v186
	v_lshlrev_b32_e32 v152, 16, v187
	v_and_b32_e32 v153, 0xffff0000, v187
	v_rcp_f32_e32 v146, v146
	v_rcp_f32_e32 v147, v147
	v_rcp_f32_e32 v148, v148
	v_rcp_f32_e32 v149, v149
	v_rcp_f32_e32 v150, v150
	v_rcp_f32_e32 v151, v151
	v_rcp_f32_e32 v152, v152
	v_rcp_f32_e32 v153, v153
	s_nop 0
	v_pk_mul_f32 v[38:39], v[38:39], v[146:147]
	v_pk_mul_f32 v[40:41], v[40:41], v[148:149]
	v_pk_mul_f32 v[30:31], v[30:31], v[150:151]
	v_pk_mul_f32 v[32:33], v[32:33], v[152:153]
	v_cvt_pk_bf16_f32 v184, v38, v39
	v_cvt_pk_bf16_f32 v185, v40, v41
	v_cvt_pk_bf16_f32 v186, v30, v31
	v_cvt_pk_bf16_f32 v187, v32, v33
	v_lshlrev_b32_e32 v168, 16, v188
	v_and_b32_e32 v169, 0xffff0000, v188
	v_lshlrev_b32_e32 v178, 16, v189
	v_and_b32_e32 v179, 0xffff0000, v189
	v_lshlrev_b32_e32 v180, 16, v190
	v_and_b32_e32 v181, 0xffff0000, v190
	v_lshlrev_b32_e32 v244, 16, v191
	v_and_b32_e32 v245, 0xffff0000, v191
	v_rcp_f32_e32 v168, v168
	v_rcp_f32_e32 v169, v169
	v_rcp_f32_e32 v178, v178
	v_rcp_f32_e32 v179, v179
	v_rcp_f32_e32 v180, v180
	v_rcp_f32_e32 v181, v181
	v_rcp_f32_e32 v244, v244
	v_rcp_f32_e32 v245, v245
	s_nop 0
	v_pk_mul_f32 v[18:19], v[18:19], v[168:169]
	v_pk_mul_f32 v[20:21], v[20:21], v[178:179]
	v_pk_mul_f32 v[10:11], v[10:11], v[180:181]
	v_pk_mul_f32 v[12:13], v[12:13], v[244:245]
	v_cvt_pk_bf16_f32 v188, v18, v19
	v_cvt_pk_bf16_f32 v189, v20, v21
	v_cvt_pk_bf16_f32 v190, v10, v11
	v_cvt_pk_bf16_f32 v191, v12, v13
	global_store_dwordx4 v[142:143], v[184:187], off
	global_store_dwordx4 v[142:143], v[188:191], off offset:256
	s_waitcnt vmcnt(10)
	v_lshlrev_b32_e32 v146, 16, v192
	v_and_b32_e32 v147, 0xffff0000, v192
	v_lshlrev_b32_e32 v148, 16, v193
	v_and_b32_e32 v149, 0xffff0000, v193
	v_lshlrev_b32_e32 v150, 16, v194
	v_and_b32_e32 v151, 0xffff0000, v194
	v_lshlrev_b32_e32 v152, 16, v195
	v_and_b32_e32 v153, 0xffff0000, v195
	v_rcp_f32_e32 v146, v146
	v_rcp_f32_e32 v147, v147
	v_rcp_f32_e32 v148, v148
	v_rcp_f32_e32 v149, v149
	v_rcp_f32_e32 v150, v150
	v_rcp_f32_e32 v151, v151
	v_rcp_f32_e32 v152, v152
	v_rcp_f32_e32 v153, v153
	s_nop 0
	v_pk_mul_f32 v[22:23], v[22:23], v[146:147]
	v_pk_mul_f32 v[24:25], v[24:25], v[148:149]
	v_pk_mul_f32 v[14:15], v[14:15], v[150:151]
	v_pk_mul_f32 v[16:17], v[16:17], v[152:153]
	v_cvt_pk_bf16_f32 v192, v22, v23
	v_cvt_pk_bf16_f32 v193, v24, v25
	v_cvt_pk_bf16_f32 v194, v14, v15
	v_cvt_pk_bf16_f32 v195, v16, v17
	v_lshlrev_b32_e32 v168, 16, v196
	v_and_b32_e32 v169, 0xffff0000, v196
	v_lshlrev_b32_e32 v178, 16, v197
	v_and_b32_e32 v179, 0xffff0000, v197
	v_lshlrev_b32_e32 v180, 16, v198
	v_and_b32_e32 v181, 0xffff0000, v198
	v_lshlrev_b32_e32 v244, 16, v199
	v_and_b32_e32 v245, 0xffff0000, v199
	v_rcp_f32_e32 v168, v168
	v_rcp_f32_e32 v169, v169
	v_rcp_f32_e32 v178, v178
	v_rcp_f32_e32 v179, v179
	v_rcp_f32_e32 v180, v180
	v_rcp_f32_e32 v181, v181
	v_rcp_f32_e32 v244, v244
	v_rcp_f32_e32 v245, v245
	s_nop 0
	v_pk_mul_f32 v[6:7], v[6:7], v[168:169]
	v_pk_mul_f32 v[8:9], v[8:9], v[178:179]
	v_pk_mul_f32 v[2:3], v[2:3], v[180:181]
	v_pk_mul_f32 v[4:5], v[4:5], v[244:245]
	v_cvt_pk_bf16_f32 v196, v6, v7
	v_cvt_pk_bf16_f32 v197, v8, v9
	v_cvt_pk_bf16_f32 v198, v2, v3
	v_cvt_pk_bf16_f32 v199, v4, v5
	global_store_dwordx4 v[144:145], v[192:195], off
	global_store_dwordx4 v[144:145], v[196:199], off offset:256

; DI float bflo(unsigned w) { return __uint_as_float(w << 16); }
; DI float bfhi(unsigned w) { return __uint_as_float(w & 0xffff0000u); }
;     DI void operator()(Acc& acc, const Unit& u, int wr, int wc, int fr, int fq) const {
;     ...
;         bf16_t* base = proj + (size_t)(u.pm * 256 + wr * 64 + fr) * NPJ + C_GL + u.pn * 256 + wc * 32 + fq * 8;
;         {
;             u32x4 g[2][4][2];
; #pragma unroll
;             for (int ai = 0; ai < 2; ++ai)
; #pragma unroll
;                 for (int m = 0; m < 4; ++m)
; #pragma unroll
;                     for (int bj = 0; bj < 2; ++bj) g[ai][m][bj] = *(const u32x4*)(base + (size_t)(ai * 128 + m * 16) * NPJ + u.k * 1024 + bj * 128);
; #pragma unroll
;             for (int ai = 0; ai < 2; ++ai)
; #pragma unroll
;                 for (int m = 0; m < 4; ++m)
; #pragma unroll
;                     for (int bj = 0; bj < 2; ++bj) { const u32x4 q = g[ai][m][bj]; f32x4& v0 = acc[ai][bj][m][0]; f32x4& v1 = acc[ai][bj][m][1];
;                         v0[0] *= bflo(q.x); v0[1] *= bfhi(q.x); v0[2] *= bflo(q.y); v0[3] *= bfhi(q.y); v1[0] *= bflo(q.z); v1[1] *= bfhi(q.z); v1[2] *= bflo(q.w); v1[3] *= bfhi(q.w); }
.LBB0_1266:
	v_mov_b32_e32 v130, v1
	v_mov_b32_e32 v132, v170
	s_lshl_b32 s22, s69, 8
	s_add_i32 s22, s22, s34
	v_add_u32_e32 v133, s22, v130
	v_mov_b64_e32 v[130:131], s[48:49]
	v_mad_i64_i32 v[130:131], s[22:23], v133, s40, v[130:131]
	s_lshl_b32 s22, s68, 8
	s_ashr_i32 s23, s22, 31
	v_lshl_add_u64 v[130:131], s[22:23], 1, v[130:131]
	v_lshlrev_b32_e32 v132, 3, v132
	v_lshl_add_u64 v[130:131], v[130:131], 0, s[8:9]
	v_ashrrev_i32_e32 v133, 31, v132
	v_lshl_add_u64 v[130:131], v[132:133], 1, v[130:131]
	s_lshl_b32 s22, s67, 10
	v_lshl_add_u64 v[166:167], v[130:131], 0, s[16:17]
	s_ashr_i32 s23, s22, 31
	v_lshl_add_u64 v[130:131], s[22:23], 1, v[166:167]
	s_nop 0
	v_readfirstlane_b32 s98, v130
	v_readfirstlane_b32 s99, v131
	v_bfe_u32 v148, v183, 5, 3
	v_mul_u32_u24_e32 v148, 0x3200, v148
	v_and_b32_e32 v149, 31, v183
	v_lshl_add_u32 v148, v149, 4, v148
	v_bfe_u32 v149, v183, 6, 2
	v_lshlrev_b32_e32 v149, 6, v149
	v_sub_u32_e32 v243, v148, v149
	s_cmp_eq_u32 s67, 2
	s_cbranch_scc1 .Lup6_final
	s_add_u32 s100, s98, 0x0
	s_addc_u32 s101, s99, 0
	global_load_dwordx4 v[184:187], v243, s[100:101]
	s_add_u32 s100, s98, 0x19000
	s_addc_u32 s101, s99, 0
	global_load_dwordx4 v[188:191], v243, s[100:101]
	s_add_u32 s100, s98, 0x0
	s_addc_u32 s101, s99, 0
	global_load_dwordx4 v[192:195], v243, s[100:101] offset:2048
	s_add_u32 s100, s98, 0x19000
	s_addc_u32 s101, s99, 0
	global_load_dwordx4 v[196:199], v243, s[100:101] offset:2048
	s_add_u32 s100, s98, 0x32000
	s_addc_u32 s101, s99, 0
	global_load_dwordx4 v[200:203], v243, s[100:101]
	s_add_u32 s100, s98, 0x4b000
	s_addc_u32 s101, s99, 0
	global_load_dwordx4 v[204:207], v243, s[100:101]
	s_add_u32 s100, s98, 0x32000
	s_addc_u32 s101, s99, 0
	global_load_dwordx4 v[208:211], v243, s[100:101] offset:2048
	s_add_u32 s100, s98, 0x4b000
	s_addc_u32 s101, s99, 0
	global_load_dwordx4 v[212:215], v243, s[100:101] offset:2048
	s_add_u32 s100, s98, 0x64000
	s_addc_u32 s101, s99, 0
	global_load_dwordx4 v[216:219], v243, s[100:101]
	s_add_u32 s100, s98, 0x7d000
	s_addc_u32 s101, s99, 0
	global_load_dwordx4 v[220:223], v243, s[100:101]
	s_add_u32 s100, s98, 0x64000
	s_addc_u32 s101, s99, 0
	global_load_dwordx4 v[224:227], v243, s[100:101] offset:2048
	s_add_u32 s100, s98, 0x7d000
	s_addc_u32 s101, s99, 0
	global_load_dwordx4 v[228:231], v243, s[100:101] offset:2048
	s_waitcnt vmcnt(8)
	v_lshlrev_b32_e32 v148, 16, v184
	v_and_b32_e32 v149, 0xffff0000, v184
	v_lshlrev_b32_e32 v150, 16, v192
	v_and_b32_e32 v151, 0xffff0000, v192
	v_lshlrev_b32_e32 v152, 16, v185
	v_and_b32_e32 v153, 0xffff0000, v185
	v_lshlrev_b32_e32 v168, 16, v193
	v_and_b32_e32 v169, 0xffff0000, v193
	v_rcp_f32_e32 v148, v148
	v_rcp_f32_e32 v149, v149
	v_rcp_f32_e32 v152, v152
	v_rcp_f32_e32 v153, v153
	s_nop 0
	v_pk_mul_f32 v[148:149], v[148:149], v[150:151]
	v_pk_mul_f32 v[152:153], v[152:153], v[168:169]
	v_pk_mul_f32 v[126:127], v[126:127], v[148:149]
	v_pk_mul_f32 v[128:129], v[128:129], v[152:153]
	v_lshlrev_b32_e32 v176, 16, v186
	v_and_b32_e32 v177, 0xffff0000, v186
	v_lshlrev_b32_e32 v178, 16, v194
	v_and_b32_e32 v179, 0xffff0000, v194
	v_lshlrev_b32_e32 v180, 16, v187
	v_and_b32_e32 v181, 0xffff0000, v187
	v_lshlrev_b32_e32 v244, 16, v195
	v_and_b32_e32 v245, 0xffff0000, v195
	v_rcp_f32_e32 v176, v176
	v_rcp_f32_e32 v177, v177
	v_rcp_f32_e32 v180, v180
	v_rcp_f32_e32 v181, v181
	s_nop 0
	v_pk_mul_f32 v[176:177], v[176:177], v[178:179]
	v_pk_mul_f32 v[180:181], v[180:181], v[244:245]
	v_pk_mul_f32 v[122:123], v[122:123], v[176:177]
	v_pk_mul_f32 v[124:125], v[124:125], v[180:181]
	v_lshlrev_b32_e32 v176, 16, v188
	v_and_b32_e32 v177, 0xffff0000, v188
	v_lshlrev_b32_e32 v178, 16, v196
	v_and_b32_e32 v179, 0xffff0000, v196
	v_lshlrev_b32_e32 v180, 16, v189
	v_and_b32_e32 v181, 0xffff0000, v189
	v_lshlrev_b32_e32 v244, 16, v197
	v_and_b32_e32 v245, 0xffff0000, v197
	v_rcp_f32_e32 v176, v176
	v_rcp_f32_e32 v177, v177
	v_rcp_f32_e32 v180, v180
	v_rcp_f32_e32 v181, v181
	s_nop 0
	v_pk_mul_f32 v[176:177], v[176:177], v[178:179]
	v_pk_mul_f32 v[180:181], v[180:181], v[244:245]
	v_pk_mul_f32 v[114:115], v[114:115], v[176:177]
	v_pk_mul_f32 v[116:117], v[116:117], v[180:181]
	v_lshlrev_b32_e32 v148, 16, v190
	v_and_b32_e32 v149, 0xffff0000, v190
	v_lshlrev_b32_e32 v150, 16, v198
	v_and_b32_e32 v151, 0xffff0000, v198
	v_lshlrev_b32_e32 v152, 16, v191
	v_and_b32_e32 v153, 0xffff0000, v191
	v_lshlrev_b32_e32 v168, 16, v199
	v_and_b32_e32 v169, 0xffff0000, v199
	v_rcp_f32_e32 v148, v148
	v_rcp_f32_e32 v149, v149
	v_rcp_f32_e32 v152, v152
	v_rcp_f32_e32 v153, v153
	s_nop 0
	v_pk_mul_f32 v[148:149], v[148:149], v[150:151]
	v_pk_mul_f32 v[152:153], v[152:153], v[168:169]
	v_pk_mul_f32 v[110:111], v[110:111], v[148:149]
	v_pk_mul_f32 v[112:113], v[112:113], v[152:153]
	s_add_u32 s100, s98, 0x96000
	s_addc_u32 s101, s99, 0
	global_load_dwordx4 v[184:187], v243, s[100:101]
	s_add_u32 s100, s98, 0xaf000
	s_addc_u32 s101, s99, 0
	global_load_dwordx4 v[188:191], v243, s[100:101]
	s_add_u32 s100, s98, 0x96000
	s_addc_u32 s101, s99, 0
	global_load_dwordx4 v[192:195], v243, s[100:101] offset:2048
	s_add_u32 s100, s98, 0xaf000
	s_addc_u32 s101, s99, 0
	global_load_dwordx4 v[196:199], v243, s[100:101] offset:2048
	s_waitcnt vmcnt(8)
; DI float bflo(unsigned w) { return __uint_as_float(w << 16); }
; DI float bfhi(unsigned w) { return __uint_as_float(w & 0xffff0000u); }
;     DI void operator()(Acc& acc, const Unit& u, int wr, int wc, int fr, int fq) const {
;     ...
;                     for (int bj = 0; bj < 2; ++bj) g[ai][m][bj] = *(const u32x4*)(base + (size_t)(ai * 128 + m * 16) * NPJ + u.k * 1024 + bj * 128);
; #pragma unroll
;             for (int ai = 0; ai < 2; ++ai)
; #pragma unroll
;                 for (int m = 0; m < 4; ++m)
; #pragma unroll
;                     for (int bj = 0; bj < 2; ++bj) { const u32x4 q = g[ai][m][bj]; f32x4& v0 = acc[ai][bj][m][0]; f32x4& v1 = acc[ai][bj][m][1];
;                         v0[0] *= bflo(q.x); v0[1] *= bfhi(q.x); v0[2] *= bflo(q.y); v0[3] *= bfhi(q.y); v1[0] *= bflo(q.z); v1[1] *= bfhi(q.z); v1[2] *= bflo(q.w); v1[3] *= bfhi(q.w); }
	v_lshlrev_b32_e32 v148, 16, v200
	v_and_b32_e32 v149, 0xffff0000, v200
	v_lshlrev_b32_e32 v150, 16, v208
	v_and_b32_e32 v151, 0xffff0000, v208
	v_lshlrev_b32_e32 v152, 16, v201
	v_and_b32_e32 v153, 0xffff0000, v201
	v_lshlrev_b32_e32 v168, 16, v209
	v_and_b32_e32 v169, 0xffff0000, v209
	v_rcp_f32_e32 v148, v148
	v_rcp_f32_e32 v149, v149
	v_rcp_f32_e32 v152, v152
	v_rcp_f32_e32 v153, v153
	s_nop 0
	v_pk_mul_f32 v[148:149], v[148:149], v[150:151]
	v_pk_mul_f32 v[152:153], v[152:153], v[168:169]
	v_pk_mul_f32 v[118:119], v[118:119], v[148:149]
	v_pk_mul_f32 v[120:121], v[120:121], v[152:153]
	v_lshlrev_b32_e32 v176, 16, v202
	v_and_b32_e32 v177, 0xffff0000, v202
	v_lshlrev_b32_e32 v178, 16, v210
	v_and_b32_e32 v179, 0xffff0000, v210
	v_lshlrev_b32_e32 v180, 16, v203
	v_and_b32_e32 v181, 0xffff0000, v203
	v_lshlrev_b32_e32 v244, 16, v211
	v_and_b32_e32 v245, 0xffff0000, v211
	v_rcp_f32_e32 v176, v176
	v_rcp_f32_e32 v177, v177
	v_rcp_f32_e32 v180, v180
	v_rcp_f32_e32 v181, v181
	s_nop 0
	v_pk_mul_f32 v[176:177], v[176:177], v[178:179]
	v_pk_mul_f32 v[180:181], v[180:181], v[244:245]
	v_pk_mul_f32 v[106:107], v[106:107], v[176:177]
	v_pk_mul_f32 v[108:109], v[108:109], v[180:181]
	v_lshlrev_b32_e32 v176, 16, v204
	v_and_b32_e32 v177, 0xffff0000, v204
	v_lshlrev_b32_e32 v178, 16, v212
	v_and_b32_e32 v179, 0xffff0000, v212
	v_lshlrev_b32_e32 v180, 16, v205
	v_and_b32_e32 v181, 0xffff0000, v205
	v_lshlrev_b32_e32 v244, 16, v213
	v_and_b32_e32 v245, 0xffff0000, v213
	v_rcp_f32_e32 v176, v176
	v_rcp_f32_e32 v177, v177
	v_rcp_f32_e32 v180, v180
	v_rcp_f32_e32 v181, v181
	s_nop 0
	v_pk_mul_f32 v[176:177], v[176:177], v[178:179]
	v_pk_mul_f32 v[180:181], v[180:181], v[244:245]
	v_pk_mul_f32 v[98:99], v[98:99], v[176:177]
	v_pk_mul_f32 v[100:101], v[100:101], v[180:181]
	v_lshlrev_b32_e32 v148, 16, v206
	v_and_b32_e32 v149, 0xffff0000, v206
	v_lshlrev_b32_e32 v150, 16, v214
	v_and_b32_e32 v151, 0xffff0000, v214
	v_lshlrev_b32_e32 v152, 16, v207
	v_and_b32_e32 v153, 0xffff0000, v207
	v_lshlrev_b32_e32 v168, 16, v215
	v_and_b32_e32 v169, 0xffff0000, v215
	v_rcp_f32_e32 v148, v148
	v_rcp_f32_e32 v149, v149
	v_rcp_f32_e32 v152, v152
	v_rcp_f32_e32 v153, v153
	s_nop 0
	v_pk_mul_f32 v[148:149], v[148:149], v[150:151]
	v_pk_mul_f32 v[152:153], v[152:153], v[168:169]
	v_pk_mul_f32 v[90:91], v[90:91], v[148:149]
	v_pk_mul_f32 v[92:93], v[92:93], v[152:153]
	s_add_u32 s100, s98, 0x190000
	s_addc_u32 s101, s99, 0
	global_load_dwordx4 v[200:203], v243, s[100:101]
	s_add_u32 s100, s98, 0x1a9000
	s_addc_u32 s101, s99, 0
	global_load_dwordx4 v[204:207], v243, s[100:101]
	s_add_u32 s100, s98, 0x190000
	s_addc_u32 s101, s99, 0
	global_load_dwordx4 v[208:211], v243, s[100:101] offset:2048
	s_add_u32 s100, s98, 0x1a9000
	s_addc_u32 s101, s99, 0
	global_load_dwordx4 v[212:215], v243, s[100:101] offset:2048
	s_waitcnt vmcnt(8)
	v_lshlrev_b32_e32 v148, 16, v216
	v_and_b32_e32 v149, 0xffff0000, v216
	v_lshlrev_b32_e32 v150, 16, v224
	v_and_b32_e32 v151, 0xffff0000, v224
	v_lshlrev_b32_e32 v152, 16, v217
	v_and_b32_e32 v153, 0xffff0000, v217
	v_lshlrev_b32_e32 v168, 16, v225
	v_and_b32_e32 v169, 0xffff0000, v225
	v_rcp_f32_e32 v148, v148
	v_rcp_f32_e32 v149, v149
	v_rcp_f32_e32 v152, v152
	v_rcp_f32_e32 v153, v153
	s_nop 0
	v_pk_mul_f32 v[148:149], v[148:149], v[150:151]
	v_pk_mul_f32 v[152:153], v[152:153], v[168:169]
	v_pk_mul_f32 v[102:103], v[102:103], v[148:149]
	v_pk_mul_f32 v[104:105], v[104:105], v[152:153]
	v_lshlrev_b32_e32 v176, 16, v218
	v_and_b32_e32 v177, 0xffff0000, v218
	v_lshlrev_b32_e32 v178, 16, v226
	v_and_b32_e32 v179, 0xffff0000, v226
	v_lshlrev_b32_e32 v180, 16, v219
	v_and_b32_e32 v181, 0xffff0000, v219
	v_lshlrev_b32_e32 v244, 16, v227
	v_and_b32_e32 v245, 0xffff0000, v227
	v_rcp_f32_e32 v176, v176
	v_rcp_f32_e32 v177, v177
	v_rcp_f32_e32 v180, v180
	v_rcp_f32_e32 v181, v181
	s_nop 0
	v_pk_mul_f32 v[176:177], v[176:177], v[178:179]
	v_pk_mul_f32 v[180:181], v[180:181], v[244:245]
	v_pk_mul_f32 v[94:95], v[94:95], v[176:177]
	v_pk_mul_f32 v[96:97], v[96:97], v[180:181]
	v_lshlrev_b32_e32 v176, 16, v220
	v_and_b32_e32 v177, 0xffff0000, v220
	v_lshlrev_b32_e32 v178, 16, v228
	v_and_b32_e32 v179, 0xffff0000, v228
	v_lshlrev_b32_e32 v180, 16, v221
	v_and_b32_e32 v181, 0xffff0000, v221
	v_lshlrev_b32_e32 v244, 16, v229
	v_and_b32_e32 v245, 0xffff0000, v229
	v_rcp_f32_e32 v176, v176
	v_rcp_f32_e32 v177, v177
	v_rcp_f32_e32 v180, v180
	v_rcp_f32_e32 v181, v181
	s_nop 0
	v_pk_mul_f32 v[176:177], v[176:177], v[178:179]
	v_pk_mul_f32 v[180:181], v[180:181], v[244:245]
	v_pk_mul_f32 v[82:83], v[82:83], v[176:177]
	v_pk_mul_f32 v[84:85], v[84:85], v[180:181]
	v_lshlrev_b32_e32 v148, 16, v222
	v_and_b32_e32 v149, 0xffff0000, v222
	v_lshlrev_b32_e32 v150, 16, v230
	v_and_b32_e32 v151, 0xffff0000, v230
	v_lshlrev_b32_e32 v152, 16, v223
	v_and_b32_e32 v153, 0xffff0000, v223
	v_lshlrev_b32_e32 v168, 16, v231
	v_and_b32_e32 v169, 0xffff0000, v231
	v_rcp_f32_e32 v148, v148
	v_rcp_f32_e32 v149, v149
	v_rcp_f32_e32 v152, v152
	v_rcp_f32_e32 v153, v153
	s_nop 0
	v_pk_mul_f32 v[148:149], v[148:149], v[150:151]
	v_pk_mul_f32 v[152:153], v[152:153], v[168:169]
	v_pk_mul_f32 v[74:75], v[74:75], v[148:149]
	v_pk_mul_f32 v[76:77], v[76:77], v[152:153]
	s_add_u32 s100, s98, 0x1c2000
	s_addc_u32 s101, s99, 0
	global_load_dwordx4 v[216:219], v243, s[100:101]
	s_add_u32 s100, s98, 0x1db000
	s_addc_u32 s101, s99, 0
	global_load_dwordx4 v[220:223], v243, s[100:101]
	s_add_u32 s100, s98, 0x1c2000
	s_addc_u32 s101, s99, 0
	global_load_dwordx4 v[224:227], v243, s[100:101] offset:2048
	s_add_u32 s100, s98, 0x1db000
	s_addc_u32 s101, s99, 0
	global_load_dwordx4 v[228:231], v243, s[100:101] offset:2048
	s_waitcnt vmcnt(8)
; DI float bflo(unsigned w) { return __uint_as_float(w << 16); }
; DI float bfhi(unsigned w) { return __uint_as_float(w & 0xffff0000u); }
;     DI void operator()(Acc& acc, const Unit& u, int wr, int wc, int fr, int fq) const {
;     ...
;                     for (int bj = 0; bj < 2; ++bj) g[ai][m][bj] = *(const u32x4*)(base + (size_t)(ai * 128 + m * 16) * NPJ + u.k * 1024 + bj * 128);
; #pragma unroll
;             for (int ai = 0; ai < 2; ++ai)
; #pragma unroll
;                 for (int m = 0; m < 4; ++m)
; #pragma unroll
;                     for (int bj = 0; bj < 2; ++bj) { const u32x4 q = g[ai][m][bj]; f32x4& v0 = acc[ai][bj][m][0]; f32x4& v1 = acc[ai][bj][m][1];
;                         v0[0] *= bflo(q.x); v0[1] *= bfhi(q.x); v0[2] *= bflo(q.y); v0[3] *= bfhi(q.y); v1[0] *= bflo(q.z); v1[1] *= bfhi(q.z); v1[2] *= bflo(q.w); v1[3] *= bfhi(q.w); }
	v_lshlrev_b32_e32 v148, 16, v184
	v_and_b32_e32 v149, 0xffff0000, v184
	v_lshlrev_b32_e32 v150, 16, v192
	v_and_b32_e32 v151, 0xffff0000, v192
	v_lshlrev_b32_e32 v152, 16, v185
	v_and_b32_e32 v153, 0xffff0000, v185
	v_lshlrev_b32_e32 v168, 16, v193
	v_and_b32_e32 v169, 0xffff0000, v193
	v_rcp_f32_e32 v148, v148
	v_rcp_f32_e32 v149, v149
	v_rcp_f32_e32 v152, v152
	v_rcp_f32_e32 v153, v153
	s_nop 0
	v_pk_mul_f32 v[148:149], v[148:149], v[150:151]
	v_pk_mul_f32 v[152:153], v[152:153], v[168:169]
	v_pk_mul_f32 v[86:87], v[86:87], v[148:149]
	v_pk_mul_f32 v[88:89], v[88:89], v[152:153]
	v_lshlrev_b32_e32 v176, 16, v186
	v_and_b32_e32 v177, 0xffff0000, v186
	v_lshlrev_b32_e32 v178, 16, v194
	v_and_b32_e32 v179, 0xffff0000, v194
	v_lshlrev_b32_e32 v180, 16, v187
	v_and_b32_e32 v181, 0xffff0000, v187
	v_lshlrev_b32_e32 v244, 16, v195
	v_and_b32_e32 v245, 0xffff0000, v195
	v_rcp_f32_e32 v176, v176
	v_rcp_f32_e32 v177, v177
	v_rcp_f32_e32 v180, v180
	v_rcp_f32_e32 v181, v181
	s_nop 0
	v_pk_mul_f32 v[176:177], v[176:177], v[178:179]
	v_pk_mul_f32 v[180:181], v[180:181], v[244:245]
	v_pk_mul_f32 v[78:79], v[78:79], v[176:177]
	v_pk_mul_f32 v[80:81], v[80:81], v[180:181]
	v_lshlrev_b32_e32 v176, 16, v188
	v_and_b32_e32 v177, 0xffff0000, v188
	v_lshlrev_b32_e32 v178, 16, v196
	v_and_b32_e32 v179, 0xffff0000, v196
	v_lshlrev_b32_e32 v180, 16, v189
	v_and_b32_e32 v181, 0xffff0000, v189
	v_lshlrev_b32_e32 v244, 16, v197
	v_and_b32_e32 v245, 0xffff0000, v197
	v_rcp_f32_e32 v176, v176
	v_rcp_f32_e32 v177, v177
	v_rcp_f32_e32 v180, v180
	v_rcp_f32_e32 v181, v181
	s_nop 0
	v_pk_mul_f32 v[176:177], v[176:177], v[178:179]
	v_pk_mul_f32 v[180:181], v[180:181], v[244:245]
	v_pk_mul_f32 v[70:71], v[70:71], v[176:177]
	v_pk_mul_f32 v[72:73], v[72:73], v[180:181]
	v_lshlrev_b32_e32 v148, 16, v190
	v_and_b32_e32 v149, 0xffff0000, v190
	v_lshlrev_b32_e32 v150, 16, v198
	v_and_b32_e32 v151, 0xffff0000, v198
	v_lshlrev_b32_e32 v152, 16, v191
	v_and_b32_e32 v153, 0xffff0000, v191
	v_lshlrev_b32_e32 v168, 16, v199
	v_and_b32_e32 v169, 0xffff0000, v199
	v_rcp_f32_e32 v148, v148
	v_rcp_f32_e32 v149, v149
	v_rcp_f32_e32 v152, v152
	v_rcp_f32_e32 v153, v153
	s_nop 0
	v_pk_mul_f32 v[148:149], v[148:149], v[150:151]
	v_pk_mul_f32 v[152:153], v[152:153], v[168:169]
	v_pk_mul_f32 v[66:67], v[66:67], v[148:149]
	v_pk_mul_f32 v[68:69], v[68:69], v[152:153]
	s_add_u32 s100, s98, 0x1f4000
	s_addc_u32 s101, s99, 0
	global_load_dwordx4 v[184:187], v243, s[100:101]
	s_add_u32 s100, s98, 0x20d000
	s_addc_u32 s101, s99, 0
	global_load_dwordx4 v[188:191], v243, s[100:101]
	s_add_u32 s100, s98, 0x1f4000
	s_addc_u32 s101, s99, 0
	global_load_dwordx4 v[192:195], v243, s[100:101] offset:2048
	s_add_u32 s100, s98, 0x20d000
	s_addc_u32 s101, s99, 0
	global_load_dwordx4 v[196:199], v243, s[100:101] offset:2048
	s_waitcnt vmcnt(8)
	v_lshlrev_b32_e32 v148, 16, v200
	v_and_b32_e32 v149, 0xffff0000, v200
	v_lshlrev_b32_e32 v150, 16, v208
	v_and_b32_e32 v151, 0xffff0000, v208
	v_lshlrev_b32_e32 v152, 16, v201
	v_and_b32_e32 v153, 0xffff0000, v201
	v_lshlrev_b32_e32 v168, 16, v209
	v_and_b32_e32 v169, 0xffff0000, v209
	v_rcp_f32_e32 v148, v148
	v_rcp_f32_e32 v149, v149
	v_rcp_f32_e32 v152, v152
	v_rcp_f32_e32 v153, v153
	s_nop 0
	v_pk_mul_f32 v[148:149], v[148:149], v[150:151]
	v_pk_mul_f32 v[152:153], v[152:153], v[168:169]
	v_pk_mul_f32 v[62:63], v[62:63], v[148:149]
	v_pk_mul_f32 v[64:65], v[64:65], v[152:153]
	v_lshlrev_b32_e32 v176, 16, v202
	v_and_b32_e32 v177, 0xffff0000, v202
	v_lshlrev_b32_e32 v178, 16, v210
	v_and_b32_e32 v179, 0xffff0000, v210
	v_lshlrev_b32_e32 v180, 16, v203
	v_and_b32_e32 v181, 0xffff0000, v203
	v_lshlrev_b32_e32 v244, 16, v211
	v_and_b32_e32 v245, 0xffff0000, v211
	v_rcp_f32_e32 v176, v176
	v_rcp_f32_e32 v177, v177
	v_rcp_f32_e32 v180, v180
	v_rcp_f32_e32 v181, v181
	s_nop 0
	v_pk_mul_f32 v[176:177], v[176:177], v[178:179]
	v_pk_mul_f32 v[180:181], v[180:181], v[244:245]
	v_pk_mul_f32 v[58:59], v[58:59], v[176:177]
	v_pk_mul_f32 v[60:61], v[60:61], v[180:181]
	v_lshlrev_b32_e32 v176, 16, v204
	v_and_b32_e32 v177, 0xffff0000, v204
	v_lshlrev_b32_e32 v178, 16, v212
	v_and_b32_e32 v179, 0xffff0000, v212
	v_lshlrev_b32_e32 v180, 16, v205
	v_and_b32_e32 v181, 0xffff0000, v205
	v_lshlrev_b32_e32 v244, 16, v213
	v_and_b32_e32 v245, 0xffff0000, v213
	v_rcp_f32_e32 v176, v176
	v_rcp_f32_e32 v177, v177
	v_rcp_f32_e32 v180, v180
	v_rcp_f32_e32 v181, v181
	s_nop 0
	v_pk_mul_f32 v[176:177], v[176:177], v[178:179]
	v_pk_mul_f32 v[180:181], v[180:181], v[244:245]
	v_pk_mul_f32 v[50:51], v[50:51], v[176:177]
	v_pk_mul_f32 v[52:53], v[52:53], v[180:181]
	v_lshlrev_b32_e32 v148, 16, v206
	v_and_b32_e32 v149, 0xffff0000, v206
	v_lshlrev_b32_e32 v150, 16, v214
	v_and_b32_e32 v151, 0xffff0000, v214
	v_lshlrev_b32_e32 v152, 16, v207
	v_and_b32_e32 v153, 0xffff0000, v207
	v_lshlrev_b32_e32 v168, 16, v215
	v_and_b32_e32 v169, 0xffff0000, v215
	v_rcp_f32_e32 v148, v148
	v_rcp_f32_e32 v149, v149
	v_rcp_f32_e32 v152, v152
	v_rcp_f32_e32 v153, v153
	s_nop 0
	v_pk_mul_f32 v[148:149], v[148:149], v[150:151]
	v_pk_mul_f32 v[152:153], v[152:153], v[168:169]
	v_pk_mul_f32 v[42:43], v[42:43], v[148:149]
	v_pk_mul_f32 v[44:45], v[44:45], v[152:153]
	s_add_u32 s100, s98, 0x226000
	s_addc_u32 s101, s99, 0
	global_load_dwordx4 v[200:203], v243, s[100:101]
	s_add_u32 s100, s98, 0x23f000
	s_addc_u32 s101, s99, 0
	global_load_dwordx4 v[204:207], v243, s[100:101]
	s_add_u32 s100, s98, 0x226000
	s_addc_u32 s101, s99, 0
	global_load_dwordx4 v[208:211], v243, s[100:101] offset:2048
	s_add_u32 s100, s98, 0x23f000
	s_addc_u32 s101, s99, 0
	global_load_dwordx4 v[212:215], v243, s[100:101] offset:2048
	s_waitcnt vmcnt(8)
; DI float bflo(unsigned w) { return __uint_as_float(w << 16); }
; DI float bfhi(unsigned w) { return __uint_as_float(w & 0xffff0000u); }
;     DI void operator()(Acc& acc, const Unit& u, int wr, int wc, int fr, int fq) const {
;     ...
;                     for (int bj = 0; bj < 2; ++bj) g[ai][m][bj] = *(const u32x4*)(base + (size_t)(ai * 128 + m * 16) * NPJ + u.k * 1024 + bj * 128);
; #pragma unroll
;             for (int ai = 0; ai < 2; ++ai)
; #pragma unroll
;                 for (int m = 0; m < 4; ++m)
; #pragma unroll
;                     for (int bj = 0; bj < 2; ++bj) { const u32x4 q = g[ai][m][bj]; f32x4& v0 = acc[ai][bj][m][0]; f32x4& v1 = acc[ai][bj][m][1];
;                         v0[0] *= bflo(q.x); v0[1] *= bfhi(q.x); v0[2] *= bflo(q.y); v0[3] *= bfhi(q.y); v1[0] *= bflo(q.z); v1[1] *= bfhi(q.z); v1[2] *= bflo(q.w); v1[3] *= bfhi(q.w); }
	v_lshlrev_b32_e32 v148, 16, v216
	v_and_b32_e32 v149, 0xffff0000, v216
	v_lshlrev_b32_e32 v150, 16, v224
	v_and_b32_e32 v151, 0xffff0000, v224
	v_lshlrev_b32_e32 v152, 16, v217
	v_and_b32_e32 v153, 0xffff0000, v217
	v_lshlrev_b32_e32 v168, 16, v225
	v_and_b32_e32 v169, 0xffff0000, v225
	v_rcp_f32_e32 v148, v148
	v_rcp_f32_e32 v149, v149
	v_rcp_f32_e32 v152, v152
	v_rcp_f32_e32 v153, v153
	s_nop 0
	v_pk_mul_f32 v[148:149], v[148:149], v[150:151]
	v_pk_mul_f32 v[152:153], v[152:153], v[168:169]
	v_pk_mul_f32 v[54:55], v[54:55], v[148:149]
	v_pk_mul_f32 v[56:57], v[56:57], v[152:153]
	v_lshlrev_b32_e32 v176, 16, v218
	v_and_b32_e32 v177, 0xffff0000, v218
	v_lshlrev_b32_e32 v178, 16, v226
	v_and_b32_e32 v179, 0xffff0000, v226
	v_lshlrev_b32_e32 v180, 16, v219
	v_and_b32_e32 v181, 0xffff0000, v219
	v_lshlrev_b32_e32 v244, 16, v227
	v_and_b32_e32 v245, 0xffff0000, v227
	v_rcp_f32_e32 v176, v176
	v_rcp_f32_e32 v177, v177
	v_rcp_f32_e32 v180, v180
	v_rcp_f32_e32 v181, v181
	s_nop 0
	v_pk_mul_f32 v[176:177], v[176:177], v[178:179]
	v_pk_mul_f32 v[180:181], v[180:181], v[244:245]
	v_pk_mul_f32 v[46:47], v[46:47], v[176:177]
	v_pk_mul_f32 v[48:49], v[48:49], v[180:181]
	v_lshlrev_b32_e32 v176, 16, v220
	v_and_b32_e32 v177, 0xffff0000, v220
	v_lshlrev_b32_e32 v178, 16, v228
	v_and_b32_e32 v179, 0xffff0000, v228
	v_lshlrev_b32_e32 v180, 16, v221
	v_and_b32_e32 v181, 0xffff0000, v221
	v_lshlrev_b32_e32 v244, 16, v229
	v_and_b32_e32 v245, 0xffff0000, v229
	v_rcp_f32_e32 v176, v176
	v_rcp_f32_e32 v177, v177
	v_rcp_f32_e32 v180, v180
	v_rcp_f32_e32 v181, v181
	s_nop 0
	v_pk_mul_f32 v[176:177], v[176:177], v[178:179]
	v_pk_mul_f32 v[180:181], v[180:181], v[244:245]
	v_pk_mul_f32 v[34:35], v[34:35], v[176:177]
	v_pk_mul_f32 v[36:37], v[36:37], v[180:181]
	v_lshlrev_b32_e32 v148, 16, v222
	v_and_b32_e32 v149, 0xffff0000, v222
	v_lshlrev_b32_e32 v150, 16, v230
	v_and_b32_e32 v151, 0xffff0000, v230
	v_lshlrev_b32_e32 v152, 16, v223
	v_and_b32_e32 v153, 0xffff0000, v223
	v_lshlrev_b32_e32 v168, 16, v231
	v_and_b32_e32 v169, 0xffff0000, v231
	v_rcp_f32_e32 v148, v148
	v_rcp_f32_e32 v149, v149
	v_rcp_f32_e32 v152, v152
	v_rcp_f32_e32 v153, v153
	s_nop 0
	v_pk_mul_f32 v[148:149], v[148:149], v[150:151]
	v_pk_mul_f32 v[152:153], v[152:153], v[168:169]
	v_pk_mul_f32 v[26:27], v[26:27], v[148:149]
	v_pk_mul_f32 v[28:29], v[28:29], v[152:153]
	s_waitcnt vmcnt(4)
	v_lshlrev_b32_e32 v148, 16, v184
	v_and_b32_e32 v149, 0xffff0000, v184
	v_lshlrev_b32_e32 v150, 16, v192
	v_and_b32_e32 v151, 0xffff0000, v192
	v_lshlrev_b32_e32 v152, 16, v185
	v_and_b32_e32 v153, 0xffff0000, v185
	v_lshlrev_b32_e32 v168, 16, v193
	v_and_b32_e32 v169, 0xffff0000, v193
	v_rcp_f32_e32 v148, v148
	v_rcp_f32_e32 v149, v149
	v_rcp_f32_e32 v152, v152
	v_rcp_f32_e32 v153, v153
	s_nop 0
	v_pk_mul_f32 v[148:149], v[148:149], v[150:151]
	v_pk_mul_f32 v[152:153], v[152:153], v[168:169]
	v_pk_mul_f32 v[38:39], v[38:39], v[148:149]
	v_pk_mul_f32 v[40:41], v[40:41], v[152:153]
	v_lshlrev_b32_e32 v176, 16, v186
	v_and_b32_e32 v177, 0xffff0000, v186
	v_lshlrev_b32_e32 v178, 16, v194
	v_and_b32_e32 v179, 0xffff0000, v194
	v_lshlrev_b32_e32 v180, 16, v187
	v_and_b32_e32 v181, 0xffff0000, v187
	v_lshlrev_b32_e32 v244, 16, v195
	v_and_b32_e32 v245, 0xffff0000, v195
	v_rcp_f32_e32 v176, v176
	v_rcp_f32_e32 v177, v177
	v_rcp_f32_e32 v180, v180
	v_rcp_f32_e32 v181, v181
	s_nop 0
	v_pk_mul_f32 v[176:177], v[176:177], v[178:179]
	v_pk_mul_f32 v[180:181], v[180:181], v[244:245]
	v_pk_mul_f32 v[30:31], v[30:31], v[176:177]
	v_pk_mul_f32 v[32:33], v[32:33], v[180:181]
	v_lshlrev_b32_e32 v176, 16, v188
	v_and_b32_e32 v177, 0xffff0000, v188
	v_lshlrev_b32_e32 v178, 16, v196
	v_and_b32_e32 v179, 0xffff0000, v196
	v_lshlrev_b32_e32 v180, 16, v189
	v_and_b32_e32 v181, 0xffff0000, v189
	v_lshlrev_b32_e32 v244, 16, v197
	v_and_b32_e32 v245, 0xffff0000, v197
	v_rcp_f32_e32 v176, v176
	v_rcp_f32_e32 v177, v177
	v_rcp_f32_e32 v180, v180
	v_rcp_f32_e32 v181, v181
	s_nop 0
	v_pk_mul_f32 v[176:177], v[176:177], v[178:179]
	v_pk_mul_f32 v[180:181], v[180:181], v[244:245]
	v_pk_mul_f32 v[18:19], v[18:19], v[176:177]
	v_pk_mul_f32 v[20:21], v[20:21], v[180:181]
	v_lshlrev_b32_e32 v148, 16, v190
	v_and_b32_e32 v149, 0xffff0000, v190
	v_lshlrev_b32_e32 v150, 16, v198
	v_and_b32_e32 v151, 0xffff0000, v198
	v_lshlrev_b32_e32 v152, 16, v191
	v_and_b32_e32 v153, 0xffff0000, v191
	v_lshlrev_b32_e32 v168, 16, v199
	v_and_b32_e32 v169, 0xffff0000, v199
	v_rcp_f32_e32 v148, v148
	v_rcp_f32_e32 v149, v149
	v_rcp_f32_e32 v152, v152
	v_rcp_f32_e32 v153, v153
	s_nop 0
	v_pk_mul_f32 v[148:149], v[148:149], v[150:151]
	v_pk_mul_f32 v[152:153], v[152:153], v[168:169]
	v_pk_mul_f32 v[10:11], v[10:11], v[148:149]
	v_pk_mul_f32 v[12:13], v[12:13], v[152:153]
	s_waitcnt vmcnt(0)
; DI float bflo(unsigned w) { return __uint_as_float(w << 16); }
; DI float bfhi(unsigned w) { return __uint_as_float(w & 0xffff0000u); }
; DI u32x4 pack8(f32x4 a, f32x4 b) { u32x4 w; w.x = pk2(a[0], a[1]); w.y = pk2(a[2], a[3]); w.z = pk2(b[0], b[1]); w.w = pk2(b[2], b[3]); return w; }
;     DI void operator()(Acc& acc, const Unit& u, int wr, int wc, int fr, int fq) const {
;     ...
;                     for (int bj = 0; bj < 2; ++bj) g[ai][m][bj] = *(const u32x4*)(base + (size_t)(ai * 128 + m * 16) * NPJ + u.k * 1024 + bj * 128);
; #pragma unroll
;             for (int ai = 0; ai < 2; ++ai)
; #pragma unroll
;                 for (int m = 0; m < 4; ++m)
; #pragma unroll
;                     for (int bj = 0; bj < 2; ++bj) { const u32x4 q = g[ai][m][bj]; f32x4& v0 = acc[ai][bj][m][0]; f32x4& v1 = acc[ai][bj][m][1];
;                         v0[0] *= bflo(q.x); v0[1] *= bfhi(q.x); v0[2] *= bflo(q.y); v0[3] *= bfhi(q.y); v1[0] *= bflo(q.z); v1[1] *= bfhi(q.z); v1[2] *= bflo(q.w); v1[3] *= bfhi(q.w); }
;         }
;         if (u.k > 0) {
;             u32x4 g[2][4][2];
; #pragma unroll
;             for (int ai = 0; ai < 2; ++ai)
; #pragma unroll
;                 for (int m = 0; m < 4; ++m)
; #pragma unroll
;                     for (int bj = 0; bj < 2; ++bj) g[ai][m][bj] = *(const u32x4*)(base + (size_t)(ai * 128 + m * 16) * NPJ + bj * 128);
; #pragma unroll
;             for (int ai = 0; ai < 2; ++ai)
; #pragma unroll
;                 for (int m = 0; m < 4; ++m)
; #pragma unroll
;                     for (int bj = 0; bj < 2; ++bj) { const u32x4 q = g[ai][m][bj]; f32x4& v0 = acc[ai][bj][m][0]; f32x4& v1 = acc[ai][bj][m][1];
;                         v0[0] += bflo(q.x); v0[1] += bfhi(q.x); v0[2] += bflo(q.y); v0[3] += bfhi(q.y); v1[0] += bflo(q.z); v1[1] += bfhi(q.z); v1[2] += bflo(q.w); v1[3] += bfhi(q.w); }
;         }
;         if (!dry) {
; #pragma unroll
;             for (int ai = 0; ai < 2; ++ai)
; #pragma unroll
;                 for (int m = 0; m < 4; ++m)
; #pragma unroll
;                     for (int bj = 0; bj < 2; ++bj) *(u32x4*)(base + (size_t)(ai * 128 + m * 16) * NPJ + bj * 128) = pack8(acc[ai][bj][m][0], acc[ai][bj][m][1]);
	v_lshlrev_b32_e32 v148, 16, v200
	v_and_b32_e32 v149, 0xffff0000, v200
	v_lshlrev_b32_e32 v150, 16, v208
	v_and_b32_e32 v151, 0xffff0000, v208
	v_lshlrev_b32_e32 v152, 16, v201
	v_and_b32_e32 v153, 0xffff0000, v201
	v_lshlrev_b32_e32 v168, 16, v209
	v_and_b32_e32 v169, 0xffff0000, v209
	v_rcp_f32_e32 v148, v148
	v_rcp_f32_e32 v149, v149
	v_rcp_f32_e32 v152, v152
	v_rcp_f32_e32 v153, v153
	s_nop 0
	v_pk_mul_f32 v[148:149], v[148:149], v[150:151]
	v_pk_mul_f32 v[152:153], v[152:153], v[168:169]
	v_pk_mul_f32 v[22:23], v[22:23], v[148:149]
	v_pk_mul_f32 v[24:25], v[24:25], v[152:153]
	v_lshlrev_b32_e32 v176, 16, v202
	v_and_b32_e32 v177, 0xffff0000, v202
	v_lshlrev_b32_e32 v178, 16, v210
	v_and_b32_e32 v179, 0xffff0000, v210
	v_lshlrev_b32_e32 v180, 16, v203
	v_and_b32_e32 v181, 0xffff0000, v203
	v_lshlrev_b32_e32 v244, 16, v211
	v_and_b32_e32 v245, 0xffff0000, v211
	v_rcp_f32_e32 v176, v176
	v_rcp_f32_e32 v177, v177
	v_rcp_f32_e32 v180, v180
	v_rcp_f32_e32 v181, v181
	s_nop 0
	v_pk_mul_f32 v[176:177], v[176:177], v[178:179]
	v_pk_mul_f32 v[180:181], v[180:181], v[244:245]
	v_pk_mul_f32 v[14:15], v[14:15], v[176:177]
	v_pk_mul_f32 v[16:17], v[16:17], v[180:181]
	v_lshlrev_b32_e32 v176, 16, v204
	v_and_b32_e32 v177, 0xffff0000, v204
	v_lshlrev_b32_e32 v178, 16, v212
	v_and_b32_e32 v179, 0xffff0000, v212
	v_lshlrev_b32_e32 v180, 16, v205
	v_and_b32_e32 v181, 0xffff0000, v205
	v_lshlrev_b32_e32 v244, 16, v213
	v_and_b32_e32 v245, 0xffff0000, v213
	v_rcp_f32_e32 v176, v176
	v_rcp_f32_e32 v177, v177
	v_rcp_f32_e32 v180, v180
	v_rcp_f32_e32 v181, v181
	s_nop 0
	v_pk_mul_f32 v[176:177], v[176:177], v[178:179]
	v_pk_mul_f32 v[180:181], v[180:181], v[244:245]
	v_pk_mul_f32 v[6:7], v[6:7], v[176:177]
	v_pk_mul_f32 v[8:9], v[8:9], v[180:181]
	v_lshlrev_b32_e32 v148, 16, v206
	v_and_b32_e32 v149, 0xffff0000, v206
	v_lshlrev_b32_e32 v150, 16, v214
	v_and_b32_e32 v151, 0xffff0000, v214
	v_lshlrev_b32_e32 v152, 16, v207
	v_and_b32_e32 v153, 0xffff0000, v207
	v_lshlrev_b32_e32 v168, 16, v215
	v_and_b32_e32 v169, 0xffff0000, v215
	v_rcp_f32_e32 v148, v148
	v_rcp_f32_e32 v149, v149
	v_rcp_f32_e32 v152, v152
	v_rcp_f32_e32 v153, v153
	s_nop 0
	v_pk_mul_f32 v[148:149], v[148:149], v[150:151]
	v_pk_mul_f32 v[152:153], v[152:153], v[168:169]
	v_pk_mul_f32 v[2:3], v[2:3], v[148:149]
	v_pk_mul_f32 v[4:5], v[4:5], v[152:153]
	s_branch .Lup6_tail
.Lup6_final:
	s_mov_b32 s101, 0
	s_mov_b32 s100, 0x32000
	v_lshl_add_u64 v[132:133], v[166:167], 0, s[100:101]
	s_mov_b32 s100, 0x64000
	v_lshl_add_u64 v[134:135], v[166:167], 0, s[100:101]
	s_mov_b32 s100, 0x96000
	v_lshl_add_u64 v[136:137], v[166:167], 0, s[100:101]
	s_mov_b32 s100, 0x190000
	v_lshl_add_u64 v[138:139], v[166:167], 0, s[100:101]
	s_mov_b32 s100, 0x1c2000
	v_lshl_add_u64 v[140:141], v[166:167], 0, s[100:101]
	s_mov_b32 s100, 0x1f4000
	v_lshl_add_u64 v[142:143], v[166:167], 0, s[100:101]
	s_mov_b32 s100, 0x226000
	v_lshl_add_u64 v[144:145], v[166:167], 0, s[100:101]
	s_add_u32 s100, s98, 0x0
	s_addc_u32 s101, s99, 0
	global_load_dwordx4 v[184:187], v243, s[100:101]
	s_add_u32 s100, s98, 0x19000
	s_addc_u32 s101, s99, 0
	global_load_dwordx4 v[188:191], v243, s[100:101]
	s_add_u32 s100, s98, 0x32000
	s_addc_u32 s101, s99, 0
	global_load_dwordx4 v[192:195], v243, s[100:101]
	s_add_u32 s100, s98, 0x4b000
	s_addc_u32 s101, s99, 0
	global_load_dwordx4 v[196:199], v243, s[100:101]
	s_add_u32 s100, s98, 0x64000
	s_addc_u32 s101, s99, 0
	global_load_dwordx4 v[200:203], v243, s[100:101]
	s_add_u32 s100, s98, 0x7d000
	s_addc_u32 s101, s99, 0
	global_load_dwordx4 v[204:207], v243, s[100:101]
	s_add_u32 s100, s98, 0x96000
	s_addc_u32 s101, s99, 0
	global_load_dwordx4 v[208:211], v243, s[100:101]
	s_add_u32 s100, s98, 0xaf000
	s_addc_u32 s101, s99, 0
	global_load_dwordx4 v[212:215], v243, s[100:101]
	s_add_u32 s100, s98, 0x190000
	s_addc_u32 s101, s99, 0
	global_load_dwordx4 v[216:219], v243, s[100:101]
	s_add_u32 s100, s98, 0x1a9000
	s_addc_u32 s101, s99, 0
	global_load_dwordx4 v[220:223], v243, s[100:101]
	s_add_u32 s100, s98, 0x1c2000
	s_addc_u32 s101, s99, 0
	global_load_dwordx4 v[224:227], v243, s[100:101]
	s_add_u32 s100, s98, 0x1db000
	s_addc_u32 s101, s99, 0
	global_load_dwordx4 v[228:231], v243, s[100:101]
	s_waitcnt vmcnt(10)
	v_lshlrev_b32_e32 v148, 16, v184
	v_and_b32_e32 v149, 0xffff0000, v184
	v_lshlrev_b32_e32 v150, 16, v185
	v_and_b32_e32 v151, 0xffff0000, v185
	v_lshlrev_b32_e32 v152, 16, v186
	v_and_b32_e32 v153, 0xffff0000, v186
	v_lshlrev_b32_e32 v168, 16, v187
	v_and_b32_e32 v169, 0xffff0000, v187
	v_rcp_f32_e32 v148, v148
	v_rcp_f32_e32 v149, v149
	v_rcp_f32_e32 v150, v150
	v_rcp_f32_e32 v151, v151
	v_rcp_f32_e32 v152, v152
	v_rcp_f32_e32 v153, v153
	v_rcp_f32_e32 v168, v168
	v_rcp_f32_e32 v169, v169
	s_nop 0
	v_pk_mul_f32 v[126:127], v[126:127], v[148:149]
	v_pk_mul_f32 v[128:129], v[128:129], v[150:151]
	v_pk_mul_f32 v[122:123], v[122:123], v[152:153]
	v_pk_mul_f32 v[124:125], v[124:125], v[168:169]
	v_cvt_pk_bf16_f32 v184, v126, v127
	v_cvt_pk_bf16_f32 v185, v128, v129
	v_cvt_pk_bf16_f32 v186, v122, v123
	v_cvt_pk_bf16_f32 v187, v124, v125
	v_lshlrev_b32_e32 v176, 16, v188
	v_and_b32_e32 v177, 0xffff0000, v188
	v_lshlrev_b32_e32 v178, 16, v189
	v_and_b32_e32 v179, 0xffff0000, v189
	v_lshlrev_b32_e32 v180, 16, v190
	v_and_b32_e32 v181, 0xffff0000, v190
	v_lshlrev_b32_e32 v244, 16, v191
	v_and_b32_e32 v245, 0xffff0000, v191
	v_rcp_f32_e32 v176, v176
	v_rcp_f32_e32 v177, v177
	v_rcp_f32_e32 v178, v178
	v_rcp_f32_e32 v179, v179
	v_rcp_f32_e32 v180, v180
	v_rcp_f32_e32 v181, v181
	v_rcp_f32_e32 v244, v244
	v_rcp_f32_e32 v245, v245
	s_nop 0
	v_pk_mul_f32 v[114:115], v[114:115], v[176:177]
	v_pk_mul_f32 v[116:117], v[116:117], v[178:179]
	v_pk_mul_f32 v[110:111], v[110:111], v[180:181]
	v_pk_mul_f32 v[112:113], v[112:113], v[244:245]
	v_cvt_pk_bf16_f32 v188, v114, v115
	v_cvt_pk_bf16_f32 v189, v116, v117
	v_cvt_pk_bf16_f32 v190, v110, v111
	v_cvt_pk_bf16_f32 v191, v112, v113
	global_store_dwordx4 v[166:167], v[184:187], off
	global_store_dwordx4 v[166:167], v[188:191], off offset:256
	s_nop 1
	s_add_u32 s100, s98, 0x1f4000
	s_addc_u32 s101, s99, 0
	global_load_dwordx4 v[184:187], v243, s[100:101]
	s_add_u32 s100, s98, 0x20d000
	s_addc_u32 s101, s99, 0
	global_load_dwordx4 v[188:191], v243, s[100:101]
	s_waitcnt vmcnt(12)
; DI float bflo(unsigned w) { return __uint_as_float(w << 16); }
; DI float bfhi(unsigned w) { return __uint_as_float(w & 0xffff0000u); }
; DI u32x4 pack8(f32x4 a, f32x4 b) { u32x4 w; w.x = pk2(a[0], a[1]); w.y = pk2(a[2], a[3]); w.z = pk2(b[0], b[1]); w.w = pk2(b[2], b[3]); return w; }
;     DI void operator()(Acc& acc, const Unit& u, int wr, int wc, int fr, int fq) const {
;     ...
;                     for (int bj = 0; bj < 2; ++bj) { const u32x4 q = g[ai][m][bj]; f32x4& v0 = acc[ai][bj][m][0]; f32x4& v1 = acc[ai][bj][m][1];
;                         v0[0] *= bflo(q.x); v0[1] *= bfhi(q.x); v0[2] *= bflo(q.y); v0[3] *= bfhi(q.y); v1[0] *= bflo(q.z); v1[1] *= bfhi(q.z); v1[2] *= bflo(q.w); v1[3] *= bfhi(q.w); }
;         }
;         if (u.k > 0) {
;             u32x4 g[2][4][2];
; #pragma unroll
;             for (int ai = 0; ai < 2; ++ai)
; #pragma unroll
;                 for (int m = 0; m < 4; ++m)
; #pragma unroll
;                     for (int bj = 0; bj < 2; ++bj) g[ai][m][bj] = *(const u32x4*)(base + (size_t)(ai * 128 + m * 16) * NPJ + bj * 128);
; #pragma unroll
;             for (int ai = 0; ai < 2; ++ai)
; #pragma unroll
;                 for (int m = 0; m < 4; ++m)
; #pragma unroll
;                     for (int bj = 0; bj < 2; ++bj) { const u32x4 q = g[ai][m][bj]; f32x4& v0 = acc[ai][bj][m][0]; f32x4& v1 = acc[ai][bj][m][1];
;                         v0[0] += bflo(q.x); v0[1] += bfhi(q.x); v0[2] += bflo(q.y); v0[3] += bfhi(q.y); v1[0] += bflo(q.z); v1[1] += bfhi(q.z); v1[2] += bflo(q.w); v1[3] += bfhi(q.w); }
;         }
;         if (!dry) {
; #pragma unroll
;             for (int ai = 0; ai < 2; ++ai)
; #pragma unroll
;                 for (int m = 0; m < 4; ++m)
; #pragma unroll
;                     for (int bj = 0; bj < 2; ++bj) *(u32x4*)(base + (size_t)(ai * 128 + m * 16) * NPJ + bj * 128) = pack8(acc[ai][bj][m][0], acc[ai][bj][m][1]);
	v_lshlrev_b32_e32 v148, 16, v192
	v_and_b32_e32 v149, 0xffff0000, v192
	v_lshlrev_b32_e32 v150, 16, v193
	v_and_b32_e32 v151, 0xffff0000, v193
	v_lshlrev_b32_e32 v152, 16, v194
	v_and_b32_e32 v153, 0xffff0000, v194
	v_lshlrev_b32_e32 v168, 16, v195
	v_and_b32_e32 v169, 0xffff0000, v195
	v_rcp_f32_e32 v148, v148
	v_rcp_f32_e32 v149, v149
	v_rcp_f32_e32 v150, v150
	v_rcp_f32_e32 v151, v151
	v_rcp_f32_e32 v152, v152
	v_rcp_f32_e32 v153, v153
	v_rcp_f32_e32 v168, v168
	v_rcp_f32_e32 v169, v169
	s_nop 0
	v_pk_mul_f32 v[118:119], v[118:119], v[148:149]
	v_pk_mul_f32 v[120:121], v[120:121], v[150:151]
	v_pk_mul_f32 v[106:107], v[106:107], v[152:153]
	v_pk_mul_f32 v[108:109], v[108:109], v[168:169]
	v_cvt_pk_bf16_f32 v192, v118, v119
	v_cvt_pk_bf16_f32 v193, v120, v121
	v_cvt_pk_bf16_f32 v194, v106, v107
	v_cvt_pk_bf16_f32 v195, v108, v109
	v_lshlrev_b32_e32 v176, 16, v196
	v_and_b32_e32 v177, 0xffff0000, v196
	v_lshlrev_b32_e32 v178, 16, v197
	v_and_b32_e32 v179, 0xffff0000, v197
	v_lshlrev_b32_e32 v180, 16, v198
	v_and_b32_e32 v181, 0xffff0000, v198
	v_lshlrev_b32_e32 v244, 16, v199
	v_and_b32_e32 v245, 0xffff0000, v199
	v_rcp_f32_e32 v176, v176
	v_rcp_f32_e32 v177, v177
	v_rcp_f32_e32 v178, v178
	v_rcp_f32_e32 v179, v179
	v_rcp_f32_e32 v180, v180
	v_rcp_f32_e32 v181, v181
	v_rcp_f32_e32 v244, v244
	v_rcp_f32_e32 v245, v245
	s_nop 0
	v_pk_mul_f32 v[98:99], v[98:99], v[176:177]
	v_pk_mul_f32 v[100:101], v[100:101], v[178:179]
	v_pk_mul_f32 v[90:91], v[90:91], v[180:181]
	v_pk_mul_f32 v[92:93], v[92:93], v[244:245]
	v_cvt_pk_bf16_f32 v196, v98, v99
	v_cvt_pk_bf16_f32 v197, v100, v101
	v_cvt_pk_bf16_f32 v198, v90, v91
	v_cvt_pk_bf16_f32 v199, v92, v93
	global_store_dwordx4 v[132:133], v[192:195], off
	global_store_dwordx4 v[132:133], v[196:199], off offset:256
	s_nop 1
	s_add_u32 s100, s98, 0x226000
	s_addc_u32 s101, s99, 0
	global_load_dwordx4 v[192:195], v243, s[100:101]
	s_add_u32 s100, s98, 0x23f000
	s_addc_u32 s101, s99, 0
	global_load_dwordx4 v[196:199], v243, s[100:101]
	s_waitcnt vmcnt(14)
	v_lshlrev_b32_e32 v148, 16, v200
	v_and_b32_e32 v149, 0xffff0000, v200
	v_lshlrev_b32_e32 v150, 16, v201
	v_and_b32_e32 v151, 0xffff0000, v201
	v_lshlrev_b32_e32 v152, 16, v202
	v_and_b32_e32 v153, 0xffff0000, v202
	v_lshlrev_b32_e32 v168, 16, v203
	v_and_b32_e32 v169, 0xffff0000, v203
	v_rcp_f32_e32 v148, v148
	v_rcp_f32_e32 v149, v149
	v_rcp_f32_e32 v150, v150
	v_rcp_f32_e32 v151, v151
	v_rcp_f32_e32 v152, v152
	v_rcp_f32_e32 v153, v153
	v_rcp_f32_e32 v168, v168
	v_rcp_f32_e32 v169, v169
	s_nop 0
	v_pk_mul_f32 v[102:103], v[102:103], v[148:149]
	v_pk_mul_f32 v[104:105], v[104:105], v[150:151]
	v_pk_mul_f32 v[94:95], v[94:95], v[152:153]
	v_pk_mul_f32 v[96:97], v[96:97], v[168:169]
	v_cvt_pk_bf16_f32 v200, v102, v103
	v_cvt_pk_bf16_f32 v201, v104, v105
	v_cvt_pk_bf16_f32 v202, v94, v95
	v_cvt_pk_bf16_f32 v203, v96, v97
	v_lshlrev_b32_e32 v176, 16, v204
	v_and_b32_e32 v177, 0xffff0000, v204
	v_lshlrev_b32_e32 v178, 16, v205
	v_and_b32_e32 v179, 0xffff0000, v205
	v_lshlrev_b32_e32 v180, 16, v206
	v_and_b32_e32 v181, 0xffff0000, v206
	v_lshlrev_b32_e32 v244, 16, v207
	v_and_b32_e32 v245, 0xffff0000, v207
	v_rcp_f32_e32 v176, v176
	v_rcp_f32_e32 v177, v177
	v_rcp_f32_e32 v178, v178
	v_rcp_f32_e32 v179, v179
	v_rcp_f32_e32 v180, v180
	v_rcp_f32_e32 v181, v181
	v_rcp_f32_e32 v244, v244
	v_rcp_f32_e32 v245, v245
	s_nop 0
	v_pk_mul_f32 v[82:83], v[82:83], v[176:177]
	v_pk_mul_f32 v[84:85], v[84:85], v[178:179]
	v_pk_mul_f32 v[74:75], v[74:75], v[180:181]
	v_pk_mul_f32 v[76:77], v[76:77], v[244:245]
	v_cvt_pk_bf16_f32 v204, v82, v83
	v_cvt_pk_bf16_f32 v205, v84, v85
	v_cvt_pk_bf16_f32 v206, v74, v75
	v_cvt_pk_bf16_f32 v207, v76, v77
	global_store_dwordx4 v[134:135], v[200:203], off
	global_store_dwordx4 v[134:135], v[204:207], off offset:256
	s_waitcnt vmcnt(14)
	v_lshlrev_b32_e32 v148, 16, v208
	v_and_b32_e32 v149, 0xffff0000, v208
	v_lshlrev_b32_e32 v150, 16, v209
	v_and_b32_e32 v151, 0xffff0000, v209
	v_lshlrev_b32_e32 v152, 16, v210
	v_and_b32_e32 v153, 0xffff0000, v210
	v_lshlrev_b32_e32 v168, 16, v211
	v_and_b32_e32 v169, 0xffff0000, v211
	v_rcp_f32_e32 v148, v148
	v_rcp_f32_e32 v149, v149
	v_rcp_f32_e32 v150, v150
	v_rcp_f32_e32 v151, v151
	v_rcp_f32_e32 v152, v152
	v_rcp_f32_e32 v153, v153
	v_rcp_f32_e32 v168, v168
	v_rcp_f32_e32 v169, v169
	s_nop 0
	v_pk_mul_f32 v[86:87], v[86:87], v[148:149]
	v_pk_mul_f32 v[88:89], v[88:89], v[150:151]
	v_pk_mul_f32 v[78:79], v[78:79], v[152:153]
	v_pk_mul_f32 v[80:81], v[80:81], v[168:169]
	v_cvt_pk_bf16_f32 v208, v86, v87
	v_cvt_pk_bf16_f32 v209, v88, v89
	v_cvt_pk_bf16_f32 v210, v78, v79
	v_cvt_pk_bf16_f32 v211, v80, v81
	v_lshlrev_b32_e32 v176, 16, v212
	v_and_b32_e32 v177, 0xffff0000, v212
	v_lshlrev_b32_e32 v178, 16, v213
	v_and_b32_e32 v179, 0xffff0000, v213
	v_lshlrev_b32_e32 v180, 16, v214
	v_and_b32_e32 v181, 0xffff0000, v214
	v_lshlrev_b32_e32 v244, 16, v215
	v_and_b32_e32 v245, 0xffff0000, v215
	v_rcp_f32_e32 v176, v176
	v_rcp_f32_e32 v177, v177
	v_rcp_f32_e32 v178, v178
	v_rcp_f32_e32 v179, v179
	v_rcp_f32_e32 v180, v180
	v_rcp_f32_e32 v181, v181
	v_rcp_f32_e32 v244, v244
	v_rcp_f32_e32 v245, v245
	s_nop 0
	v_pk_mul_f32 v[70:71], v[70:71], v[176:177]
	v_pk_mul_f32 v[72:73], v[72:73], v[178:179]
	v_pk_mul_f32 v[66:67], v[66:67], v[180:181]
	v_pk_mul_f32 v[68:69], v[68:69], v[244:245]
	v_cvt_pk_bf16_f32 v212, v70, v71
	v_cvt_pk_bf16_f32 v213, v72, v73
	v_cvt_pk_bf16_f32 v214, v66, v67
	v_cvt_pk_bf16_f32 v215, v68, v69
	global_store_dwordx4 v[136:137], v[208:211], off
	global_store_dwordx4 v[136:137], v[212:215], off offset:256
	s_waitcnt vmcnt(14)
; DI float bflo(unsigned w) { return __uint_as_float(w << 16); }
; DI float bfhi(unsigned w) { return __uint_as_float(w & 0xffff0000u); }
; DI u32x4 pack8(f32x4 a, f32x4 b) { u32x4 w; w.x = pk2(a[0], a[1]); w.y = pk2(a[2], a[3]); w.z = pk2(b[0], b[1]); w.w = pk2(b[2], b[3]); return w; }
;     DI void operator()(Acc& acc, const Unit& u, int wr, int wc, int fr, int fq) const {
;     ...
;                     for (int bj = 0; bj < 2; ++bj) { const u32x4 q = g[ai][m][bj]; f32x4& v0 = acc[ai][bj][m][0]; f32x4& v1 = acc[ai][bj][m][1];
;                         v0[0] *= bflo(q.x); v0[1] *= bfhi(q.x); v0[2] *= bflo(q.y); v0[3] *= bfhi(q.y); v1[0] *= bflo(q.z); v1[1] *= bfhi(q.z); v1[2] *= bflo(q.w); v1[3] *= bfhi(q.w); }
;         }
;         if (u.k > 0) {
;             u32x4 g[2][4][2];
; #pragma unroll
;             for (int ai = 0; ai < 2; ++ai)
; #pragma unroll
;                 for (int m = 0; m < 4; ++m)
; #pragma unroll
;                     for (int bj = 0; bj < 2; ++bj) g[ai][m][bj] = *(const u32x4*)(base + (size_t)(ai * 128 + m * 16) * NPJ + bj * 128);
; #pragma unroll
;             for (int ai = 0; ai < 2; ++ai)
; #pragma unroll
;                 for (int m = 0; m < 4; ++m)
; #pragma unroll
;                     for (int bj = 0; bj < 2; ++bj) { const u32x4 q = g[ai][m][bj]; f32x4& v0 = acc[ai][bj][m][0]; f32x4& v1 = acc[ai][bj][m][1];
;                         v0[0] += bflo(q.x); v0[1] += bfhi(q.x); v0[2] += bflo(q.y); v0[3] += bfhi(q.y); v1[0] += bflo(q.z); v1[1] += bfhi(q.z); v1[2] += bflo(q.w); v1[3] += bfhi(q.w); }
;         }
;         if (!dry) {
; #pragma unroll
;             for (int ai = 0; ai < 2; ++ai)
; #pragma unroll
;                 for (int m = 0; m < 4; ++m)
; #pragma unroll
;                     for (int bj = 0; bj < 2; ++bj) *(u32x4*)(base + (size_t)(ai * 128 + m * 16) * NPJ + bj * 128) = pack8(acc[ai][bj][m][0], acc[ai][bj][m][1]);
	v_lshlrev_b32_e32 v148, 16, v216
	v_and_b32_e32 v149, 0xffff0000, v216
	v_lshlrev_b32_e32 v150, 16, v217
	v_and_b32_e32 v151, 0xffff0000, v217
	v_lshlrev_b32_e32 v152, 16, v218
	v_and_b32_e32 v153, 0xffff0000, v218
	v_lshlrev_b32_e32 v168, 16, v219
	v_and_b32_e32 v169, 0xffff0000, v219
	v_rcp_f32_e32 v148, v148
	v_rcp_f32_e32 v149, v149
	v_rcp_f32_e32 v150, v150
	v_rcp_f32_e32 v151, v151
	v_rcp_f32_e32 v152, v152
	v_rcp_f32_e32 v153, v153
	v_rcp_f32_e32 v168, v168
	v_rcp_f32_e32 v169, v169
	s_nop 0
	v_pk_mul_f32 v[62:63], v[62:63], v[148:149]
	v_pk_mul_f32 v[64:65], v[64:65], v[150:151]
	v_pk_mul_f32 v[58:59], v[58:59], v[152:153]
	v_pk_mul_f32 v[60:61], v[60:61], v[168:169]
	v_cvt_pk_bf16_f32 v216, v62, v63
	v_cvt_pk_bf16_f32 v217, v64, v65
	v_cvt_pk_bf16_f32 v218, v58, v59
	v_cvt_pk_bf16_f32 v219, v60, v61
	v_lshlrev_b32_e32 v176, 16, v220
	v_and_b32_e32 v177, 0xffff0000, v220
	v_lshlrev_b32_e32 v178, 16, v221
	v_and_b32_e32 v179, 0xffff0000, v221
	v_lshlrev_b32_e32 v180, 16, v222
	v_and_b32_e32 v181, 0xffff0000, v222
	v_lshlrev_b32_e32 v244, 16, v223
	v_and_b32_e32 v245, 0xffff0000, v223
	v_rcp_f32_e32 v176, v176
	v_rcp_f32_e32 v177, v177
	v_rcp_f32_e32 v178, v178
	v_rcp_f32_e32 v179, v179
	v_rcp_f32_e32 v180, v180
	v_rcp_f32_e32 v181, v181
	v_rcp_f32_e32 v244, v244
	v_rcp_f32_e32 v245, v245
	s_nop 0
	v_pk_mul_f32 v[50:51], v[50:51], v[176:177]
	v_pk_mul_f32 v[52:53], v[52:53], v[178:179]
	v_pk_mul_f32 v[42:43], v[42:43], v[180:181]
	v_pk_mul_f32 v[44:45], v[44:45], v[244:245]
	v_cvt_pk_bf16_f32 v220, v50, v51
	v_cvt_pk_bf16_f32 v221, v52, v53
	v_cvt_pk_bf16_f32 v222, v42, v43
	v_cvt_pk_bf16_f32 v223, v44, v45
	global_store_dwordx4 v[138:139], v[216:219], off
	global_store_dwordx4 v[138:139], v[220:223], off offset:256
	s_waitcnt vmcnt(14)
	v_lshlrev_b32_e32 v148, 16, v224
	v_and_b32_e32 v149, 0xffff0000, v224
	v_lshlrev_b32_e32 v150, 16, v225
	v_and_b32_e32 v151, 0xffff0000, v225
	v_lshlrev_b32_e32 v152, 16, v226
	v_and_b32_e32 v153, 0xffff0000, v226
	v_lshlrev_b32_e32 v168, 16, v227
	v_and_b32_e32 v169, 0xffff0000, v227
	v_rcp_f32_e32 v148, v148
	v_rcp_f32_e32 v149, v149
	v_rcp_f32_e32 v150, v150
	v_rcp_f32_e32 v151, v151
	v_rcp_f32_e32 v152, v152
	v_rcp_f32_e32 v153, v153
	v_rcp_f32_e32 v168, v168
	v_rcp_f32_e32 v169, v169
	s_nop 0
	v_pk_mul_f32 v[54:55], v[54:55], v[148:149]
	v_pk_mul_f32 v[56:57], v[56:57], v[150:151]
	v_pk_mul_f32 v[46:47], v[46:47], v[152:153]
	v_pk_mul_f32 v[48:49], v[48:49], v[168:169]
	v_cvt_pk_bf16_f32 v224, v54, v55
	v_cvt_pk_bf16_f32 v225, v56, v57
	v_cvt_pk_bf16_f32 v226, v46, v47
	v_cvt_pk_bf16_f32 v227, v48, v49
	v_lshlrev_b32_e32 v176, 16, v228
	v_and_b32_e32 v177, 0xffff0000, v228
	v_lshlrev_b32_e32 v178, 16, v229
	v_and_b32_e32 v179, 0xffff0000, v229
	v_lshlrev_b32_e32 v180, 16, v230
	v_and_b32_e32 v181, 0xffff0000, v230
	v_lshlrev_b32_e32 v244, 16, v231
	v_and_b32_e32 v245, 0xffff0000, v231
	v_rcp_f32_e32 v176, v176
	v_rcp_f32_e32 v177, v177
	v_rcp_f32_e32 v178, v178
	v_rcp_f32_e32 v179, v179
	v_rcp_f32_e32 v180, v180
	v_rcp_f32_e32 v181, v181
	v_rcp_f32_e32 v244, v244
	v_rcp_f32_e32 v245, v245
	s_nop 0
	v_pk_mul_f32 v[34:35], v[34:35], v[176:177]
	v_pk_mul_f32 v[36:37], v[36:37], v[178:179]
	v_pk_mul_f32 v[26:27], v[26:27], v[180:181]
	v_pk_mul_f32 v[28:29], v[28:29], v[244:245]
	v_cvt_pk_bf16_f32 v228, v34, v35
	v_cvt_pk_bf16_f32 v229, v36, v37
	v_cvt_pk_bf16_f32 v230, v26, v27
	v_cvt_pk_bf16_f32 v231, v28, v29
	global_store_dwordx4 v[140:141], v[224:227], off
	global_store_dwordx4 v[140:141], v[228:231], off offset:256
	s_waitcnt vmcnt(12)
; DI float bflo(unsigned w) { return __uint_as_float(w << 16); }
; DI float bfhi(unsigned w) { return __uint_as_float(w & 0xffff0000u); }
; DI u32x4 pack8(f32x4 a, f32x4 b) { u32x4 w; w.x = pk2(a[0], a[1]); w.y = pk2(a[2], a[3]); w.z = pk2(b[0], b[1]); w.w = pk2(b[2], b[3]); return w; }
;     DI void operator()(Acc& acc, const Unit& u, int wr, int wc, int fr, int fq) const {
;     ...
;                     for (int bj = 0; bj < 2; ++bj) { const u32x4 q = g[ai][m][bj]; f32x4& v0 = acc[ai][bj][m][0]; f32x4& v1 = acc[ai][bj][m][1];
;                         v0[0] *= bflo(q.x); v0[1] *= bfhi(q.x); v0[2] *= bflo(q.y); v0[3] *= bfhi(q.y); v1[0] *= bflo(q.z); v1[1] *= bfhi(q.z); v1[2] *= bflo(q.w); v1[3] *= bfhi(q.w); }
;         }
;         if (u.k > 0) {
;             u32x4 g[2][4][2];
; #pragma unroll
;             for (int ai = 0; ai < 2; ++ai)
; #pragma unroll
;                 for (int m = 0; m < 4; ++m)
; #pragma unroll
;                     for (int bj = 0; bj < 2; ++bj) g[ai][m][bj] = *(const u32x4*)(base + (size_t)(ai * 128 + m * 16) * NPJ + bj * 128);
; #pragma unroll
;             for (int ai = 0; ai < 2; ++ai)
; #pragma unroll
;                 for (int m = 0; m < 4; ++m)
; #pragma unroll
;                     for (int bj = 0; bj < 2; ++bj) { const u32x4 q = g[ai][m][bj]; f32x4& v0 = acc[ai][bj][m][0]; f32x4& v1 = acc[ai][bj][m][1];
;                         v0[0] += bflo(q.x); v0[1] += bfhi(q.x); v0[2] += bflo(q.y); v0[3] += bfhi(q.y); v1[0] += bflo(q.z); v1[1] += bfhi(q.z); v1[2] += bflo(q.w); v1[3] += bfhi(q.w); }
;         }
;         if (!dry) {
; #pragma unroll
;             for (int ai = 0; ai < 2; ++ai)
; #pragma unroll
;                 for (int m = 0; m < 4; ++m)
; #pragma unroll
;                     for (int bj = 0; bj < 2; ++bj) *(u32x4*)(base + (size_t)(ai * 128 + m * 16) * NPJ + bj * 128) = pack8(acc[ai][bj][m][0], acc[ai][bj][m][1]);
	v_lshlrev_b32_e32 v148, 16, v184
	v_and_b32_e32 v149, 0xffff0000, v184
	v_lshlrev_b32_e32 v150, 16, v185
	v_and_b32_e32 v151, 0xffff0000, v185
	v_lshlrev_b32_e32 v152, 16, v186
	v_and_b32_e32 v153, 0xffff0000, v186
	v_lshlrev_b32_e32 v168, 16, v187
	v_and_b32_e32 v169, 0xffff0000, v187
	v_rcp_f32_e32 v148, v148
	v_rcp_f32_e32 v149, v149
	v_rcp_f32_e32 v150, v150
	v_rcp_f32_e32 v151, v151
	v_rcp_f32_e32 v152, v152
	v_rcp_f32_e32 v153, v153
	v_rcp_f32_e32 v168, v168
	v_rcp_f32_e32 v169, v169
	s_nop 0
	v_pk_mul_f32 v[38:39], v[38:39], v[148:149]
	v_pk_mul_f32 v[40:41], v[40:41], v[150:151]
	v_pk_mul_f32 v[30:31], v[30:31], v[152:153]
	v_pk_mul_f32 v[32:33], v[32:33], v[168:169]
	v_cvt_pk_bf16_f32 v184, v38, v39
	v_cvt_pk_bf16_f32 v185, v40, v41
	v_cvt_pk_bf16_f32 v186, v30, v31
	v_cvt_pk_bf16_f32 v187, v32, v33
	v_lshlrev_b32_e32 v176, 16, v188
	v_and_b32_e32 v177, 0xffff0000, v188
	v_lshlrev_b32_e32 v178, 16, v189
	v_and_b32_e32 v179, 0xffff0000, v189
	v_lshlrev_b32_e32 v180, 16, v190
	v_and_b32_e32 v181, 0xffff0000, v190
	v_lshlrev_b32_e32 v244, 16, v191
	v_and_b32_e32 v245, 0xffff0000, v191
	v_rcp_f32_e32 v176, v176
	v_rcp_f32_e32 v177, v177
	v_rcp_f32_e32 v178, v178
	v_rcp_f32_e32 v179, v179
	v_rcp_f32_e32 v180, v180
	v_rcp_f32_e32 v181, v181
	v_rcp_f32_e32 v244, v244
	v_rcp_f32_e32 v245, v245
	s_nop 0
	v_pk_mul_f32 v[18:19], v[18:19], v[176:177]
	v_pk_mul_f32 v[20:21], v[20:21], v[178:179]
	v_pk_mul_f32 v[10:11], v[10:11], v[180:181]
	v_pk_mul_f32 v[12:13], v[12:13], v[244:245]
	v_cvt_pk_bf16_f32 v188, v18, v19
	v_cvt_pk_bf16_f32 v189, v20, v21
	v_cvt_pk_bf16_f32 v190, v10, v11
	v_cvt_pk_bf16_f32 v191, v12, v13
	global_store_dwordx4 v[142:143], v[184:187], off
	global_store_dwordx4 v[142:143], v[188:191], off offset:256
	s_waitcnt vmcnt(10)
	v_lshlrev_b32_e32 v148, 16, v192
	v_and_b32_e32 v149, 0xffff0000, v192
	v_lshlrev_b32_e32 v150, 16, v193
	v_and_b32_e32 v151, 0xffff0000, v193
	v_lshlrev_b32_e32 v152, 16, v194
	v_and_b32_e32 v153, 0xffff0000, v194
	v_lshlrev_b32_e32 v168, 16, v195
	v_and_b32_e32 v169, 0xffff0000, v195
	v_rcp_f32_e32 v148, v148
	v_rcp_f32_e32 v149, v149
	v_rcp_f32_e32 v150, v150
	v_rcp_f32_e32 v151, v151
	v_rcp_f32_e32 v152, v152
	v_rcp_f32_e32 v153, v153
	v_rcp_f32_e32 v168, v168
	v_rcp_f32_e32 v169, v169
	s_nop 0
	v_pk_mul_f32 v[22:23], v[22:23], v[148:149]
	v_pk_mul_f32 v[24:25], v[24:25], v[150:151]
	v_pk_mul_f32 v[14:15], v[14:15], v[152:153]
	v_pk_mul_f32 v[16:17], v[16:17], v[168:169]
	v_cvt_pk_bf16_f32 v192, v22, v23
	v_cvt_pk_bf16_f32 v193, v24, v25
	v_cvt_pk_bf16_f32 v194, v14, v15
	v_cvt_pk_bf16_f32 v195, v16, v17
	v_lshlrev_b32_e32 v176, 16, v196
	v_and_b32_e32 v177, 0xffff0000, v196
	v_lshlrev_b32_e32 v178, 16, v197
	v_and_b32_e32 v179, 0xffff0000, v197
	v_lshlrev_b32_e32 v180, 16, v198
	v_and_b32_e32 v181, 0xffff0000, v198
	v_lshlrev_b32_e32 v244, 16, v199
	v_and_b32_e32 v245, 0xffff0000, v199
	v_rcp_f32_e32 v176, v176
	v_rcp_f32_e32 v177, v177
	v_rcp_f32_e32 v178, v178
	v_rcp_f32_e32 v179, v179
	v_rcp_f32_e32 v180, v180
	v_rcp_f32_e32 v181, v181
	v_rcp_f32_e32 v244, v244
	v_rcp_f32_e32 v245, v245
	s_nop 0
	v_pk_mul_f32 v[6:7], v[6:7], v[176:177]
	v_pk_mul_f32 v[8:9], v[8:9], v[178:179]
	v_pk_mul_f32 v[2:3], v[2:3], v[180:181]
	v_pk_mul_f32 v[4:5], v[4:5], v[244:245]
	v_cvt_pk_bf16_f32 v196, v6, v7
	v_cvt_pk_bf16_f32 v197, v8, v9
	v_cvt_pk_bf16_f32 v198, v2, v3
	v_cvt_pk_bf16_f32 v199, v4, v5
	global_store_dwordx4 v[144:145], v[192:195], off
	global_store_dwordx4 v[144:145], v[196:199], off offset:256
